# GEMM mainloops (gemm1 phase, prep gemm1 tile, out): A/B tiles via LDS-DMA with swizzled source addresses, two LDS stages filled two k-steps ahead, tile moved LDS->registers under the MFMAs; no ds_writ
# speedup vs baseline: 1.0296x; 1.0243x over previous
.LBB0_463:
	s_ashr_i32 s0, s12, 3
	s_mul_hi_i32 s1, s0, 0x66666667
	s_lshr_b32 s13, s1, 31
	s_ashr_i32 s1, s1, 4
	s_add_i32 s1, s1, s13
	s_mul_i32 s13, s1, 40
	s_sub_i32 s0, s0, s13
	s_and_b32 s22, s0, 7
	s_mul_i32 s1, s1, 5
	s_ashr_i32 s0, s0, 3
	s_lshl_b32 s13, s12, 3
	s_add_i32 s1, s1, s0
	s_and_b32 s13, s13, 56
	s_lshl_b32 s0, s1, 7
	s_or_b32 s13, s22, s13
	s_add_i32 s22, s0, 0x100
	s_cmp_lt_i32 s1, 6
	s_cselect_b32 s0, s0, s22
	s_lshl_b32 s1, s13, 18
	v_readlane_b32 s22, v251, 31
	v_mov_b32_e32 v36, v178
	v_readlane_b32 s23, v251, 32
	s_add_u32 s22, s22, s1
	s_addc_u32 s23, s23, 0
	v_ashrrev_i32_e32 v34, 3, v36
	s_ashr_i32 s1, s0, 31
	v_lshlrev_b32_e32 v0, 3, v36
	v_ashrrev_i32_e32 v35, 31, v34
	s_lshl_b64 s[24:25], s[0:1], 11
	v_and_b32_e32 v37, 56, v0
	v_lshlrev_b64 v[2:3], 11, v[34:35]
	s_add_u32 s24, s92, s24
	v_lshl_add_u64 v[4:5], s[22:23], 0, v[2:3]
	v_lshlrev_b32_e32 v0, 1, v37
	s_addc_u32 s25, s93, s25
	v_lshl_add_u64 v[68:69], v[4:5], 0, v[0:1]
	v_lshl_add_u64 v[2:3], s[24:25], 0, v[2:3]
	v_lshl_add_u64 v[70:71], v[2:3], 0, v[0:1]
	v_and_b32_e32 v0, 7, v36
	v_bfe_u32 v66, v36, 4, 3
	v_xor_b32_e32 v66, v66, v0
	v_sub_u32_e32 v66, v66, v0
	v_lshlrev_b32_e32 v66, 4, v66
	v_ashrrev_i32_e32 v67, 31, v66
	v_lshl_add_u64 v[68:69], v[68:69], 0, v[66:67]
	v_lshl_add_u64 v[70:71], v[70:71], 0, v[66:67]
	v_add_co_u32_e32 v72, vcc, s73, v68
	s_nop 1
	v_addc_co_u32_e32 v73, vcc, 0, v69, vcc
	v_add_co_u32_e32 v74, vcc, s73, v70
	s_nop 1
	v_addc_co_u32_e32 v75, vcc, 0, v71, vcc
	v_add_co_u32_e32 v76, vcc, s52, v68
	s_nop 1
	v_addc_co_u32_e32 v77, vcc, 0, v69, vcc
	v_add_co_u32_e32 v78, vcc, s52, v70
	s_nop 1
	v_addc_co_u32_e32 v79, vcc, 0, v71, vcc
	v_add_co_u32_e32 v80, vcc, s53, v68
	s_nop 1
	v_addc_co_u32_e32 v81, vcc, 0, v69, vcc
	v_add_co_u32_e32 v82, vcc, s53, v70
	s_nop 1
	v_addc_co_u32_e32 v83, vcc, 0, v71, vcc
	v_and_b32_e32 v0, 31, v36
	v_bfe_u32 v66, v36, 5, 1
	v_bfe_u32 v67, v36, 1, 3
	v_xor_b32_e32 v66, v66, v67
	v_lshlrev_b32_e32 v66, 4, v66
	v_lshl_add_u32 v66, v0, 7, v66
	v_bfe_u32 v67, v36, 7, 1
	v_lshl_add_u32 v86, v67, 13, v66
	v_bfe_u32 v67, v36, 6, 1
	v_lshl_add_u32 v90, v67, 13, v66
	v_add_u32_e32 v90, 0x4000, v90
	v_xor_b32_e32 v87, 32, v86
	v_xor_b32_e32 v91, 32, v90
	v_xor_b32_e32 v88, 64, v86
	v_xor_b32_e32 v92, 64, v90
	v_xor_b32_e32 v89, 96, v86
	v_xor_b32_e32 v93, 96, v90
	v_lshrrev_b32_e32 v66, 6, v36
	v_lshlrev_b32_e32 v66, 10, v66
	s_nop 1
	v_readfirstlane_b32 s14, v66
	s_movk_i32 s1, 0x14c0
	s_mov_b32 s27, 0
	s_lshl_b32 s13, s13, 7
	s_add_u32 m0, s14, 0x800
	s_nop 0
	global_load_lds_dwordx4 v[68:69], off
	s_add_u32 m0, s14, 0x1800
	s_nop 0
	global_load_lds_dwordx4 v[72:73], off
	s_add_u32 m0, s14, 0x2800
	s_nop 0
	global_load_lds_dwordx4 v[76:77], off
	s_add_u32 m0, s14, 0x3800
	s_nop 0
	global_load_lds_dwordx4 v[80:81], off
	s_add_u32 m0, s14, 0x4800
	s_nop 0
	global_load_lds_dwordx4 v[70:71], off
	s_add_u32 m0, s14, 0x5800
	s_nop 0
	global_load_lds_dwordx4 v[74:75], off
	s_add_u32 m0, s14, 0x6800
	s_nop 0
	global_load_lds_dwordx4 v[78:79], off
	s_add_u32 m0, s14, 0x7800
	s_nop 0
	global_load_lds_dwordx4 v[82:83], off
	s_add_u32 m0, s14, 0x8780
	s_nop 0
	global_load_lds_dwordx4 v[68:69], off offset:128
	s_add_u32 m0, s14, 0x9780
	s_nop 0
	global_load_lds_dwordx4 v[72:73], off offset:128
	s_add_u32 m0, s14, 0xa780
	s_nop 0
	global_load_lds_dwordx4 v[76:77], off offset:128
	s_add_u32 m0, s14, 0xb780
	s_nop 0
	global_load_lds_dwordx4 v[80:81], off offset:128
	s_add_u32 m0, s14, 0xc780
	s_nop 0
	global_load_lds_dwordx4 v[70:71], off offset:128
	s_add_u32 m0, s14, 0xd780
	s_nop 0
	global_load_lds_dwordx4 v[74:75], off offset:128
	s_add_u32 m0, s14, 0xe780
	s_nop 0
	global_load_lds_dwordx4 v[78:79], off offset:128
	s_add_u32 m0, s14, 0xf780
	s_nop 0
	global_load_lds_dwordx4 v[82:83], off offset:128
	s_waitcnt vmcnt(8)
	s_barrier
	ds_read_b128 v[94:97], v86 offset:2048
	ds_read_b128 v[98:101], v86 offset:6144
	ds_read_b128 v[102:105], v90 offset:2048
	ds_read_b128 v[106:109], v90 offset:6144
	ds_read_b128 v[110:113], v87 offset:2048
	ds_read_b128 v[114:117], v87 offset:6144
	ds_read_b128 v[118:121], v91 offset:2048
	ds_read_b128 v[122:125], v91 offset:6144
	ds_read_b128 v[126:129], v88 offset:2048
	ds_read_b128 v[130:133], v88 offset:6144
	ds_read_b128 v[134:137], v92 offset:2048
	ds_read_b128 v[138:141], v92 offset:6144
	ds_read_b128 v[142:145], v89 offset:2048
	ds_read_b128 v[146:149], v89 offset:6144
	ds_read_b128 v[150:153], v93 offset:2048
	ds_read_b128 v[154:157], v93 offset:6144
	s_waitcnt lgkmcnt(0)
	s_barrier
	s_add_u32 m0, s14, 0x700
	s_nop 0
	global_load_lds_dwordx4 v[68:69], off offset:256
	s_add_u32 m0, s14, 0x1700
	s_nop 0
	global_load_lds_dwordx4 v[72:73], off offset:256
	s_add_u32 m0, s14, 0x2700
	s_nop 0
	global_load_lds_dwordx4 v[76:77], off offset:256
	s_add_u32 m0, s14, 0x3700
	s_nop 0
	global_load_lds_dwordx4 v[80:81], off offset:256
	s_add_u32 m0, s14, 0x4700
	s_nop 0
	global_load_lds_dwordx4 v[70:71], off offset:256
	s_add_u32 m0, s14, 0x5700
	s_nop 0
	global_load_lds_dwordx4 v[74:75], off offset:256
	s_add_u32 m0, s14, 0x6700
	s_nop 0
	global_load_lds_dwordx4 v[78:79], off offset:256
	s_add_u32 m0, s14, 0x7700
	s_nop 0
	global_load_lds_dwordx4 v[82:83], off offset:256
	v_mfma_f32_32x32x16_bf16 v[34:49], v[94:97], v[102:105], 0
	v_mfma_f32_32x32x16_bf16 v[50:65], v[94:97], v[106:109], 0
	v_mfma_f32_32x32x16_bf16 v[2:17], v[98:101], v[102:105], 0
	v_mfma_f32_32x32x16_bf16 v[18:33], v[98:101], v[106:109], 0
	s_waitcnt vmcnt(8)
	s_barrier
	ds_read_b128 v[94:97], v86 offset:34816
	ds_read_b128 v[98:101], v86 offset:38912
	ds_read_b128 v[102:105], v90 offset:34816
	ds_read_b128 v[106:109], v90 offset:38912
	v_mfma_f32_32x32x16_bf16 v[34:49], v[110:113], v[118:121], v[34:49]
	v_mfma_f32_32x32x16_bf16 v[50:65], v[110:113], v[122:125], v[50:65]
	v_mfma_f32_32x32x16_bf16 v[2:17], v[114:117], v[118:121], v[2:17]
	v_mfma_f32_32x32x16_bf16 v[18:33], v[114:117], v[122:125], v[18:33]
	ds_read_b128 v[110:113], v87 offset:34816
	ds_read_b128 v[114:117], v87 offset:38912
	ds_read_b128 v[118:121], v91 offset:34816
	ds_read_b128 v[122:125], v91 offset:38912
	v_mfma_f32_32x32x16_bf16 v[34:49], v[126:129], v[134:137], v[34:49]
	v_mfma_f32_32x32x16_bf16 v[50:65], v[126:129], v[138:141], v[50:65]
	v_mfma_f32_32x32x16_bf16 v[2:17], v[130:133], v[134:137], v[2:17]
	v_mfma_f32_32x32x16_bf16 v[18:33], v[130:133], v[138:141], v[18:33]
	ds_read_b128 v[126:129], v88 offset:34816
	ds_read_b128 v[130:133], v88 offset:38912
	ds_read_b128 v[134:137], v92 offset:34816
	ds_read_b128 v[138:141], v92 offset:38912
	v_mfma_f32_32x32x16_bf16 v[34:49], v[142:145], v[150:153], v[34:49]
	v_mfma_f32_32x32x16_bf16 v[50:65], v[142:145], v[154:157], v[50:65]
	v_mfma_f32_32x32x16_bf16 v[2:17], v[146:149], v[150:153], v[2:17]
	v_mfma_f32_32x32x16_bf16 v[18:33], v[146:149], v[154:157], v[18:33]
	ds_read_b128 v[142:145], v89 offset:34816
	ds_read_b128 v[146:149], v89 offset:38912
	ds_read_b128 v[150:153], v93 offset:34816
	ds_read_b128 v[154:157], v93 offset:38912
	s_waitcnt lgkmcnt(0)
	s_barrier
	s_add_u32 m0, s14, 0x8680
	s_nop 0
	global_load_lds_dwordx4 v[68:69], off offset:384
	s_add_u32 m0, s14, 0x9680
	s_nop 0
	global_load_lds_dwordx4 v[72:73], off offset:384
	s_add_u32 m0, s14, 0xa680
	s_nop 0
	global_load_lds_dwordx4 v[76:77], off offset:384
	s_add_u32 m0, s14, 0xb680
	s_nop 0
	global_load_lds_dwordx4 v[80:81], off offset:384
	s_add_u32 m0, s14, 0xc680
	s_nop 0
	global_load_lds_dwordx4 v[70:71], off offset:384
	s_add_u32 m0, s14, 0xd680
	s_nop 0
	global_load_lds_dwordx4 v[74:75], off offset:384
	s_add_u32 m0, s14, 0xe680
	s_nop 0
	global_load_lds_dwordx4 v[78:79], off offset:384
	s_add_u32 m0, s14, 0xf680
	s_nop 0
	global_load_lds_dwordx4 v[82:83], off offset:384
	v_mfma_f32_32x32x16_bf16 v[34:49], v[94:97], v[102:105], v[34:49]
	v_mfma_f32_32x32x16_bf16 v[50:65], v[94:97], v[106:109], v[50:65]
	v_mfma_f32_32x32x16_bf16 v[2:17], v[98:101], v[102:105], v[2:17]
	v_mfma_f32_32x32x16_bf16 v[18:33], v[98:101], v[106:109], v[18:33]
	s_waitcnt vmcnt(8)
	s_barrier
	ds_read_b128 v[94:97], v86 offset:2048
	ds_read_b128 v[98:101], v86 offset:6144
	ds_read_b128 v[102:105], v90 offset:2048
	ds_read_b128 v[106:109], v90 offset:6144
	v_mfma_f32_32x32x16_bf16 v[34:49], v[110:113], v[118:121], v[34:49]
	v_mfma_f32_32x32x16_bf16 v[50:65], v[110:113], v[122:125], v[50:65]
	v_mfma_f32_32x32x16_bf16 v[2:17], v[114:117], v[118:121], v[2:17]
	v_mfma_f32_32x32x16_bf16 v[18:33], v[114:117], v[122:125], v[18:33]
	ds_read_b128 v[110:113], v87 offset:2048
	ds_read_b128 v[114:117], v87 offset:6144
	ds_read_b128 v[118:121], v91 offset:2048
	ds_read_b128 v[122:125], v91 offset:6144
	v_mfma_f32_32x32x16_bf16 v[34:49], v[126:129], v[134:137], v[34:49]
	v_mfma_f32_32x32x16_bf16 v[50:65], v[126:129], v[138:141], v[50:65]
	v_mfma_f32_32x32x16_bf16 v[2:17], v[130:133], v[134:137], v[2:17]
	v_mfma_f32_32x32x16_bf16 v[18:33], v[130:133], v[138:141], v[18:33]
	ds_read_b128 v[126:129], v88 offset:2048
	ds_read_b128 v[130:133], v88 offset:6144
	ds_read_b128 v[134:137], v92 offset:2048
	ds_read_b128 v[138:141], v92 offset:6144
	v_mfma_f32_32x32x16_bf16 v[34:49], v[142:145], v[150:153], v[34:49]
	v_mfma_f32_32x32x16_bf16 v[50:65], v[142:145], v[154:157], v[50:65]
	v_mfma_f32_32x32x16_bf16 v[2:17], v[146:149], v[150:153], v[2:17]
	v_mfma_f32_32x32x16_bf16 v[18:33], v[146:149], v[154:157], v[18:33]
	ds_read_b128 v[142:145], v89 offset:2048
	ds_read_b128 v[146:149], v89 offset:6144
	ds_read_b128 v[150:153], v93 offset:2048
	ds_read_b128 v[154:157], v93 offset:6144
	s_waitcnt lgkmcnt(0)
	s_barrier
	s_add_u32 m0, s14, 0x600
	s_nop 0
	global_load_lds_dwordx4 v[68:69], off offset:512
	s_add_u32 m0, s14, 0x1600
	s_nop 0
	global_load_lds_dwordx4 v[72:73], off offset:512
	s_add_u32 m0, s14, 0x2600
	s_nop 0
	global_load_lds_dwordx4 v[76:77], off offset:512
	s_add_u32 m0, s14, 0x3600
	s_nop 0
	global_load_lds_dwordx4 v[80:81], off offset:512
	s_add_u32 m0, s14, 0x4600
	s_nop 0
	global_load_lds_dwordx4 v[70:71], off offset:512
	s_add_u32 m0, s14, 0x5600
	s_nop 0
	global_load_lds_dwordx4 v[74:75], off offset:512
	s_add_u32 m0, s14, 0x6600
	s_nop 0
	global_load_lds_dwordx4 v[78:79], off offset:512
	s_add_u32 m0, s14, 0x7600
	s_nop 0
	global_load_lds_dwordx4 v[82:83], off offset:512
	v_mfma_f32_32x32x16_bf16 v[34:49], v[94:97], v[102:105], v[34:49]
	v_mfma_f32_32x32x16_bf16 v[50:65], v[94:97], v[106:109], v[50:65]
	v_mfma_f32_32x32x16_bf16 v[2:17], v[98:101], v[102:105], v[2:17]
	v_mfma_f32_32x32x16_bf16 v[18:33], v[98:101], v[106:109], v[18:33]
	s_waitcnt vmcnt(8)
	s_barrier
	ds_read_b128 v[94:97], v86 offset:34816
	ds_read_b128 v[98:101], v86 offset:38912
	ds_read_b128 v[102:105], v90 offset:34816
	ds_read_b128 v[106:109], v90 offset:38912
	v_mfma_f32_32x32x16_bf16 v[34:49], v[110:113], v[118:121], v[34:49]
	v_mfma_f32_32x32x16_bf16 v[50:65], v[110:113], v[122:125], v[50:65]
	v_mfma_f32_32x32x16_bf16 v[2:17], v[114:117], v[118:121], v[2:17]
	v_mfma_f32_32x32x16_bf16 v[18:33], v[114:117], v[122:125], v[18:33]
	ds_read_b128 v[110:113], v87 offset:34816
	ds_read_b128 v[114:117], v87 offset:38912
	ds_read_b128 v[118:121], v91 offset:34816
	ds_read_b128 v[122:125], v91 offset:38912
	v_mfma_f32_32x32x16_bf16 v[34:49], v[126:129], v[134:137], v[34:49]
	v_mfma_f32_32x32x16_bf16 v[50:65], v[126:129], v[138:141], v[50:65]
	v_mfma_f32_32x32x16_bf16 v[2:17], v[130:133], v[134:137], v[2:17]
	v_mfma_f32_32x32x16_bf16 v[18:33], v[130:133], v[138:141], v[18:33]
	ds_read_b128 v[126:129], v88 offset:34816
	ds_read_b128 v[130:133], v88 offset:38912
	ds_read_b128 v[134:137], v92 offset:34816
	ds_read_b128 v[138:141], v92 offset:38912
	v_mfma_f32_32x32x16_bf16 v[34:49], v[142:145], v[150:153], v[34:49]
	v_mfma_f32_32x32x16_bf16 v[50:65], v[142:145], v[154:157], v[50:65]
	v_mfma_f32_32x32x16_bf16 v[2:17], v[146:149], v[150:153], v[2:17]
	v_mfma_f32_32x32x16_bf16 v[18:33], v[146:149], v[154:157], v[18:33]
	ds_read_b128 v[142:145], v89 offset:34816
	ds_read_b128 v[146:149], v89 offset:38912
	ds_read_b128 v[150:153], v93 offset:34816
	ds_read_b128 v[154:157], v93 offset:38912
	s_waitcnt lgkmcnt(0)
	s_barrier
	s_add_u32 m0, s14, 0x8580
	s_nop 0
	global_load_lds_dwordx4 v[68:69], off offset:640
	s_add_u32 m0, s14, 0x9580
	s_nop 0
	global_load_lds_dwordx4 v[72:73], off offset:640
	s_add_u32 m0, s14, 0xa580
	s_nop 0
	global_load_lds_dwordx4 v[76:77], off offset:640
	s_add_u32 m0, s14, 0xb580
	s_nop 0
	global_load_lds_dwordx4 v[80:81], off offset:640
	s_add_u32 m0, s14, 0xc580
	s_nop 0
	global_load_lds_dwordx4 v[70:71], off offset:640
	s_add_u32 m0, s14, 0xd580
	s_nop 0
	global_load_lds_dwordx4 v[74:75], off offset:640
	s_add_u32 m0, s14, 0xe580
	s_nop 0
	global_load_lds_dwordx4 v[78:79], off offset:640
	s_add_u32 m0, s14, 0xf580
	s_nop 0
	global_load_lds_dwordx4 v[82:83], off offset:640
	v_mfma_f32_32x32x16_bf16 v[34:49], v[94:97], v[102:105], v[34:49]
	v_mfma_f32_32x32x16_bf16 v[50:65], v[94:97], v[106:109], v[50:65]
	v_mfma_f32_32x32x16_bf16 v[2:17], v[98:101], v[102:105], v[2:17]
	v_mfma_f32_32x32x16_bf16 v[18:33], v[98:101], v[106:109], v[18:33]
	s_waitcnt vmcnt(8)
	s_barrier
	ds_read_b128 v[94:97], v86 offset:2048
	ds_read_b128 v[98:101], v86 offset:6144
	ds_read_b128 v[102:105], v90 offset:2048
	ds_read_b128 v[106:109], v90 offset:6144
	v_mfma_f32_32x32x16_bf16 v[34:49], v[110:113], v[118:121], v[34:49]
	v_mfma_f32_32x32x16_bf16 v[50:65], v[110:113], v[122:125], v[50:65]
	v_mfma_f32_32x32x16_bf16 v[2:17], v[114:117], v[118:121], v[2:17]
	v_mfma_f32_32x32x16_bf16 v[18:33], v[114:117], v[122:125], v[18:33]
	ds_read_b128 v[110:113], v87 offset:2048
	ds_read_b128 v[114:117], v87 offset:6144
	ds_read_b128 v[118:121], v91 offset:2048
	ds_read_b128 v[122:125], v91 offset:6144
	v_mfma_f32_32x32x16_bf16 v[34:49], v[126:129], v[134:137], v[34:49]
	v_mfma_f32_32x32x16_bf16 v[50:65], v[126:129], v[138:141], v[50:65]
	v_mfma_f32_32x32x16_bf16 v[2:17], v[130:133], v[134:137], v[2:17]
	v_mfma_f32_32x32x16_bf16 v[18:33], v[130:133], v[138:141], v[18:33]
	ds_read_b128 v[126:129], v88 offset:2048
	ds_read_b128 v[130:133], v88 offset:6144
	ds_read_b128 v[134:137], v92 offset:2048
	ds_read_b128 v[138:141], v92 offset:6144
	v_mfma_f32_32x32x16_bf16 v[34:49], v[142:145], v[150:153], v[34:49]
	v_mfma_f32_32x32x16_bf16 v[50:65], v[142:145], v[154:157], v[50:65]
	v_mfma_f32_32x32x16_bf16 v[2:17], v[146:149], v[150:153], v[2:17]
	v_mfma_f32_32x32x16_bf16 v[18:33], v[146:149], v[154:157], v[18:33]
	ds_read_b128 v[142:145], v89 offset:2048
	ds_read_b128 v[146:149], v89 offset:6144
	ds_read_b128 v[150:153], v93 offset:2048
	ds_read_b128 v[154:157], v93 offset:6144
	s_waitcnt lgkmcnt(0)
	s_barrier
	s_add_u32 m0, s14, 0x500
	s_nop 0
	global_load_lds_dwordx4 v[68:69], off offset:768
	s_add_u32 m0, s14, 0x1500
	s_nop 0
	global_load_lds_dwordx4 v[72:73], off offset:768
	s_add_u32 m0, s14, 0x2500
	s_nop 0
	global_load_lds_dwordx4 v[76:77], off offset:768
	s_add_u32 m0, s14, 0x3500
	s_nop 0
	global_load_lds_dwordx4 v[80:81], off offset:768
	s_add_u32 m0, s14, 0x4500
	s_nop 0
	global_load_lds_dwordx4 v[70:71], off offset:768
	s_add_u32 m0, s14, 0x5500
	s_nop 0
	global_load_lds_dwordx4 v[74:75], off offset:768
	s_add_u32 m0, s14, 0x6500
	s_nop 0
	global_load_lds_dwordx4 v[78:79], off offset:768
	s_add_u32 m0, s14, 0x7500
	s_nop 0
	global_load_lds_dwordx4 v[82:83], off offset:768
	v_mfma_f32_32x32x16_bf16 v[34:49], v[94:97], v[102:105], v[34:49]
	v_mfma_f32_32x32x16_bf16 v[50:65], v[94:97], v[106:109], v[50:65]
	v_mfma_f32_32x32x16_bf16 v[2:17], v[98:101], v[102:105], v[2:17]
	v_mfma_f32_32x32x16_bf16 v[18:33], v[98:101], v[106:109], v[18:33]
	s_waitcnt vmcnt(8)
	s_barrier
	ds_read_b128 v[94:97], v86 offset:34816
	ds_read_b128 v[98:101], v86 offset:38912
	ds_read_b128 v[102:105], v90 offset:34816
	ds_read_b128 v[106:109], v90 offset:38912
	v_mfma_f32_32x32x16_bf16 v[34:49], v[110:113], v[118:121], v[34:49]
	v_mfma_f32_32x32x16_bf16 v[50:65], v[110:113], v[122:125], v[50:65]
	v_mfma_f32_32x32x16_bf16 v[2:17], v[114:117], v[118:121], v[2:17]
	v_mfma_f32_32x32x16_bf16 v[18:33], v[114:117], v[122:125], v[18:33]
	ds_read_b128 v[110:113], v87 offset:34816
	ds_read_b128 v[114:117], v87 offset:38912
	ds_read_b128 v[118:121], v91 offset:34816
	ds_read_b128 v[122:125], v91 offset:38912
	v_mfma_f32_32x32x16_bf16 v[34:49], v[126:129], v[134:137], v[34:49]
	v_mfma_f32_32x32x16_bf16 v[50:65], v[126:129], v[138:141], v[50:65]
	v_mfma_f32_32x32x16_bf16 v[2:17], v[130:133], v[134:137], v[2:17]
	v_mfma_f32_32x32x16_bf16 v[18:33], v[130:133], v[138:141], v[18:33]
	ds_read_b128 v[126:129], v88 offset:34816
	ds_read_b128 v[130:133], v88 offset:38912
	ds_read_b128 v[134:137], v92 offset:34816
	ds_read_b128 v[138:141], v92 offset:38912
	v_mfma_f32_32x32x16_bf16 v[34:49], v[142:145], v[150:153], v[34:49]
	v_mfma_f32_32x32x16_bf16 v[50:65], v[142:145], v[154:157], v[50:65]
	v_mfma_f32_32x32x16_bf16 v[2:17], v[146:149], v[150:153], v[2:17]
	v_mfma_f32_32x32x16_bf16 v[18:33], v[146:149], v[154:157], v[18:33]
	ds_read_b128 v[142:145], v89 offset:34816
	ds_read_b128 v[146:149], v89 offset:38912
	ds_read_b128 v[150:153], v93 offset:34816
	ds_read_b128 v[154:157], v93 offset:38912
	s_waitcnt lgkmcnt(0)
	s_barrier
	s_add_u32 m0, s14, 0x8480
	s_nop 0
	global_load_lds_dwordx4 v[68:69], off offset:896
	s_add_u32 m0, s14, 0x9480
	s_nop 0
	global_load_lds_dwordx4 v[72:73], off offset:896
	s_add_u32 m0, s14, 0xa480
	s_nop 0
	global_load_lds_dwordx4 v[76:77], off offset:896
	s_add_u32 m0, s14, 0xb480
	s_nop 0
	global_load_lds_dwordx4 v[80:81], off offset:896
	s_add_u32 m0, s14, 0xc480
	s_nop 0
	global_load_lds_dwordx4 v[70:71], off offset:896
	s_add_u32 m0, s14, 0xd480
	s_nop 0
	global_load_lds_dwordx4 v[74:75], off offset:896
	s_add_u32 m0, s14, 0xe480
	s_nop 0
	global_load_lds_dwordx4 v[78:79], off offset:896
	s_add_u32 m0, s14, 0xf480
	s_nop 0
	global_load_lds_dwordx4 v[82:83], off offset:896
	v_mfma_f32_32x32x16_bf16 v[34:49], v[94:97], v[102:105], v[34:49]
	v_mfma_f32_32x32x16_bf16 v[50:65], v[94:97], v[106:109], v[50:65]
	v_mfma_f32_32x32x16_bf16 v[2:17], v[98:101], v[102:105], v[2:17]
	v_mfma_f32_32x32x16_bf16 v[18:33], v[98:101], v[106:109], v[18:33]
	s_waitcnt vmcnt(8)
	s_barrier
	ds_read_b128 v[94:97], v86 offset:2048
	ds_read_b128 v[98:101], v86 offset:6144
	ds_read_b128 v[102:105], v90 offset:2048
	ds_read_b128 v[106:109], v90 offset:6144
	v_mfma_f32_32x32x16_bf16 v[34:49], v[110:113], v[118:121], v[34:49]
	v_mfma_f32_32x32x16_bf16 v[50:65], v[110:113], v[122:125], v[50:65]
	v_mfma_f32_32x32x16_bf16 v[2:17], v[114:117], v[118:121], v[2:17]
	v_mfma_f32_32x32x16_bf16 v[18:33], v[114:117], v[122:125], v[18:33]
	ds_read_b128 v[110:113], v87 offset:2048
	ds_read_b128 v[114:117], v87 offset:6144
	ds_read_b128 v[118:121], v91 offset:2048
	ds_read_b128 v[122:125], v91 offset:6144
	v_mfma_f32_32x32x16_bf16 v[34:49], v[126:129], v[134:137], v[34:49]
	v_mfma_f32_32x32x16_bf16 v[50:65], v[126:129], v[138:141], v[50:65]
	v_mfma_f32_32x32x16_bf16 v[2:17], v[130:133], v[134:137], v[2:17]
	v_mfma_f32_32x32x16_bf16 v[18:33], v[130:133], v[138:141], v[18:33]
	ds_read_b128 v[126:129], v88 offset:2048
	ds_read_b128 v[130:133], v88 offset:6144
	ds_read_b128 v[134:137], v92 offset:2048
	ds_read_b128 v[138:141], v92 offset:6144
	v_mfma_f32_32x32x16_bf16 v[34:49], v[142:145], v[150:153], v[34:49]
	v_mfma_f32_32x32x16_bf16 v[50:65], v[142:145], v[154:157], v[50:65]
	v_mfma_f32_32x32x16_bf16 v[2:17], v[146:149], v[150:153], v[2:17]
	v_mfma_f32_32x32x16_bf16 v[18:33], v[146:149], v[154:157], v[18:33]
	ds_read_b128 v[142:145], v89 offset:2048
	ds_read_b128 v[146:149], v89 offset:6144
	ds_read_b128 v[150:153], v93 offset:2048
	ds_read_b128 v[154:157], v93 offset:6144
	s_waitcnt lgkmcnt(0)
	s_barrier
	s_add_u32 m0, s14, 0x400
	s_nop 0
	global_load_lds_dwordx4 v[68:69], off offset:1024
	s_add_u32 m0, s14, 0x1400
	s_nop 0
	global_load_lds_dwordx4 v[72:73], off offset:1024
	s_add_u32 m0, s14, 0x2400
	s_nop 0
	global_load_lds_dwordx4 v[76:77], off offset:1024
	s_add_u32 m0, s14, 0x3400
	s_nop 0
	global_load_lds_dwordx4 v[80:81], off offset:1024
	s_add_u32 m0, s14, 0x4400
	s_nop 0
	global_load_lds_dwordx4 v[70:71], off offset:1024
	s_add_u32 m0, s14, 0x5400
	s_nop 0
	global_load_lds_dwordx4 v[74:75], off offset:1024
	s_add_u32 m0, s14, 0x6400
	s_nop 0
	global_load_lds_dwordx4 v[78:79], off offset:1024
	s_add_u32 m0, s14, 0x7400
	s_nop 0
	global_load_lds_dwordx4 v[82:83], off offset:1024
	v_mfma_f32_32x32x16_bf16 v[34:49], v[94:97], v[102:105], v[34:49]
	v_mfma_f32_32x32x16_bf16 v[50:65], v[94:97], v[106:109], v[50:65]
	v_mfma_f32_32x32x16_bf16 v[2:17], v[98:101], v[102:105], v[2:17]
	v_mfma_f32_32x32x16_bf16 v[18:33], v[98:101], v[106:109], v[18:33]
	s_waitcnt vmcnt(8)
	s_barrier
	ds_read_b128 v[94:97], v86 offset:34816
	ds_read_b128 v[98:101], v86 offset:38912
	ds_read_b128 v[102:105], v90 offset:34816
	ds_read_b128 v[106:109], v90 offset:38912
	v_mfma_f32_32x32x16_bf16 v[34:49], v[110:113], v[118:121], v[34:49]
	v_mfma_f32_32x32x16_bf16 v[50:65], v[110:113], v[122:125], v[50:65]
	v_mfma_f32_32x32x16_bf16 v[2:17], v[114:117], v[118:121], v[2:17]
	v_mfma_f32_32x32x16_bf16 v[18:33], v[114:117], v[122:125], v[18:33]
	ds_read_b128 v[110:113], v87 offset:34816
	ds_read_b128 v[114:117], v87 offset:38912
	ds_read_b128 v[118:121], v91 offset:34816
	ds_read_b128 v[122:125], v91 offset:38912
	v_mfma_f32_32x32x16_bf16 v[34:49], v[126:129], v[134:137], v[34:49]
	v_mfma_f32_32x32x16_bf16 v[50:65], v[126:129], v[138:141], v[50:65]
	v_mfma_f32_32x32x16_bf16 v[2:17], v[130:133], v[134:137], v[2:17]
	v_mfma_f32_32x32x16_bf16 v[18:33], v[130:133], v[138:141], v[18:33]
	ds_read_b128 v[126:129], v88 offset:34816
	ds_read_b128 v[130:133], v88 offset:38912
	ds_read_b128 v[134:137], v92 offset:34816
	ds_read_b128 v[138:141], v92 offset:38912
	v_mfma_f32_32x32x16_bf16 v[34:49], v[142:145], v[150:153], v[34:49]
	v_mfma_f32_32x32x16_bf16 v[50:65], v[142:145], v[154:157], v[50:65]
	v_mfma_f32_32x32x16_bf16 v[2:17], v[146:149], v[150:153], v[2:17]
	v_mfma_f32_32x32x16_bf16 v[18:33], v[146:149], v[154:157], v[18:33]
	ds_read_b128 v[142:145], v89 offset:34816
	ds_read_b128 v[146:149], v89 offset:38912
	ds_read_b128 v[150:153], v93 offset:34816
	ds_read_b128 v[154:157], v93 offset:38912
	s_waitcnt lgkmcnt(0)
	s_barrier
	s_add_u32 m0, s14, 0x8380
	s_nop 0
	global_load_lds_dwordx4 v[68:69], off offset:1152
	s_add_u32 m0, s14, 0x9380
	s_nop 0
	global_load_lds_dwordx4 v[72:73], off offset:1152
	s_add_u32 m0, s14, 0xa380
	s_nop 0
	global_load_lds_dwordx4 v[76:77], off offset:1152
	s_add_u32 m0, s14, 0xb380
	s_nop 0
	global_load_lds_dwordx4 v[80:81], off offset:1152
	s_add_u32 m0, s14, 0xc380
	s_nop 0
	global_load_lds_dwordx4 v[70:71], off offset:1152
	s_add_u32 m0, s14, 0xd380
	s_nop 0
	global_load_lds_dwordx4 v[74:75], off offset:1152
	s_add_u32 m0, s14, 0xe380
	s_nop 0
	global_load_lds_dwordx4 v[78:79], off offset:1152
	s_add_u32 m0, s14, 0xf380
	s_nop 0
	global_load_lds_dwordx4 v[82:83], off offset:1152
	v_mfma_f32_32x32x16_bf16 v[34:49], v[94:97], v[102:105], v[34:49]
	v_mfma_f32_32x32x16_bf16 v[50:65], v[94:97], v[106:109], v[50:65]
	v_mfma_f32_32x32x16_bf16 v[2:17], v[98:101], v[102:105], v[2:17]
	v_mfma_f32_32x32x16_bf16 v[18:33], v[98:101], v[106:109], v[18:33]
	s_waitcnt vmcnt(8)
	s_barrier
	ds_read_b128 v[94:97], v86 offset:2048
	ds_read_b128 v[98:101], v86 offset:6144
	ds_read_b128 v[102:105], v90 offset:2048
	ds_read_b128 v[106:109], v90 offset:6144
	v_mfma_f32_32x32x16_bf16 v[34:49], v[110:113], v[118:121], v[34:49]
	v_mfma_f32_32x32x16_bf16 v[50:65], v[110:113], v[122:125], v[50:65]
	v_mfma_f32_32x32x16_bf16 v[2:17], v[114:117], v[118:121], v[2:17]
	v_mfma_f32_32x32x16_bf16 v[18:33], v[114:117], v[122:125], v[18:33]
	ds_read_b128 v[110:113], v87 offset:2048
	ds_read_b128 v[114:117], v87 offset:6144
	ds_read_b128 v[118:121], v91 offset:2048
	ds_read_b128 v[122:125], v91 offset:6144
	v_mfma_f32_32x32x16_bf16 v[34:49], v[126:129], v[134:137], v[34:49]
	v_mfma_f32_32x32x16_bf16 v[50:65], v[126:129], v[138:141], v[50:65]
	v_mfma_f32_32x32x16_bf16 v[2:17], v[130:133], v[134:137], v[2:17]
	v_mfma_f32_32x32x16_bf16 v[18:33], v[130:133], v[138:141], v[18:33]
	ds_read_b128 v[126:129], v88 offset:2048
	ds_read_b128 v[130:133], v88 offset:6144
	ds_read_b128 v[134:137], v92 offset:2048
	ds_read_b128 v[138:141], v92 offset:6144
	v_mfma_f32_32x32x16_bf16 v[34:49], v[142:145], v[150:153], v[34:49]
	v_mfma_f32_32x32x16_bf16 v[50:65], v[142:145], v[154:157], v[50:65]
	v_mfma_f32_32x32x16_bf16 v[2:17], v[146:149], v[150:153], v[2:17]
	v_mfma_f32_32x32x16_bf16 v[18:33], v[146:149], v[154:157], v[18:33]
	ds_read_b128 v[142:145], v89 offset:2048
	ds_read_b128 v[146:149], v89 offset:6144
	ds_read_b128 v[150:153], v93 offset:2048
	ds_read_b128 v[154:157], v93 offset:6144
	s_waitcnt lgkmcnt(0)
	s_barrier
	s_add_u32 m0, s14, 0x300
	s_nop 0
	global_load_lds_dwordx4 v[68:69], off offset:1280
	s_add_u32 m0, s14, 0x1300
	s_nop 0
	global_load_lds_dwordx4 v[72:73], off offset:1280
	s_add_u32 m0, s14, 0x2300
	s_nop 0
	global_load_lds_dwordx4 v[76:77], off offset:1280
	s_add_u32 m0, s14, 0x3300
	s_nop 0
	global_load_lds_dwordx4 v[80:81], off offset:1280
	s_add_u32 m0, s14, 0x4300
	s_nop 0
	global_load_lds_dwordx4 v[70:71], off offset:1280
	s_add_u32 m0, s14, 0x5300
	s_nop 0
	global_load_lds_dwordx4 v[74:75], off offset:1280
	s_add_u32 m0, s14, 0x6300
	s_nop 0
	global_load_lds_dwordx4 v[78:79], off offset:1280
	s_add_u32 m0, s14, 0x7300
	s_nop 0
	global_load_lds_dwordx4 v[82:83], off offset:1280
	v_mfma_f32_32x32x16_bf16 v[34:49], v[94:97], v[102:105], v[34:49]
	v_mfma_f32_32x32x16_bf16 v[50:65], v[94:97], v[106:109], v[50:65]
	v_mfma_f32_32x32x16_bf16 v[2:17], v[98:101], v[102:105], v[2:17]
	v_mfma_f32_32x32x16_bf16 v[18:33], v[98:101], v[106:109], v[18:33]
	s_waitcnt vmcnt(8)
	s_barrier
	ds_read_b128 v[94:97], v86 offset:34816
	ds_read_b128 v[98:101], v86 offset:38912
	ds_read_b128 v[102:105], v90 offset:34816
	ds_read_b128 v[106:109], v90 offset:38912
	v_mfma_f32_32x32x16_bf16 v[34:49], v[110:113], v[118:121], v[34:49]
	v_mfma_f32_32x32x16_bf16 v[50:65], v[110:113], v[122:125], v[50:65]
	v_mfma_f32_32x32x16_bf16 v[2:17], v[114:117], v[118:121], v[2:17]
	v_mfma_f32_32x32x16_bf16 v[18:33], v[114:117], v[122:125], v[18:33]
	ds_read_b128 v[110:113], v87 offset:34816
	ds_read_b128 v[114:117], v87 offset:38912
	ds_read_b128 v[118:121], v91 offset:34816
	ds_read_b128 v[122:125], v91 offset:38912
	v_mfma_f32_32x32x16_bf16 v[34:49], v[126:129], v[134:137], v[34:49]
	v_mfma_f32_32x32x16_bf16 v[50:65], v[126:129], v[138:141], v[50:65]
	v_mfma_f32_32x32x16_bf16 v[2:17], v[130:133], v[134:137], v[2:17]
	v_mfma_f32_32x32x16_bf16 v[18:33], v[130:133], v[138:141], v[18:33]
	ds_read_b128 v[126:129], v88 offset:34816
	ds_read_b128 v[130:133], v88 offset:38912
	ds_read_b128 v[134:137], v92 offset:34816
	ds_read_b128 v[138:141], v92 offset:38912
	v_mfma_f32_32x32x16_bf16 v[34:49], v[142:145], v[150:153], v[34:49]
	v_mfma_f32_32x32x16_bf16 v[50:65], v[142:145], v[154:157], v[50:65]
	v_mfma_f32_32x32x16_bf16 v[2:17], v[146:149], v[150:153], v[2:17]
	v_mfma_f32_32x32x16_bf16 v[18:33], v[146:149], v[154:157], v[18:33]
	ds_read_b128 v[142:145], v89 offset:34816
	ds_read_b128 v[146:149], v89 offset:38912
	ds_read_b128 v[150:153], v93 offset:34816
	ds_read_b128 v[154:157], v93 offset:38912
	s_waitcnt lgkmcnt(0)
	s_barrier
	s_add_u32 m0, s14, 0x8280
	s_nop 0
	global_load_lds_dwordx4 v[68:69], off offset:1408
	s_add_u32 m0, s14, 0x9280
	s_nop 0
	global_load_lds_dwordx4 v[72:73], off offset:1408
	s_add_u32 m0, s14, 0xa280
	s_nop 0
	global_load_lds_dwordx4 v[76:77], off offset:1408
	s_add_u32 m0, s14, 0xb280
	s_nop 0
	global_load_lds_dwordx4 v[80:81], off offset:1408
	s_add_u32 m0, s14, 0xc280
	s_nop 0
	global_load_lds_dwordx4 v[70:71], off offset:1408
	s_add_u32 m0, s14, 0xd280
	s_nop 0
	global_load_lds_dwordx4 v[74:75], off offset:1408
	s_add_u32 m0, s14, 0xe280
	s_nop 0
	global_load_lds_dwordx4 v[78:79], off offset:1408
	s_add_u32 m0, s14, 0xf280
	s_nop 0
	global_load_lds_dwordx4 v[82:83], off offset:1408
	v_mfma_f32_32x32x16_bf16 v[34:49], v[94:97], v[102:105], v[34:49]
	v_mfma_f32_32x32x16_bf16 v[50:65], v[94:97], v[106:109], v[50:65]
	v_mfma_f32_32x32x16_bf16 v[2:17], v[98:101], v[102:105], v[2:17]
	v_mfma_f32_32x32x16_bf16 v[18:33], v[98:101], v[106:109], v[18:33]
	s_waitcnt vmcnt(8)
	s_barrier
	ds_read_b128 v[94:97], v86 offset:2048
	ds_read_b128 v[98:101], v86 offset:6144
	ds_read_b128 v[102:105], v90 offset:2048
	ds_read_b128 v[106:109], v90 offset:6144
	v_mfma_f32_32x32x16_bf16 v[34:49], v[110:113], v[118:121], v[34:49]
	v_mfma_f32_32x32x16_bf16 v[50:65], v[110:113], v[122:125], v[50:65]
	v_mfma_f32_32x32x16_bf16 v[2:17], v[114:117], v[118:121], v[2:17]
	v_mfma_f32_32x32x16_bf16 v[18:33], v[114:117], v[122:125], v[18:33]
	ds_read_b128 v[110:113], v87 offset:2048
	ds_read_b128 v[114:117], v87 offset:6144
	ds_read_b128 v[118:121], v91 offset:2048
	ds_read_b128 v[122:125], v91 offset:6144
	v_mfma_f32_32x32x16_bf16 v[34:49], v[126:129], v[134:137], v[34:49]
	v_mfma_f32_32x32x16_bf16 v[50:65], v[126:129], v[138:141], v[50:65]
	v_mfma_f32_32x32x16_bf16 v[2:17], v[130:133], v[134:137], v[2:17]
	v_mfma_f32_32x32x16_bf16 v[18:33], v[130:133], v[138:141], v[18:33]
	ds_read_b128 v[126:129], v88 offset:2048
	ds_read_b128 v[130:133], v88 offset:6144
	ds_read_b128 v[134:137], v92 offset:2048
	ds_read_b128 v[138:141], v92 offset:6144
	v_mfma_f32_32x32x16_bf16 v[34:49], v[142:145], v[150:153], v[34:49]
	v_mfma_f32_32x32x16_bf16 v[50:65], v[142:145], v[154:157], v[50:65]
	v_mfma_f32_32x32x16_bf16 v[2:17], v[146:149], v[150:153], v[2:17]
	v_mfma_f32_32x32x16_bf16 v[18:33], v[146:149], v[154:157], v[18:33]
	ds_read_b128 v[142:145], v89 offset:2048
	ds_read_b128 v[146:149], v89 offset:6144
	ds_read_b128 v[150:153], v93 offset:2048
	ds_read_b128 v[154:157], v93 offset:6144
	s_waitcnt lgkmcnt(0)
	s_barrier
	s_add_u32 m0, s14, 0x200
	s_nop 0
	global_load_lds_dwordx4 v[68:69], off offset:1536
	s_add_u32 m0, s14, 0x1200
	s_nop 0
	global_load_lds_dwordx4 v[72:73], off offset:1536
	s_add_u32 m0, s14, 0x2200
	s_nop 0
	global_load_lds_dwordx4 v[76:77], off offset:1536
	s_add_u32 m0, s14, 0x3200
	s_nop 0
	global_load_lds_dwordx4 v[80:81], off offset:1536
	s_add_u32 m0, s14, 0x4200
	s_nop 0
	global_load_lds_dwordx4 v[70:71], off offset:1536
	s_add_u32 m0, s14, 0x5200
	s_nop 0
	global_load_lds_dwordx4 v[74:75], off offset:1536
	s_add_u32 m0, s14, 0x6200
	s_nop 0
	global_load_lds_dwordx4 v[78:79], off offset:1536
	s_add_u32 m0, s14, 0x7200
	s_nop 0
	global_load_lds_dwordx4 v[82:83], off offset:1536
	v_mfma_f32_32x32x16_bf16 v[34:49], v[94:97], v[102:105], v[34:49]
	v_mfma_f32_32x32x16_bf16 v[50:65], v[94:97], v[106:109], v[50:65]
	v_mfma_f32_32x32x16_bf16 v[2:17], v[98:101], v[102:105], v[2:17]
	v_mfma_f32_32x32x16_bf16 v[18:33], v[98:101], v[106:109], v[18:33]
	s_waitcnt vmcnt(8)
	s_barrier
	ds_read_b128 v[94:97], v86 offset:34816
	ds_read_b128 v[98:101], v86 offset:38912
	ds_read_b128 v[102:105], v90 offset:34816
	ds_read_b128 v[106:109], v90 offset:38912
	v_mfma_f32_32x32x16_bf16 v[34:49], v[110:113], v[118:121], v[34:49]
	v_mfma_f32_32x32x16_bf16 v[50:65], v[110:113], v[122:125], v[50:65]
	v_mfma_f32_32x32x16_bf16 v[2:17], v[114:117], v[118:121], v[2:17]
	v_mfma_f32_32x32x16_bf16 v[18:33], v[114:117], v[122:125], v[18:33]
	ds_read_b128 v[110:113], v87 offset:34816
	ds_read_b128 v[114:117], v87 offset:38912
	ds_read_b128 v[118:121], v91 offset:34816
	ds_read_b128 v[122:125], v91 offset:38912
	v_mfma_f32_32x32x16_bf16 v[34:49], v[126:129], v[134:137], v[34:49]
	v_mfma_f32_32x32x16_bf16 v[50:65], v[126:129], v[138:141], v[50:65]
	v_mfma_f32_32x32x16_bf16 v[2:17], v[130:133], v[134:137], v[2:17]
	v_mfma_f32_32x32x16_bf16 v[18:33], v[130:133], v[138:141], v[18:33]
	ds_read_b128 v[126:129], v88 offset:34816
	ds_read_b128 v[130:133], v88 offset:38912
	ds_read_b128 v[134:137], v92 offset:34816
	ds_read_b128 v[138:141], v92 offset:38912
	v_mfma_f32_32x32x16_bf16 v[34:49], v[142:145], v[150:153], v[34:49]
	v_mfma_f32_32x32x16_bf16 v[50:65], v[142:145], v[154:157], v[50:65]
	v_mfma_f32_32x32x16_bf16 v[2:17], v[146:149], v[150:153], v[2:17]
	v_mfma_f32_32x32x16_bf16 v[18:33], v[146:149], v[154:157], v[18:33]
	ds_read_b128 v[142:145], v89 offset:34816
	ds_read_b128 v[146:149], v89 offset:38912
	ds_read_b128 v[150:153], v93 offset:34816
	ds_read_b128 v[154:157], v93 offset:38912
	s_waitcnt lgkmcnt(0)
	s_barrier
	s_add_u32 m0, s14, 0x8180
	s_nop 0
	global_load_lds_dwordx4 v[68:69], off offset:1664
	s_add_u32 m0, s14, 0x9180
	s_nop 0
	global_load_lds_dwordx4 v[72:73], off offset:1664
	s_add_u32 m0, s14, 0xa180
	s_nop 0
	global_load_lds_dwordx4 v[76:77], off offset:1664
	s_add_u32 m0, s14, 0xb180
	s_nop 0
	global_load_lds_dwordx4 v[80:81], off offset:1664
	s_add_u32 m0, s14, 0xc180
	s_nop 0
	global_load_lds_dwordx4 v[70:71], off offset:1664
	s_add_u32 m0, s14, 0xd180
	s_nop 0
	global_load_lds_dwordx4 v[74:75], off offset:1664
	s_add_u32 m0, s14, 0xe180
	s_nop 0
	global_load_lds_dwordx4 v[78:79], off offset:1664
	s_add_u32 m0, s14, 0xf180
	s_nop 0
	global_load_lds_dwordx4 v[82:83], off offset:1664
	v_mfma_f32_32x32x16_bf16 v[34:49], v[94:97], v[102:105], v[34:49]
	v_mfma_f32_32x32x16_bf16 v[50:65], v[94:97], v[106:109], v[50:65]
	v_mfma_f32_32x32x16_bf16 v[2:17], v[98:101], v[102:105], v[2:17]
	v_mfma_f32_32x32x16_bf16 v[18:33], v[98:101], v[106:109], v[18:33]
	s_waitcnt vmcnt(8)
	s_barrier
	ds_read_b128 v[94:97], v86 offset:2048
	ds_read_b128 v[98:101], v86 offset:6144
	ds_read_b128 v[102:105], v90 offset:2048
	ds_read_b128 v[106:109], v90 offset:6144
	v_mfma_f32_32x32x16_bf16 v[34:49], v[110:113], v[118:121], v[34:49]
	v_mfma_f32_32x32x16_bf16 v[50:65], v[110:113], v[122:125], v[50:65]
	v_mfma_f32_32x32x16_bf16 v[2:17], v[114:117], v[118:121], v[2:17]
	v_mfma_f32_32x32x16_bf16 v[18:33], v[114:117], v[122:125], v[18:33]
	ds_read_b128 v[110:113], v87 offset:2048
	ds_read_b128 v[114:117], v87 offset:6144
	ds_read_b128 v[118:121], v91 offset:2048
	ds_read_b128 v[122:125], v91 offset:6144
	v_mfma_f32_32x32x16_bf16 v[34:49], v[126:129], v[134:137], v[34:49]
	v_mfma_f32_32x32x16_bf16 v[50:65], v[126:129], v[138:141], v[50:65]
	v_mfma_f32_32x32x16_bf16 v[2:17], v[130:133], v[134:137], v[2:17]
	v_mfma_f32_32x32x16_bf16 v[18:33], v[130:133], v[138:141], v[18:33]
	ds_read_b128 v[126:129], v88 offset:2048
	ds_read_b128 v[130:133], v88 offset:6144
	ds_read_b128 v[134:137], v92 offset:2048
	ds_read_b128 v[138:141], v92 offset:6144
	v_mfma_f32_32x32x16_bf16 v[34:49], v[142:145], v[150:153], v[34:49]
	v_mfma_f32_32x32x16_bf16 v[50:65], v[142:145], v[154:157], v[50:65]
	v_mfma_f32_32x32x16_bf16 v[2:17], v[146:149], v[150:153], v[2:17]
	v_mfma_f32_32x32x16_bf16 v[18:33], v[146:149], v[154:157], v[18:33]
	ds_read_b128 v[142:145], v89 offset:2048
	ds_read_b128 v[146:149], v89 offset:6144
	ds_read_b128 v[150:153], v93 offset:2048
	ds_read_b128 v[154:157], v93 offset:6144
	s_waitcnt lgkmcnt(0)
	s_barrier
	s_add_u32 m0, s14, 0x100
	s_nop 0
	global_load_lds_dwordx4 v[68:69], off offset:1792
	s_add_u32 m0, s14, 0x1100
	s_nop 0
	global_load_lds_dwordx4 v[72:73], off offset:1792
	s_add_u32 m0, s14, 0x2100
	s_nop 0
	global_load_lds_dwordx4 v[76:77], off offset:1792
	s_add_u32 m0, s14, 0x3100
	s_nop 0
	global_load_lds_dwordx4 v[80:81], off offset:1792
	s_add_u32 m0, s14, 0x4100
	s_nop 0
	global_load_lds_dwordx4 v[70:71], off offset:1792
	s_add_u32 m0, s14, 0x5100
	s_nop 0
	global_load_lds_dwordx4 v[74:75], off offset:1792
	s_add_u32 m0, s14, 0x6100
	s_nop 0
	global_load_lds_dwordx4 v[78:79], off offset:1792
	s_add_u32 m0, s14, 0x7100
	s_nop 0
	global_load_lds_dwordx4 v[82:83], off offset:1792
	v_mfma_f32_32x32x16_bf16 v[34:49], v[94:97], v[102:105], v[34:49]
	v_mfma_f32_32x32x16_bf16 v[50:65], v[94:97], v[106:109], v[50:65]
	v_mfma_f32_32x32x16_bf16 v[2:17], v[98:101], v[102:105], v[2:17]
	v_mfma_f32_32x32x16_bf16 v[18:33], v[98:101], v[106:109], v[18:33]
	s_waitcnt vmcnt(8)
	s_barrier
	ds_read_b128 v[94:97], v86 offset:34816
	ds_read_b128 v[98:101], v86 offset:38912
	ds_read_b128 v[102:105], v90 offset:34816
	ds_read_b128 v[106:109], v90 offset:38912
	v_mfma_f32_32x32x16_bf16 v[34:49], v[110:113], v[118:121], v[34:49]
	v_mfma_f32_32x32x16_bf16 v[50:65], v[110:113], v[122:125], v[50:65]
	v_mfma_f32_32x32x16_bf16 v[2:17], v[114:117], v[118:121], v[2:17]
	v_mfma_f32_32x32x16_bf16 v[18:33], v[114:117], v[122:125], v[18:33]
	ds_read_b128 v[110:113], v87 offset:34816
	ds_read_b128 v[114:117], v87 offset:38912
	ds_read_b128 v[118:121], v91 offset:34816
	ds_read_b128 v[122:125], v91 offset:38912
	v_mfma_f32_32x32x16_bf16 v[34:49], v[126:129], v[134:137], v[34:49]
	v_mfma_f32_32x32x16_bf16 v[50:65], v[126:129], v[138:141], v[50:65]
	v_mfma_f32_32x32x16_bf16 v[2:17], v[130:133], v[134:137], v[2:17]
	v_mfma_f32_32x32x16_bf16 v[18:33], v[130:133], v[138:141], v[18:33]
	ds_read_b128 v[126:129], v88 offset:34816
	ds_read_b128 v[130:133], v88 offset:38912
	ds_read_b128 v[134:137], v92 offset:34816
	ds_read_b128 v[138:141], v92 offset:38912
	v_mfma_f32_32x32x16_bf16 v[34:49], v[142:145], v[150:153], v[34:49]
	v_mfma_f32_32x32x16_bf16 v[50:65], v[142:145], v[154:157], v[50:65]
	v_mfma_f32_32x32x16_bf16 v[2:17], v[146:149], v[150:153], v[2:17]
	v_mfma_f32_32x32x16_bf16 v[18:33], v[146:149], v[154:157], v[18:33]
	ds_read_b128 v[142:145], v89 offset:34816
	ds_read_b128 v[146:149], v89 offset:38912
	ds_read_b128 v[150:153], v93 offset:34816
	ds_read_b128 v[154:157], v93 offset:38912
	s_waitcnt lgkmcnt(0)
	s_barrier
	s_add_u32 m0, s14, 0x8080
	s_nop 0
	global_load_lds_dwordx4 v[68:69], off offset:1920
	s_add_u32 m0, s14, 0x9080
	s_nop 0
	global_load_lds_dwordx4 v[72:73], off offset:1920
	s_add_u32 m0, s14, 0xa080
	s_nop 0
	global_load_lds_dwordx4 v[76:77], off offset:1920
	s_add_u32 m0, s14, 0xb080
	s_nop 0
	global_load_lds_dwordx4 v[80:81], off offset:1920
	s_add_u32 m0, s14, 0xc080
	s_nop 0
	global_load_lds_dwordx4 v[70:71], off offset:1920
	s_add_u32 m0, s14, 0xd080
	s_nop 0
	global_load_lds_dwordx4 v[74:75], off offset:1920
	s_add_u32 m0, s14, 0xe080
	s_nop 0
	global_load_lds_dwordx4 v[78:79], off offset:1920
	s_add_u32 m0, s14, 0xf080
	s_nop 0
	global_load_lds_dwordx4 v[82:83], off offset:1920
	v_mfma_f32_32x32x16_bf16 v[34:49], v[94:97], v[102:105], v[34:49]
	v_mfma_f32_32x32x16_bf16 v[50:65], v[94:97], v[106:109], v[50:65]
	v_mfma_f32_32x32x16_bf16 v[2:17], v[98:101], v[102:105], v[2:17]
	v_mfma_f32_32x32x16_bf16 v[18:33], v[98:101], v[106:109], v[18:33]
	s_waitcnt vmcnt(8)
	s_barrier
	ds_read_b128 v[94:97], v86 offset:2048
	ds_read_b128 v[98:101], v86 offset:6144
	ds_read_b128 v[102:105], v90 offset:2048
	ds_read_b128 v[106:109], v90 offset:6144
	v_mfma_f32_32x32x16_bf16 v[34:49], v[110:113], v[118:121], v[34:49]
	v_mfma_f32_32x32x16_bf16 v[50:65], v[110:113], v[122:125], v[50:65]
	v_mfma_f32_32x32x16_bf16 v[2:17], v[114:117], v[118:121], v[2:17]
	v_mfma_f32_32x32x16_bf16 v[18:33], v[114:117], v[122:125], v[18:33]
	ds_read_b128 v[110:113], v87 offset:2048
	ds_read_b128 v[114:117], v87 offset:6144
	ds_read_b128 v[118:121], v91 offset:2048
	ds_read_b128 v[122:125], v91 offset:6144
	v_mfma_f32_32x32x16_bf16 v[34:49], v[126:129], v[134:137], v[34:49]
	v_mfma_f32_32x32x16_bf16 v[50:65], v[126:129], v[138:141], v[50:65]
	v_mfma_f32_32x32x16_bf16 v[2:17], v[130:133], v[134:137], v[2:17]
	v_mfma_f32_32x32x16_bf16 v[18:33], v[130:133], v[138:141], v[18:33]
	ds_read_b128 v[126:129], v88 offset:2048
	ds_read_b128 v[130:133], v88 offset:6144
	ds_read_b128 v[134:137], v92 offset:2048
	ds_read_b128 v[138:141], v92 offset:6144
	v_mfma_f32_32x32x16_bf16 v[34:49], v[142:145], v[150:153], v[34:49]
	v_mfma_f32_32x32x16_bf16 v[50:65], v[142:145], v[154:157], v[50:65]
	v_mfma_f32_32x32x16_bf16 v[2:17], v[146:149], v[150:153], v[2:17]
	v_mfma_f32_32x32x16_bf16 v[18:33], v[146:149], v[154:157], v[18:33]
	ds_read_b128 v[142:145], v89 offset:2048
	ds_read_b128 v[146:149], v89 offset:6144
	ds_read_b128 v[150:153], v93 offset:2048
	ds_read_b128 v[154:157], v93 offset:6144
	s_waitcnt lgkmcnt(0)
	v_mfma_f32_32x32x16_bf16 v[34:49], v[94:97], v[102:105], v[34:49]
	v_mfma_f32_32x32x16_bf16 v[50:65], v[94:97], v[106:109], v[50:65]
	v_mfma_f32_32x32x16_bf16 v[2:17], v[98:101], v[102:105], v[2:17]
	v_mfma_f32_32x32x16_bf16 v[18:33], v[98:101], v[106:109], v[18:33]
	s_waitcnt vmcnt(0)
	s_barrier
	ds_read_b128 v[94:97], v86 offset:34816
	ds_read_b128 v[98:101], v86 offset:38912
	ds_read_b128 v[102:105], v90 offset:34816
	ds_read_b128 v[106:109], v90 offset:38912
	v_mfma_f32_32x32x16_bf16 v[34:49], v[110:113], v[118:121], v[34:49]
	v_mfma_f32_32x32x16_bf16 v[50:65], v[110:113], v[122:125], v[50:65]
	v_mfma_f32_32x32x16_bf16 v[2:17], v[114:117], v[118:121], v[2:17]
	v_mfma_f32_32x32x16_bf16 v[18:33], v[114:117], v[122:125], v[18:33]
	ds_read_b128 v[110:113], v87 offset:34816
	ds_read_b128 v[114:117], v87 offset:38912
	ds_read_b128 v[118:121], v91 offset:34816
	ds_read_b128 v[122:125], v91 offset:38912
	v_mfma_f32_32x32x16_bf16 v[34:49], v[126:129], v[134:137], v[34:49]
	v_mfma_f32_32x32x16_bf16 v[50:65], v[126:129], v[138:141], v[50:65]
	v_mfma_f32_32x32x16_bf16 v[2:17], v[130:133], v[134:137], v[2:17]
	v_mfma_f32_32x32x16_bf16 v[18:33], v[130:133], v[138:141], v[18:33]
	ds_read_b128 v[126:129], v88 offset:34816
	ds_read_b128 v[130:133], v88 offset:38912
	ds_read_b128 v[134:137], v92 offset:34816
	ds_read_b128 v[138:141], v92 offset:38912
	v_mfma_f32_32x32x16_bf16 v[34:49], v[142:145], v[150:153], v[34:49]
	v_mfma_f32_32x32x16_bf16 v[50:65], v[142:145], v[154:157], v[50:65]
	v_mfma_f32_32x32x16_bf16 v[2:17], v[146:149], v[150:153], v[2:17]
	v_mfma_f32_32x32x16_bf16 v[18:33], v[146:149], v[154:157], v[18:33]
	ds_read_b128 v[142:145], v89 offset:34816
	ds_read_b128 v[146:149], v89 offset:38912
	ds_read_b128 v[150:153], v93 offset:34816
	ds_read_b128 v[154:157], v93 offset:38912
	s_waitcnt lgkmcnt(0)
	v_mfma_f32_32x32x16_bf16 v[34:49], v[94:97], v[102:105], v[34:49]
	v_mfma_f32_32x32x16_bf16 v[50:65], v[94:97], v[106:109], v[50:65]
	v_mfma_f32_32x32x16_bf16 v[2:17], v[98:101], v[102:105], v[2:17]
	v_mfma_f32_32x32x16_bf16 v[18:33], v[98:101], v[106:109], v[18:33]
	v_mfma_f32_32x32x16_bf16 v[34:49], v[110:113], v[118:121], v[34:49]
	v_mfma_f32_32x32x16_bf16 v[50:65], v[110:113], v[122:125], v[50:65]
	v_mfma_f32_32x32x16_bf16 v[2:17], v[114:117], v[118:121], v[2:17]
	v_mfma_f32_32x32x16_bf16 v[18:33], v[114:117], v[122:125], v[18:33]
	v_mfma_f32_32x32x16_bf16 v[34:49], v[126:129], v[134:137], v[34:49]
	v_mfma_f32_32x32x16_bf16 v[50:65], v[126:129], v[138:141], v[50:65]
	v_mfma_f32_32x32x16_bf16 v[2:17], v[130:133], v[134:137], v[2:17]
	v_mfma_f32_32x32x16_bf16 v[18:33], v[130:133], v[138:141], v[18:33]
	v_mfma_f32_32x32x16_bf16 v[34:49], v[142:145], v[150:153], v[34:49]
	v_mfma_f32_32x32x16_bf16 v[50:65], v[142:145], v[154:157], v[50:65]
	v_mfma_f32_32x32x16_bf16 v[2:17], v[146:149], v[150:153], v[2:17]
	v_mfma_f32_32x32x16_bf16 v[18:33], v[146:149], v[154:157], v[18:33]
	v_mov_b32_e32 v66, v178
	s_waitcnt lgkmcnt(0)
	s_barrier
	v_lshrrev_b32_e32 v0, 1, v66
	v_and_b32_e32 v0, 0xfffffc0, v0
	v_lshrrev_b32_e32 v67, 3, v66
	v_and_or_b32 v0, v67, 4, v0
	v_and_b32_e32 v67, 0x5f, v66
	v_mul_lo_u32 v0, v0, s83
	v_lshl_add_u32 v0, v67, 2, v0
	s_nop 11
	ds_write2_b32 v0, v34, v50 offset1:32
	ds_write2_b32 v0, v35, v51 offset0:132 offset1:164
	v_add_u32_e32 v34, 0x400, v0
	ds_write2_b32 v34, v36, v52 offset0:8 offset1:40
	ds_write2_b32 v34, v37, v53 offset0:140 offset1:172
	v_add_u32_e32 v34, 0x1000, v0
	ds_write2_b32 v34, v38, v54 offset0:32 offset1:64
	ds_write2_b32 v34, v39, v55 offset0:164 offset1:196
	v_add_u32_e32 v34, 0x1400, v0
	ds_write2_b32 v34, v40, v56 offset0:40 offset1:72
	ds_write2_b32 v34, v41, v57 offset0:172 offset1:204
	v_add_u32_e32 v34, 0x2000, v0
	ds_write2_b32 v34, v42, v58 offset0:64 offset1:96
	ds_write2_b32 v34, v43, v59 offset0:196 offset1:228
	v_add_u32_e32 v34, 0x2400, v0
	ds_write2_b32 v34, v44, v60 offset0:72 offset1:104
	ds_write2_b32 v34, v45, v61 offset0:204 offset1:236
	v_add_u32_e32 v34, 0x3000, v0
	ds_write2_b32 v34, v46, v62 offset0:96 offset1:128
	v_add_u32_e32 v34, 0x3200, v0
	ds_write2_b32 v34, v47, v63 offset0:100 offset1:132
	v_add_u32_e32 v34, 0x3400, v0
	ds_write2_b32 v34, v48, v64 offset0:104 offset1:136
	v_add_u32_e32 v34, 0x3600, v0
	ds_write2_b32 v34, v49, v65 offset0:108 offset1:140
	v_add_u32_e32 v34, 0x4000, v0
	s_nop 11
	ds_write2_b32 v34, v2, v18 offset0:128 offset1:160
	v_add_u32_e32 v2, 0x4400, v0
	ds_write2_b32 v2, v3, v19 offset0:4 offset1:36
	ds_write2_b32 v2, v4, v20 offset0:136 offset1:168
	v_add_u32_e32 v2, 0x4800, v0
	ds_write2_b32 v2, v5, v21 offset0:12 offset1:44
	v_add_u32_e32 v2, 0x5000, v0
	ds_write2_b32 v2, v6, v22 offset0:160 offset1:192
	v_add_u32_e32 v2, 0x5400, v0
	ds_write2_b32 v2, v7, v23 offset0:36 offset1:68
	ds_write2_b32 v2, v8, v24 offset0:168 offset1:200
	v_add_u32_e32 v2, 0x5800, v0
	ds_write2_b32 v2, v9, v25 offset0:44 offset1:76
	v_add_u32_e32 v2, 0x6000, v0
	ds_write2_b32 v2, v10, v26 offset0:192 offset1:224
	v_add_u32_e32 v2, 0x6400, v0
	ds_write2_b32 v2, v11, v27 offset0:68 offset1:100
	ds_write2_b32 v2, v12, v28 offset0:200 offset1:232
	v_add_u32_e32 v2, 0x6800, v0
	v_lshlrev_b32_e32 v6, 2, v66
	ds_write2_b32 v2, v13, v29 offset0:76 offset1:108
	v_add_u32_e32 v2, 0x7200, v0
	v_and_b32_e32 v6, 4, v6
	ds_write2_b32 v2, v14, v30 offset0:96 offset1:128
	v_add_u32_e32 v2, 0x7400, v0
	v_cvt_f32_ubyte0_e32 v7, v6
	ds_write2_b32 v2, v15, v31 offset0:100 offset1:132
	v_add_u32_e32 v2, 0x7600, v0
	v_add_u32_e32 v0, 0x7800, v0
	v_mul_f32_e32 v7, 0xbfd49a78, v7
	ds_write2_b32 v0, v17, v33 offset0:108 offset1:140
	v_lshlrev_b32_e32 v0, 3, v66
	v_exp_f32_e32 v15, v7
	v_or_b32_e32 v7, 1, v6
	v_and_b32_e32 v0, 0x78, v0
	v_cvt_f32_ubyte0_e32 v7, v7
	ds_write2_b32 v2, v16, v32 offset0:104 offset1:136
	v_or_b32_e32 v2, s0, v0
	v_mov_b32_e32 v4, s0
	s_movk_i32 s0, 0xffe0
	v_mul_f32_e32 v7, 0xbfd49a78, v7
	v_lshlrev_b32_e32 v14, 2, v0
	v_bitop3_b32 v0, v0, s0, v4 bitop3:0xc8
	s_movk_i32 s0, 0x280
	v_exp_f32_e32 v28, v7
	v_or_b32_e32 v7, 2, v6
	v_or_b32_e32 v6, 3, v6
	v_cmp_ne_u32_e64 s[40:41], s0, v0
	s_movk_i32 s0, 0x149f
	v_cvt_f32_ubyte0_e32 v7, v7
	v_cvt_f32_ubyte0_e32 v6, v6
	v_cmp_gt_i32_e64 s[38:39], s1, v2
	v_cmp_lt_i32_e64 s[42:43], s0, v2
	v_mul_f32_e32 v7, 0xbfd49a78, v7
	v_mul_f32_e32 v6, 0xbfd49a78, v6
	v_readlane_b32 s0, v251, 35
	v_mov_b32_e32 v4, v2
	v_mov_b32_e32 v5, v1
	v_exp_f32_e32 v29, v7
	v_exp_f32_e32 v30, v6
	v_readlane_b32 s1, v251, 36
	v_ashrrev_i32_e32 v3, 31, v2
	v_add_u32_e32 v0, 0xfffffd80, v2
	v_lshl_add_u64 v[18:19], v[4:5], 2, s[0:1]
	v_readlane_b32 s0, v249, 11
	v_readlane_b32 s1, v249, 12
	v_cmp_gt_u32_e64 s[44:45], 16, v0
	v_cmp_gt_u32_e64 s[46:47], 14, v0
	v_cmp_gt_u32_e64 s[48:49], 12, v0
	v_cmp_gt_u32_e64 s[50:51], 10, v0
	v_lshl_add_u64 v[16:17], v[2:3], 1, s[78:79]
	v_lshl_add_u64 v[20:21], v[0:1], 1, s[0:1]
	s_waitcnt lgkmcnt(0)
	s_barrier
	s_branch .LBB0_465

.LBB0_582:
	s_add_i32 s0, s25, 0xfffffc00
	s_lshr_b32 s1, s0, 1
	s_lshl_b32 s0, s25, 7
	s_and_b32 s0, s0, 0x80
	s_waitcnt vmcnt(12)
	v_mov_b32_e32 v36, v178
	s_or_b32 s0, s0, 0x300
	s_lshl_b32 s12, s1, 18
	v_readlane_b32 s22, v251, 31
	v_readlane_b32 s23, v251, 32
	v_ashrrev_i32_e32 v34, 3, v36
	s_add_u32 s12, s22, s12
	v_lshlrev_b32_e32 v0, 3, v36
	v_ashrrev_i32_e32 v35, 31, v34
	s_addc_u32 s13, s23, 0
	s_lshl_b32 s22, s0, 11
	v_and_b32_e32 v37, 56, v0
	s_waitcnt vmcnt(5)
	v_lshlrev_b64 v[2:3], 11, v[34:35]
	s_add_u32 s22, s92, s22
	v_lshl_add_u64 v[4:5], s[12:13], 0, v[2:3]
	v_lshlrev_b32_e32 v0, 1, v37
	s_addc_u32 s23, s93, 0
	v_lshl_add_u64 v[68:69], v[4:5], 0, v[0:1]
	v_lshl_add_u64 v[2:3], s[22:23], 0, v[2:3]
	v_lshl_add_u64 v[70:71], v[2:3], 0, v[0:1]
	v_and_b32_e32 v0, 7, v36
	v_bfe_u32 v66, v36, 4, 3
	v_xor_b32_e32 v66, v66, v0
	v_sub_u32_e32 v66, v66, v0
	v_lshlrev_b32_e32 v66, 4, v66
	v_ashrrev_i32_e32 v67, 31, v66
	v_lshl_add_u64 v[68:69], v[68:69], 0, v[66:67]
	v_lshl_add_u64 v[70:71], v[70:71], 0, v[66:67]
	v_add_co_u32_e32 v72, vcc, s73, v68
	s_nop 1
	v_addc_co_u32_e32 v73, vcc, 0, v69, vcc
	v_add_co_u32_e32 v74, vcc, s73, v70
	s_nop 1
	v_addc_co_u32_e32 v75, vcc, 0, v71, vcc
	v_add_co_u32_e32 v76, vcc, s52, v68
	s_nop 1
	v_addc_co_u32_e32 v77, vcc, 0, v69, vcc
	v_add_co_u32_e32 v78, vcc, s52, v70
	s_nop 1
	v_addc_co_u32_e32 v79, vcc, 0, v71, vcc
	v_add_co_u32_e32 v80, vcc, s53, v68
	s_nop 1
	v_addc_co_u32_e32 v81, vcc, 0, v69, vcc
	v_add_co_u32_e32 v82, vcc, s53, v70
	s_nop 1
	v_addc_co_u32_e32 v83, vcc, 0, v71, vcc
	v_and_b32_e32 v0, 31, v36
	v_bfe_u32 v66, v36, 5, 1
	v_bfe_u32 v67, v36, 1, 3
	v_xor_b32_e32 v66, v66, v67
	v_lshlrev_b32_e32 v66, 4, v66
	v_lshl_add_u32 v66, v0, 7, v66
	v_bfe_u32 v67, v36, 7, 1
	v_lshl_add_u32 v86, v67, 13, v66
	v_bfe_u32 v67, v36, 6, 1
	v_lshl_add_u32 v90, v67, 13, v66
	v_add_u32_e32 v90, 0x4000, v90
	v_xor_b32_e32 v87, 32, v86
	v_xor_b32_e32 v91, 32, v90
	v_xor_b32_e32 v88, 64, v86
	v_xor_b32_e32 v92, 64, v90
	v_xor_b32_e32 v89, 96, v86
	v_xor_b32_e32 v93, 96, v90
	v_lshrrev_b32_e32 v66, 6, v36
	v_lshlrev_b32_e32 v66, 10, v66
	s_nop 1
	v_readfirstlane_b32 s14, v66
	s_mov_b32 s12, 0
	s_lshl_b32 s1, s1, 7
	s_add_u32 m0, s14, 0x800
	s_nop 0
	global_load_lds_dwordx4 v[68:69], off
	s_add_u32 m0, s14, 0x1800
	s_nop 0
	global_load_lds_dwordx4 v[72:73], off
	s_add_u32 m0, s14, 0x2800
	s_nop 0
	global_load_lds_dwordx4 v[76:77], off
	s_add_u32 m0, s14, 0x3800
	s_nop 0
	global_load_lds_dwordx4 v[80:81], off
	s_add_u32 m0, s14, 0x4800
	s_nop 0
	global_load_lds_dwordx4 v[70:71], off
	s_add_u32 m0, s14, 0x5800
	s_nop 0
	global_load_lds_dwordx4 v[74:75], off
	s_add_u32 m0, s14, 0x6800
	s_nop 0
	global_load_lds_dwordx4 v[78:79], off
	s_add_u32 m0, s14, 0x7800
	s_nop 0
	global_load_lds_dwordx4 v[82:83], off
	s_add_u32 m0, s14, 0x8780
	s_nop 0
	global_load_lds_dwordx4 v[68:69], off offset:128
	s_add_u32 m0, s14, 0x9780
	s_nop 0
	global_load_lds_dwordx4 v[72:73], off offset:128
	s_add_u32 m0, s14, 0xa780
	s_nop 0
	global_load_lds_dwordx4 v[76:77], off offset:128
	s_add_u32 m0, s14, 0xb780
	s_nop 0
	global_load_lds_dwordx4 v[80:81], off offset:128
	s_add_u32 m0, s14, 0xc780
	s_nop 0
	global_load_lds_dwordx4 v[70:71], off offset:128
	s_add_u32 m0, s14, 0xd780
	s_nop 0
	global_load_lds_dwordx4 v[74:75], off offset:128
	s_add_u32 m0, s14, 0xe780
	s_nop 0
	global_load_lds_dwordx4 v[78:79], off offset:128
	s_add_u32 m0, s14, 0xf780
	s_nop 0
	global_load_lds_dwordx4 v[82:83], off offset:128
	s_waitcnt vmcnt(8)
	s_barrier
	ds_read_b128 v[94:97], v86 offset:2048
	ds_read_b128 v[98:101], v86 offset:6144
	ds_read_b128 v[102:105], v90 offset:2048
	ds_read_b128 v[106:109], v90 offset:6144
	ds_read_b128 v[110:113], v87 offset:2048
	ds_read_b128 v[114:117], v87 offset:6144
	ds_read_b128 v[118:121], v91 offset:2048
	ds_read_b128 v[122:125], v91 offset:6144
	ds_read_b128 v[126:129], v88 offset:2048
	ds_read_b128 v[130:133], v88 offset:6144
	ds_read_b128 v[134:137], v92 offset:2048
	ds_read_b128 v[138:141], v92 offset:6144
	ds_read_b128 v[142:145], v89 offset:2048
	ds_read_b128 v[146:149], v89 offset:6144
	ds_read_b128 v[150:153], v93 offset:2048
	ds_read_b128 v[154:157], v93 offset:6144
	s_waitcnt lgkmcnt(0)
	s_barrier
	s_add_u32 m0, s14, 0x700
	s_nop 0
	global_load_lds_dwordx4 v[68:69], off offset:256
	s_add_u32 m0, s14, 0x1700
	s_nop 0
	global_load_lds_dwordx4 v[72:73], off offset:256
	s_add_u32 m0, s14, 0x2700
	s_nop 0
	global_load_lds_dwordx4 v[76:77], off offset:256
	s_add_u32 m0, s14, 0x3700
	s_nop 0
	global_load_lds_dwordx4 v[80:81], off offset:256
	s_add_u32 m0, s14, 0x4700
	s_nop 0
	global_load_lds_dwordx4 v[70:71], off offset:256
	s_add_u32 m0, s14, 0x5700
	s_nop 0
	global_load_lds_dwordx4 v[74:75], off offset:256
	s_add_u32 m0, s14, 0x6700
	s_nop 0
	global_load_lds_dwordx4 v[78:79], off offset:256
	s_add_u32 m0, s14, 0x7700
	s_nop 0
	global_load_lds_dwordx4 v[82:83], off offset:256
	v_mfma_f32_32x32x16_bf16 v[34:49], v[94:97], v[102:105], 0
	v_mfma_f32_32x32x16_bf16 v[50:65], v[94:97], v[106:109], 0
	v_mfma_f32_32x32x16_bf16 v[2:17], v[98:101], v[102:105], 0
	v_mfma_f32_32x32x16_bf16 v[18:33], v[98:101], v[106:109], 0
	s_waitcnt vmcnt(8)
	s_barrier
	ds_read_b128 v[94:97], v86 offset:34816
	ds_read_b128 v[98:101], v86 offset:38912
	ds_read_b128 v[102:105], v90 offset:34816
	ds_read_b128 v[106:109], v90 offset:38912
	v_mfma_f32_32x32x16_bf16 v[34:49], v[110:113], v[118:121], v[34:49]
	v_mfma_f32_32x32x16_bf16 v[50:65], v[110:113], v[122:125], v[50:65]
	v_mfma_f32_32x32x16_bf16 v[2:17], v[114:117], v[118:121], v[2:17]
	v_mfma_f32_32x32x16_bf16 v[18:33], v[114:117], v[122:125], v[18:33]
	ds_read_b128 v[110:113], v87 offset:34816
	ds_read_b128 v[114:117], v87 offset:38912
	ds_read_b128 v[118:121], v91 offset:34816
	ds_read_b128 v[122:125], v91 offset:38912
	v_mfma_f32_32x32x16_bf16 v[34:49], v[126:129], v[134:137], v[34:49]
	v_mfma_f32_32x32x16_bf16 v[50:65], v[126:129], v[138:141], v[50:65]
	v_mfma_f32_32x32x16_bf16 v[2:17], v[130:133], v[134:137], v[2:17]
	v_mfma_f32_32x32x16_bf16 v[18:33], v[130:133], v[138:141], v[18:33]
	ds_read_b128 v[126:129], v88 offset:34816
	ds_read_b128 v[130:133], v88 offset:38912
	ds_read_b128 v[134:137], v92 offset:34816
	ds_read_b128 v[138:141], v92 offset:38912
	v_mfma_f32_32x32x16_bf16 v[34:49], v[142:145], v[150:153], v[34:49]
	v_mfma_f32_32x32x16_bf16 v[50:65], v[142:145], v[154:157], v[50:65]
	v_mfma_f32_32x32x16_bf16 v[2:17], v[146:149], v[150:153], v[2:17]
	v_mfma_f32_32x32x16_bf16 v[18:33], v[146:149], v[154:157], v[18:33]
	ds_read_b128 v[142:145], v89 offset:34816
	ds_read_b128 v[146:149], v89 offset:38912
	ds_read_b128 v[150:153], v93 offset:34816
	ds_read_b128 v[154:157], v93 offset:38912
	s_waitcnt lgkmcnt(0)
	s_barrier
	s_add_u32 m0, s14, 0x8680
	s_nop 0
	global_load_lds_dwordx4 v[68:69], off offset:384
	s_add_u32 m0, s14, 0x9680
	s_nop 0
	global_load_lds_dwordx4 v[72:73], off offset:384
	s_add_u32 m0, s14, 0xa680
	s_nop 0
	global_load_lds_dwordx4 v[76:77], off offset:384
	s_add_u32 m0, s14, 0xb680
	s_nop 0
	global_load_lds_dwordx4 v[80:81], off offset:384
	s_add_u32 m0, s14, 0xc680
	s_nop 0
	global_load_lds_dwordx4 v[70:71], off offset:384
	s_add_u32 m0, s14, 0xd680
	s_nop 0
	global_load_lds_dwordx4 v[74:75], off offset:384
	s_add_u32 m0, s14, 0xe680
	s_nop 0
	global_load_lds_dwordx4 v[78:79], off offset:384
	s_add_u32 m0, s14, 0xf680
	s_nop 0
	global_load_lds_dwordx4 v[82:83], off offset:384
	v_mfma_f32_32x32x16_bf16 v[34:49], v[94:97], v[102:105], v[34:49]
	v_mfma_f32_32x32x16_bf16 v[50:65], v[94:97], v[106:109], v[50:65]
	v_mfma_f32_32x32x16_bf16 v[2:17], v[98:101], v[102:105], v[2:17]
	v_mfma_f32_32x32x16_bf16 v[18:33], v[98:101], v[106:109], v[18:33]
	s_waitcnt vmcnt(8)
	s_barrier
	ds_read_b128 v[94:97], v86 offset:2048
	ds_read_b128 v[98:101], v86 offset:6144
	ds_read_b128 v[102:105], v90 offset:2048
	ds_read_b128 v[106:109], v90 offset:6144
	v_mfma_f32_32x32x16_bf16 v[34:49], v[110:113], v[118:121], v[34:49]
	v_mfma_f32_32x32x16_bf16 v[50:65], v[110:113], v[122:125], v[50:65]
	v_mfma_f32_32x32x16_bf16 v[2:17], v[114:117], v[118:121], v[2:17]
	v_mfma_f32_32x32x16_bf16 v[18:33], v[114:117], v[122:125], v[18:33]
	ds_read_b128 v[110:113], v87 offset:2048
	ds_read_b128 v[114:117], v87 offset:6144
	ds_read_b128 v[118:121], v91 offset:2048
	ds_read_b128 v[122:125], v91 offset:6144
	v_mfma_f32_32x32x16_bf16 v[34:49], v[126:129], v[134:137], v[34:49]
	v_mfma_f32_32x32x16_bf16 v[50:65], v[126:129], v[138:141], v[50:65]
	v_mfma_f32_32x32x16_bf16 v[2:17], v[130:133], v[134:137], v[2:17]
	v_mfma_f32_32x32x16_bf16 v[18:33], v[130:133], v[138:141], v[18:33]
	ds_read_b128 v[126:129], v88 offset:2048
	ds_read_b128 v[130:133], v88 offset:6144
	ds_read_b128 v[134:137], v92 offset:2048
	ds_read_b128 v[138:141], v92 offset:6144
	v_mfma_f32_32x32x16_bf16 v[34:49], v[142:145], v[150:153], v[34:49]
	v_mfma_f32_32x32x16_bf16 v[50:65], v[142:145], v[154:157], v[50:65]
	v_mfma_f32_32x32x16_bf16 v[2:17], v[146:149], v[150:153], v[2:17]
	v_mfma_f32_32x32x16_bf16 v[18:33], v[146:149], v[154:157], v[18:33]
	ds_read_b128 v[142:145], v89 offset:2048
	ds_read_b128 v[146:149], v89 offset:6144
	ds_read_b128 v[150:153], v93 offset:2048
	ds_read_b128 v[154:157], v93 offset:6144
	s_waitcnt lgkmcnt(0)
	s_barrier
	s_add_u32 m0, s14, 0x600
	s_nop 0
	global_load_lds_dwordx4 v[68:69], off offset:512
	s_add_u32 m0, s14, 0x1600
	s_nop 0
	global_load_lds_dwordx4 v[72:73], off offset:512
	s_add_u32 m0, s14, 0x2600
	s_nop 0
	global_load_lds_dwordx4 v[76:77], off offset:512
	s_add_u32 m0, s14, 0x3600
	s_nop 0
	global_load_lds_dwordx4 v[80:81], off offset:512
	s_add_u32 m0, s14, 0x4600
	s_nop 0
	global_load_lds_dwordx4 v[70:71], off offset:512
	s_add_u32 m0, s14, 0x5600
	s_nop 0
	global_load_lds_dwordx4 v[74:75], off offset:512
	s_add_u32 m0, s14, 0x6600
	s_nop 0
	global_load_lds_dwordx4 v[78:79], off offset:512
	s_add_u32 m0, s14, 0x7600
	s_nop 0
	global_load_lds_dwordx4 v[82:83], off offset:512
	v_mfma_f32_32x32x16_bf16 v[34:49], v[94:97], v[102:105], v[34:49]
	v_mfma_f32_32x32x16_bf16 v[50:65], v[94:97], v[106:109], v[50:65]
	v_mfma_f32_32x32x16_bf16 v[2:17], v[98:101], v[102:105], v[2:17]
	v_mfma_f32_32x32x16_bf16 v[18:33], v[98:101], v[106:109], v[18:33]
	s_waitcnt vmcnt(8)
	s_barrier
	ds_read_b128 v[94:97], v86 offset:34816
	ds_read_b128 v[98:101], v86 offset:38912
	ds_read_b128 v[102:105], v90 offset:34816
	ds_read_b128 v[106:109], v90 offset:38912
	v_mfma_f32_32x32x16_bf16 v[34:49], v[110:113], v[118:121], v[34:49]
	v_mfma_f32_32x32x16_bf16 v[50:65], v[110:113], v[122:125], v[50:65]
	v_mfma_f32_32x32x16_bf16 v[2:17], v[114:117], v[118:121], v[2:17]
	v_mfma_f32_32x32x16_bf16 v[18:33], v[114:117], v[122:125], v[18:33]
	ds_read_b128 v[110:113], v87 offset:34816
	ds_read_b128 v[114:117], v87 offset:38912
	ds_read_b128 v[118:121], v91 offset:34816
	ds_read_b128 v[122:125], v91 offset:38912
	v_mfma_f32_32x32x16_bf16 v[34:49], v[126:129], v[134:137], v[34:49]
	v_mfma_f32_32x32x16_bf16 v[50:65], v[126:129], v[138:141], v[50:65]
	v_mfma_f32_32x32x16_bf16 v[2:17], v[130:133], v[134:137], v[2:17]
	v_mfma_f32_32x32x16_bf16 v[18:33], v[130:133], v[138:141], v[18:33]
	ds_read_b128 v[126:129], v88 offset:34816
	ds_read_b128 v[130:133], v88 offset:38912
	ds_read_b128 v[134:137], v92 offset:34816
	ds_read_b128 v[138:141], v92 offset:38912
	v_mfma_f32_32x32x16_bf16 v[34:49], v[142:145], v[150:153], v[34:49]
	v_mfma_f32_32x32x16_bf16 v[50:65], v[142:145], v[154:157], v[50:65]
	v_mfma_f32_32x32x16_bf16 v[2:17], v[146:149], v[150:153], v[2:17]
	v_mfma_f32_32x32x16_bf16 v[18:33], v[146:149], v[154:157], v[18:33]
	ds_read_b128 v[142:145], v89 offset:34816
	ds_read_b128 v[146:149], v89 offset:38912
	ds_read_b128 v[150:153], v93 offset:34816
	ds_read_b128 v[154:157], v93 offset:38912
	s_waitcnt lgkmcnt(0)
	s_barrier
	s_add_u32 m0, s14, 0x8580
	s_nop 0
	global_load_lds_dwordx4 v[68:69], off offset:640
	s_add_u32 m0, s14, 0x9580
	s_nop 0
	global_load_lds_dwordx4 v[72:73], off offset:640
	s_add_u32 m0, s14, 0xa580
	s_nop 0
	global_load_lds_dwordx4 v[76:77], off offset:640
	s_add_u32 m0, s14, 0xb580
	s_nop 0
	global_load_lds_dwordx4 v[80:81], off offset:640
	s_add_u32 m0, s14, 0xc580
	s_nop 0
	global_load_lds_dwordx4 v[70:71], off offset:640
	s_add_u32 m0, s14, 0xd580
	s_nop 0
	global_load_lds_dwordx4 v[74:75], off offset:640
	s_add_u32 m0, s14, 0xe580
	s_nop 0
	global_load_lds_dwordx4 v[78:79], off offset:640
	s_add_u32 m0, s14, 0xf580
	s_nop 0
	global_load_lds_dwordx4 v[82:83], off offset:640
	v_mfma_f32_32x32x16_bf16 v[34:49], v[94:97], v[102:105], v[34:49]
	v_mfma_f32_32x32x16_bf16 v[50:65], v[94:97], v[106:109], v[50:65]
	v_mfma_f32_32x32x16_bf16 v[2:17], v[98:101], v[102:105], v[2:17]
	v_mfma_f32_32x32x16_bf16 v[18:33], v[98:101], v[106:109], v[18:33]
	s_waitcnt vmcnt(8)
	s_barrier
	ds_read_b128 v[94:97], v86 offset:2048
	ds_read_b128 v[98:101], v86 offset:6144
	ds_read_b128 v[102:105], v90 offset:2048
	ds_read_b128 v[106:109], v90 offset:6144
	v_mfma_f32_32x32x16_bf16 v[34:49], v[110:113], v[118:121], v[34:49]
	v_mfma_f32_32x32x16_bf16 v[50:65], v[110:113], v[122:125], v[50:65]
	v_mfma_f32_32x32x16_bf16 v[2:17], v[114:117], v[118:121], v[2:17]
	v_mfma_f32_32x32x16_bf16 v[18:33], v[114:117], v[122:125], v[18:33]
	ds_read_b128 v[110:113], v87 offset:2048
	ds_read_b128 v[114:117], v87 offset:6144
	ds_read_b128 v[118:121], v91 offset:2048
	ds_read_b128 v[122:125], v91 offset:6144
	v_mfma_f32_32x32x16_bf16 v[34:49], v[126:129], v[134:137], v[34:49]
	v_mfma_f32_32x32x16_bf16 v[50:65], v[126:129], v[138:141], v[50:65]
	v_mfma_f32_32x32x16_bf16 v[2:17], v[130:133], v[134:137], v[2:17]
	v_mfma_f32_32x32x16_bf16 v[18:33], v[130:133], v[138:141], v[18:33]
	ds_read_b128 v[126:129], v88 offset:2048
	ds_read_b128 v[130:133], v88 offset:6144
	ds_read_b128 v[134:137], v92 offset:2048
	ds_read_b128 v[138:141], v92 offset:6144
	v_mfma_f32_32x32x16_bf16 v[34:49], v[142:145], v[150:153], v[34:49]
	v_mfma_f32_32x32x16_bf16 v[50:65], v[142:145], v[154:157], v[50:65]
	v_mfma_f32_32x32x16_bf16 v[2:17], v[146:149], v[150:153], v[2:17]
	v_mfma_f32_32x32x16_bf16 v[18:33], v[146:149], v[154:157], v[18:33]
	ds_read_b128 v[142:145], v89 offset:2048
	ds_read_b128 v[146:149], v89 offset:6144
	ds_read_b128 v[150:153], v93 offset:2048
	ds_read_b128 v[154:157], v93 offset:6144
	s_waitcnt lgkmcnt(0)
	s_barrier
	s_add_u32 m0, s14, 0x500
	s_nop 0
	global_load_lds_dwordx4 v[68:69], off offset:768
	s_add_u32 m0, s14, 0x1500
	s_nop 0
	global_load_lds_dwordx4 v[72:73], off offset:768
	s_add_u32 m0, s14, 0x2500
	s_nop 0
	global_load_lds_dwordx4 v[76:77], off offset:768
	s_add_u32 m0, s14, 0x3500
	s_nop 0
	global_load_lds_dwordx4 v[80:81], off offset:768
	s_add_u32 m0, s14, 0x4500
	s_nop 0
	global_load_lds_dwordx4 v[70:71], off offset:768
	s_add_u32 m0, s14, 0x5500
	s_nop 0
	global_load_lds_dwordx4 v[74:75], off offset:768
	s_add_u32 m0, s14, 0x6500
	s_nop 0
	global_load_lds_dwordx4 v[78:79], off offset:768
	s_add_u32 m0, s14, 0x7500
	s_nop 0
	global_load_lds_dwordx4 v[82:83], off offset:768
	v_mfma_f32_32x32x16_bf16 v[34:49], v[94:97], v[102:105], v[34:49]
	v_mfma_f32_32x32x16_bf16 v[50:65], v[94:97], v[106:109], v[50:65]
	v_mfma_f32_32x32x16_bf16 v[2:17], v[98:101], v[102:105], v[2:17]
	v_mfma_f32_32x32x16_bf16 v[18:33], v[98:101], v[106:109], v[18:33]
	s_waitcnt vmcnt(8)
	s_barrier
	ds_read_b128 v[94:97], v86 offset:34816
	ds_read_b128 v[98:101], v86 offset:38912
	ds_read_b128 v[102:105], v90 offset:34816
	ds_read_b128 v[106:109], v90 offset:38912
	v_mfma_f32_32x32x16_bf16 v[34:49], v[110:113], v[118:121], v[34:49]
	v_mfma_f32_32x32x16_bf16 v[50:65], v[110:113], v[122:125], v[50:65]
	v_mfma_f32_32x32x16_bf16 v[2:17], v[114:117], v[118:121], v[2:17]
	v_mfma_f32_32x32x16_bf16 v[18:33], v[114:117], v[122:125], v[18:33]
	ds_read_b128 v[110:113], v87 offset:34816
	ds_read_b128 v[114:117], v87 offset:38912
	ds_read_b128 v[118:121], v91 offset:34816
	ds_read_b128 v[122:125], v91 offset:38912
	v_mfma_f32_32x32x16_bf16 v[34:49], v[126:129], v[134:137], v[34:49]
	v_mfma_f32_32x32x16_bf16 v[50:65], v[126:129], v[138:141], v[50:65]
	v_mfma_f32_32x32x16_bf16 v[2:17], v[130:133], v[134:137], v[2:17]
	v_mfma_f32_32x32x16_bf16 v[18:33], v[130:133], v[138:141], v[18:33]
	ds_read_b128 v[126:129], v88 offset:34816
	ds_read_b128 v[130:133], v88 offset:38912
	ds_read_b128 v[134:137], v92 offset:34816
	ds_read_b128 v[138:141], v92 offset:38912
	v_mfma_f32_32x32x16_bf16 v[34:49], v[142:145], v[150:153], v[34:49]
	v_mfma_f32_32x32x16_bf16 v[50:65], v[142:145], v[154:157], v[50:65]
	v_mfma_f32_32x32x16_bf16 v[2:17], v[146:149], v[150:153], v[2:17]
	v_mfma_f32_32x32x16_bf16 v[18:33], v[146:149], v[154:157], v[18:33]
	ds_read_b128 v[142:145], v89 offset:34816
	ds_read_b128 v[146:149], v89 offset:38912
	ds_read_b128 v[150:153], v93 offset:34816
	ds_read_b128 v[154:157], v93 offset:38912
	s_waitcnt lgkmcnt(0)
	s_barrier
	s_add_u32 m0, s14, 0x8480
	s_nop 0
	global_load_lds_dwordx4 v[68:69], off offset:896
	s_add_u32 m0, s14, 0x9480
	s_nop 0
	global_load_lds_dwordx4 v[72:73], off offset:896
	s_add_u32 m0, s14, 0xa480
	s_nop 0
	global_load_lds_dwordx4 v[76:77], off offset:896
	s_add_u32 m0, s14, 0xb480
	s_nop 0
	global_load_lds_dwordx4 v[80:81], off offset:896
	s_add_u32 m0, s14, 0xc480
	s_nop 0
	global_load_lds_dwordx4 v[70:71], off offset:896
	s_add_u32 m0, s14, 0xd480
	s_nop 0
	global_load_lds_dwordx4 v[74:75], off offset:896
	s_add_u32 m0, s14, 0xe480
	s_nop 0
	global_load_lds_dwordx4 v[78:79], off offset:896
	s_add_u32 m0, s14, 0xf480
	s_nop 0
	global_load_lds_dwordx4 v[82:83], off offset:896
	v_mfma_f32_32x32x16_bf16 v[34:49], v[94:97], v[102:105], v[34:49]
	v_mfma_f32_32x32x16_bf16 v[50:65], v[94:97], v[106:109], v[50:65]
	v_mfma_f32_32x32x16_bf16 v[2:17], v[98:101], v[102:105], v[2:17]
	v_mfma_f32_32x32x16_bf16 v[18:33], v[98:101], v[106:109], v[18:33]
	s_waitcnt vmcnt(8)
	s_barrier
	ds_read_b128 v[94:97], v86 offset:2048
	ds_read_b128 v[98:101], v86 offset:6144
	ds_read_b128 v[102:105], v90 offset:2048
	ds_read_b128 v[106:109], v90 offset:6144
	v_mfma_f32_32x32x16_bf16 v[34:49], v[110:113], v[118:121], v[34:49]
	v_mfma_f32_32x32x16_bf16 v[50:65], v[110:113], v[122:125], v[50:65]
	v_mfma_f32_32x32x16_bf16 v[2:17], v[114:117], v[118:121], v[2:17]
	v_mfma_f32_32x32x16_bf16 v[18:33], v[114:117], v[122:125], v[18:33]
	ds_read_b128 v[110:113], v87 offset:2048
	ds_read_b128 v[114:117], v87 offset:6144
	ds_read_b128 v[118:121], v91 offset:2048
	ds_read_b128 v[122:125], v91 offset:6144
	v_mfma_f32_32x32x16_bf16 v[34:49], v[126:129], v[134:137], v[34:49]
	v_mfma_f32_32x32x16_bf16 v[50:65], v[126:129], v[138:141], v[50:65]
	v_mfma_f32_32x32x16_bf16 v[2:17], v[130:133], v[134:137], v[2:17]
	v_mfma_f32_32x32x16_bf16 v[18:33], v[130:133], v[138:141], v[18:33]
	ds_read_b128 v[126:129], v88 offset:2048
	ds_read_b128 v[130:133], v88 offset:6144
	ds_read_b128 v[134:137], v92 offset:2048
	ds_read_b128 v[138:141], v92 offset:6144
	v_mfma_f32_32x32x16_bf16 v[34:49], v[142:145], v[150:153], v[34:49]
	v_mfma_f32_32x32x16_bf16 v[50:65], v[142:145], v[154:157], v[50:65]
	v_mfma_f32_32x32x16_bf16 v[2:17], v[146:149], v[150:153], v[2:17]
	v_mfma_f32_32x32x16_bf16 v[18:33], v[146:149], v[154:157], v[18:33]
	ds_read_b128 v[142:145], v89 offset:2048
	ds_read_b128 v[146:149], v89 offset:6144
	ds_read_b128 v[150:153], v93 offset:2048
	ds_read_b128 v[154:157], v93 offset:6144
	s_waitcnt lgkmcnt(0)
	s_barrier
	s_add_u32 m0, s14, 0x400
	s_nop 0
	global_load_lds_dwordx4 v[68:69], off offset:1024
	s_add_u32 m0, s14, 0x1400
	s_nop 0
	global_load_lds_dwordx4 v[72:73], off offset:1024
	s_add_u32 m0, s14, 0x2400
	s_nop 0
	global_load_lds_dwordx4 v[76:77], off offset:1024
	s_add_u32 m0, s14, 0x3400
	s_nop 0
	global_load_lds_dwordx4 v[80:81], off offset:1024
	s_add_u32 m0, s14, 0x4400
	s_nop 0
	global_load_lds_dwordx4 v[70:71], off offset:1024
	s_add_u32 m0, s14, 0x5400
	s_nop 0
	global_load_lds_dwordx4 v[74:75], off offset:1024
	s_add_u32 m0, s14, 0x6400
	s_nop 0
	global_load_lds_dwordx4 v[78:79], off offset:1024
	s_add_u32 m0, s14, 0x7400
	s_nop 0
	global_load_lds_dwordx4 v[82:83], off offset:1024
	v_mfma_f32_32x32x16_bf16 v[34:49], v[94:97], v[102:105], v[34:49]
	v_mfma_f32_32x32x16_bf16 v[50:65], v[94:97], v[106:109], v[50:65]
	v_mfma_f32_32x32x16_bf16 v[2:17], v[98:101], v[102:105], v[2:17]
	v_mfma_f32_32x32x16_bf16 v[18:33], v[98:101], v[106:109], v[18:33]
	s_waitcnt vmcnt(8)
	s_barrier
	ds_read_b128 v[94:97], v86 offset:34816
	ds_read_b128 v[98:101], v86 offset:38912
	ds_read_b128 v[102:105], v90 offset:34816
	ds_read_b128 v[106:109], v90 offset:38912
	v_mfma_f32_32x32x16_bf16 v[34:49], v[110:113], v[118:121], v[34:49]
	v_mfma_f32_32x32x16_bf16 v[50:65], v[110:113], v[122:125], v[50:65]
	v_mfma_f32_32x32x16_bf16 v[2:17], v[114:117], v[118:121], v[2:17]
	v_mfma_f32_32x32x16_bf16 v[18:33], v[114:117], v[122:125], v[18:33]
	ds_read_b128 v[110:113], v87 offset:34816
	ds_read_b128 v[114:117], v87 offset:38912
	ds_read_b128 v[118:121], v91 offset:34816
	ds_read_b128 v[122:125], v91 offset:38912
	v_mfma_f32_32x32x16_bf16 v[34:49], v[126:129], v[134:137], v[34:49]
	v_mfma_f32_32x32x16_bf16 v[50:65], v[126:129], v[138:141], v[50:65]
	v_mfma_f32_32x32x16_bf16 v[2:17], v[130:133], v[134:137], v[2:17]
	v_mfma_f32_32x32x16_bf16 v[18:33], v[130:133], v[138:141], v[18:33]
	ds_read_b128 v[126:129], v88 offset:34816
	ds_read_b128 v[130:133], v88 offset:38912
	ds_read_b128 v[134:137], v92 offset:34816
	ds_read_b128 v[138:141], v92 offset:38912
	v_mfma_f32_32x32x16_bf16 v[34:49], v[142:145], v[150:153], v[34:49]
	v_mfma_f32_32x32x16_bf16 v[50:65], v[142:145], v[154:157], v[50:65]
	v_mfma_f32_32x32x16_bf16 v[2:17], v[146:149], v[150:153], v[2:17]
	v_mfma_f32_32x32x16_bf16 v[18:33], v[146:149], v[154:157], v[18:33]
	ds_read_b128 v[142:145], v89 offset:34816
	ds_read_b128 v[146:149], v89 offset:38912
	ds_read_b128 v[150:153], v93 offset:34816
	ds_read_b128 v[154:157], v93 offset:38912
	s_waitcnt lgkmcnt(0)
	s_barrier
	s_add_u32 m0, s14, 0x8380
	s_nop 0
	global_load_lds_dwordx4 v[68:69], off offset:1152
	s_add_u32 m0, s14, 0x9380
	s_nop 0
	global_load_lds_dwordx4 v[72:73], off offset:1152
	s_add_u32 m0, s14, 0xa380
	s_nop 0
	global_load_lds_dwordx4 v[76:77], off offset:1152
	s_add_u32 m0, s14, 0xb380
	s_nop 0
	global_load_lds_dwordx4 v[80:81], off offset:1152
	s_add_u32 m0, s14, 0xc380
	s_nop 0
	global_load_lds_dwordx4 v[70:71], off offset:1152
	s_add_u32 m0, s14, 0xd380
	s_nop 0
	global_load_lds_dwordx4 v[74:75], off offset:1152
	s_add_u32 m0, s14, 0xe380
	s_nop 0
	global_load_lds_dwordx4 v[78:79], off offset:1152
	s_add_u32 m0, s14, 0xf380
	s_nop 0
	global_load_lds_dwordx4 v[82:83], off offset:1152
	v_mfma_f32_32x32x16_bf16 v[34:49], v[94:97], v[102:105], v[34:49]
	v_mfma_f32_32x32x16_bf16 v[50:65], v[94:97], v[106:109], v[50:65]
	v_mfma_f32_32x32x16_bf16 v[2:17], v[98:101], v[102:105], v[2:17]
	v_mfma_f32_32x32x16_bf16 v[18:33], v[98:101], v[106:109], v[18:33]
	s_waitcnt vmcnt(8)
	s_barrier
	ds_read_b128 v[94:97], v86 offset:2048
	ds_read_b128 v[98:101], v86 offset:6144
	ds_read_b128 v[102:105], v90 offset:2048
	ds_read_b128 v[106:109], v90 offset:6144
	v_mfma_f32_32x32x16_bf16 v[34:49], v[110:113], v[118:121], v[34:49]
	v_mfma_f32_32x32x16_bf16 v[50:65], v[110:113], v[122:125], v[50:65]
	v_mfma_f32_32x32x16_bf16 v[2:17], v[114:117], v[118:121], v[2:17]
	v_mfma_f32_32x32x16_bf16 v[18:33], v[114:117], v[122:125], v[18:33]
	ds_read_b128 v[110:113], v87 offset:2048
	ds_read_b128 v[114:117], v87 offset:6144
	ds_read_b128 v[118:121], v91 offset:2048
	ds_read_b128 v[122:125], v91 offset:6144
	v_mfma_f32_32x32x16_bf16 v[34:49], v[126:129], v[134:137], v[34:49]
	v_mfma_f32_32x32x16_bf16 v[50:65], v[126:129], v[138:141], v[50:65]
	v_mfma_f32_32x32x16_bf16 v[2:17], v[130:133], v[134:137], v[2:17]
	v_mfma_f32_32x32x16_bf16 v[18:33], v[130:133], v[138:141], v[18:33]
	ds_read_b128 v[126:129], v88 offset:2048
	ds_read_b128 v[130:133], v88 offset:6144
	ds_read_b128 v[134:137], v92 offset:2048
	ds_read_b128 v[138:141], v92 offset:6144
	v_mfma_f32_32x32x16_bf16 v[34:49], v[142:145], v[150:153], v[34:49]
	v_mfma_f32_32x32x16_bf16 v[50:65], v[142:145], v[154:157], v[50:65]
	v_mfma_f32_32x32x16_bf16 v[2:17], v[146:149], v[150:153], v[2:17]
	v_mfma_f32_32x32x16_bf16 v[18:33], v[146:149], v[154:157], v[18:33]
	ds_read_b128 v[142:145], v89 offset:2048
	ds_read_b128 v[146:149], v89 offset:6144
	ds_read_b128 v[150:153], v93 offset:2048
	ds_read_b128 v[154:157], v93 offset:6144
	s_waitcnt lgkmcnt(0)
	s_barrier
	s_add_u32 m0, s14, 0x300
	s_nop 0
	global_load_lds_dwordx4 v[68:69], off offset:1280
	s_add_u32 m0, s14, 0x1300
	s_nop 0
	global_load_lds_dwordx4 v[72:73], off offset:1280
	s_add_u32 m0, s14, 0x2300
	s_nop 0
	global_load_lds_dwordx4 v[76:77], off offset:1280
	s_add_u32 m0, s14, 0x3300
	s_nop 0
	global_load_lds_dwordx4 v[80:81], off offset:1280
	s_add_u32 m0, s14, 0x4300
	s_nop 0
	global_load_lds_dwordx4 v[70:71], off offset:1280
	s_add_u32 m0, s14, 0x5300
	s_nop 0
	global_load_lds_dwordx4 v[74:75], off offset:1280
	s_add_u32 m0, s14, 0x6300
	s_nop 0
	global_load_lds_dwordx4 v[78:79], off offset:1280
	s_add_u32 m0, s14, 0x7300
	s_nop 0
	global_load_lds_dwordx4 v[82:83], off offset:1280
	v_mfma_f32_32x32x16_bf16 v[34:49], v[94:97], v[102:105], v[34:49]
	v_mfma_f32_32x32x16_bf16 v[50:65], v[94:97], v[106:109], v[50:65]
	v_mfma_f32_32x32x16_bf16 v[2:17], v[98:101], v[102:105], v[2:17]
	v_mfma_f32_32x32x16_bf16 v[18:33], v[98:101], v[106:109], v[18:33]
	s_waitcnt vmcnt(8)
	s_barrier
	ds_read_b128 v[94:97], v86 offset:34816
	ds_read_b128 v[98:101], v86 offset:38912
	ds_read_b128 v[102:105], v90 offset:34816
	ds_read_b128 v[106:109], v90 offset:38912
	v_mfma_f32_32x32x16_bf16 v[34:49], v[110:113], v[118:121], v[34:49]
	v_mfma_f32_32x32x16_bf16 v[50:65], v[110:113], v[122:125], v[50:65]
	v_mfma_f32_32x32x16_bf16 v[2:17], v[114:117], v[118:121], v[2:17]
	v_mfma_f32_32x32x16_bf16 v[18:33], v[114:117], v[122:125], v[18:33]
	ds_read_b128 v[110:113], v87 offset:34816
	ds_read_b128 v[114:117], v87 offset:38912
	ds_read_b128 v[118:121], v91 offset:34816
	ds_read_b128 v[122:125], v91 offset:38912
	v_mfma_f32_32x32x16_bf16 v[34:49], v[126:129], v[134:137], v[34:49]
	v_mfma_f32_32x32x16_bf16 v[50:65], v[126:129], v[138:141], v[50:65]
	v_mfma_f32_32x32x16_bf16 v[2:17], v[130:133], v[134:137], v[2:17]
	v_mfma_f32_32x32x16_bf16 v[18:33], v[130:133], v[138:141], v[18:33]
	ds_read_b128 v[126:129], v88 offset:34816
	ds_read_b128 v[130:133], v88 offset:38912
	ds_read_b128 v[134:137], v92 offset:34816
	ds_read_b128 v[138:141], v92 offset:38912
	v_mfma_f32_32x32x16_bf16 v[34:49], v[142:145], v[150:153], v[34:49]
	v_mfma_f32_32x32x16_bf16 v[50:65], v[142:145], v[154:157], v[50:65]
	v_mfma_f32_32x32x16_bf16 v[2:17], v[146:149], v[150:153], v[2:17]
	v_mfma_f32_32x32x16_bf16 v[18:33], v[146:149], v[154:157], v[18:33]
	ds_read_b128 v[142:145], v89 offset:34816
	ds_read_b128 v[146:149], v89 offset:38912
	ds_read_b128 v[150:153], v93 offset:34816
	ds_read_b128 v[154:157], v93 offset:38912
	s_waitcnt lgkmcnt(0)
	s_barrier
	s_add_u32 m0, s14, 0x8280
	s_nop 0
	global_load_lds_dwordx4 v[68:69], off offset:1408
	s_add_u32 m0, s14, 0x9280
	s_nop 0
	global_load_lds_dwordx4 v[72:73], off offset:1408
	s_add_u32 m0, s14, 0xa280
	s_nop 0
	global_load_lds_dwordx4 v[76:77], off offset:1408
	s_add_u32 m0, s14, 0xb280
	s_nop 0
	global_load_lds_dwordx4 v[80:81], off offset:1408
	s_add_u32 m0, s14, 0xc280
	s_nop 0
	global_load_lds_dwordx4 v[70:71], off offset:1408
	s_add_u32 m0, s14, 0xd280
	s_nop 0
	global_load_lds_dwordx4 v[74:75], off offset:1408
	s_add_u32 m0, s14, 0xe280
	s_nop 0
	global_load_lds_dwordx4 v[78:79], off offset:1408
	s_add_u32 m0, s14, 0xf280
	s_nop 0
	global_load_lds_dwordx4 v[82:83], off offset:1408
	v_mfma_f32_32x32x16_bf16 v[34:49], v[94:97], v[102:105], v[34:49]
	v_mfma_f32_32x32x16_bf16 v[50:65], v[94:97], v[106:109], v[50:65]
	v_mfma_f32_32x32x16_bf16 v[2:17], v[98:101], v[102:105], v[2:17]
	v_mfma_f32_32x32x16_bf16 v[18:33], v[98:101], v[106:109], v[18:33]
	s_waitcnt vmcnt(8)
	s_barrier
	ds_read_b128 v[94:97], v86 offset:2048
	ds_read_b128 v[98:101], v86 offset:6144
	ds_read_b128 v[102:105], v90 offset:2048
	ds_read_b128 v[106:109], v90 offset:6144
	v_mfma_f32_32x32x16_bf16 v[34:49], v[110:113], v[118:121], v[34:49]
	v_mfma_f32_32x32x16_bf16 v[50:65], v[110:113], v[122:125], v[50:65]
	v_mfma_f32_32x32x16_bf16 v[2:17], v[114:117], v[118:121], v[2:17]
	v_mfma_f32_32x32x16_bf16 v[18:33], v[114:117], v[122:125], v[18:33]
	ds_read_b128 v[110:113], v87 offset:2048
	ds_read_b128 v[114:117], v87 offset:6144
	ds_read_b128 v[118:121], v91 offset:2048
	ds_read_b128 v[122:125], v91 offset:6144
	v_mfma_f32_32x32x16_bf16 v[34:49], v[126:129], v[134:137], v[34:49]
	v_mfma_f32_32x32x16_bf16 v[50:65], v[126:129], v[138:141], v[50:65]
	v_mfma_f32_32x32x16_bf16 v[2:17], v[130:133], v[134:137], v[2:17]
	v_mfma_f32_32x32x16_bf16 v[18:33], v[130:133], v[138:141], v[18:33]
	ds_read_b128 v[126:129], v88 offset:2048
	ds_read_b128 v[130:133], v88 offset:6144
	ds_read_b128 v[134:137], v92 offset:2048
	ds_read_b128 v[138:141], v92 offset:6144
	v_mfma_f32_32x32x16_bf16 v[34:49], v[142:145], v[150:153], v[34:49]
	v_mfma_f32_32x32x16_bf16 v[50:65], v[142:145], v[154:157], v[50:65]
	v_mfma_f32_32x32x16_bf16 v[2:17], v[146:149], v[150:153], v[2:17]
	v_mfma_f32_32x32x16_bf16 v[18:33], v[146:149], v[154:157], v[18:33]
	ds_read_b128 v[142:145], v89 offset:2048
	ds_read_b128 v[146:149], v89 offset:6144
	ds_read_b128 v[150:153], v93 offset:2048
	ds_read_b128 v[154:157], v93 offset:6144
	s_waitcnt lgkmcnt(0)
	s_barrier
	s_add_u32 m0, s14, 0x200
	s_nop 0
	global_load_lds_dwordx4 v[68:69], off offset:1536
	s_add_u32 m0, s14, 0x1200
	s_nop 0
	global_load_lds_dwordx4 v[72:73], off offset:1536
	s_add_u32 m0, s14, 0x2200
	s_nop 0
	global_load_lds_dwordx4 v[76:77], off offset:1536
	s_add_u32 m0, s14, 0x3200
	s_nop 0
	global_load_lds_dwordx4 v[80:81], off offset:1536
	s_add_u32 m0, s14, 0x4200
	s_nop 0
	global_load_lds_dwordx4 v[70:71], off offset:1536
	s_add_u32 m0, s14, 0x5200
	s_nop 0
	global_load_lds_dwordx4 v[74:75], off offset:1536
	s_add_u32 m0, s14, 0x6200
	s_nop 0
	global_load_lds_dwordx4 v[78:79], off offset:1536
	s_add_u32 m0, s14, 0x7200
	s_nop 0
	global_load_lds_dwordx4 v[82:83], off offset:1536
	v_mfma_f32_32x32x16_bf16 v[34:49], v[94:97], v[102:105], v[34:49]
	v_mfma_f32_32x32x16_bf16 v[50:65], v[94:97], v[106:109], v[50:65]
	v_mfma_f32_32x32x16_bf16 v[2:17], v[98:101], v[102:105], v[2:17]
	v_mfma_f32_32x32x16_bf16 v[18:33], v[98:101], v[106:109], v[18:33]
	s_waitcnt vmcnt(8)
	s_barrier
	ds_read_b128 v[94:97], v86 offset:34816
	ds_read_b128 v[98:101], v86 offset:38912
	ds_read_b128 v[102:105], v90 offset:34816
	ds_read_b128 v[106:109], v90 offset:38912
	v_mfma_f32_32x32x16_bf16 v[34:49], v[110:113], v[118:121], v[34:49]
	v_mfma_f32_32x32x16_bf16 v[50:65], v[110:113], v[122:125], v[50:65]
	v_mfma_f32_32x32x16_bf16 v[2:17], v[114:117], v[118:121], v[2:17]
	v_mfma_f32_32x32x16_bf16 v[18:33], v[114:117], v[122:125], v[18:33]
	ds_read_b128 v[110:113], v87 offset:34816
	ds_read_b128 v[114:117], v87 offset:38912
	ds_read_b128 v[118:121], v91 offset:34816
	ds_read_b128 v[122:125], v91 offset:38912
	v_mfma_f32_32x32x16_bf16 v[34:49], v[126:129], v[134:137], v[34:49]
	v_mfma_f32_32x32x16_bf16 v[50:65], v[126:129], v[138:141], v[50:65]
	v_mfma_f32_32x32x16_bf16 v[2:17], v[130:133], v[134:137], v[2:17]
	v_mfma_f32_32x32x16_bf16 v[18:33], v[130:133], v[138:141], v[18:33]
	ds_read_b128 v[126:129], v88 offset:34816
	ds_read_b128 v[130:133], v88 offset:38912
	ds_read_b128 v[134:137], v92 offset:34816
	ds_read_b128 v[138:141], v92 offset:38912
	v_mfma_f32_32x32x16_bf16 v[34:49], v[142:145], v[150:153], v[34:49]
	v_mfma_f32_32x32x16_bf16 v[50:65], v[142:145], v[154:157], v[50:65]
	v_mfma_f32_32x32x16_bf16 v[2:17], v[146:149], v[150:153], v[2:17]
	v_mfma_f32_32x32x16_bf16 v[18:33], v[146:149], v[154:157], v[18:33]
	ds_read_b128 v[142:145], v89 offset:34816
	ds_read_b128 v[146:149], v89 offset:38912
	ds_read_b128 v[150:153], v93 offset:34816
	ds_read_b128 v[154:157], v93 offset:38912
	s_waitcnt lgkmcnt(0)
	s_barrier
	s_add_u32 m0, s14, 0x8180
	s_nop 0
	global_load_lds_dwordx4 v[68:69], off offset:1664
	s_add_u32 m0, s14, 0x9180
	s_nop 0
	global_load_lds_dwordx4 v[72:73], off offset:1664
	s_add_u32 m0, s14, 0xa180
	s_nop 0
	global_load_lds_dwordx4 v[76:77], off offset:1664
	s_add_u32 m0, s14, 0xb180
	s_nop 0
	global_load_lds_dwordx4 v[80:81], off offset:1664
	s_add_u32 m0, s14, 0xc180
	s_nop 0
	global_load_lds_dwordx4 v[70:71], off offset:1664
	s_add_u32 m0, s14, 0xd180
	s_nop 0
	global_load_lds_dwordx4 v[74:75], off offset:1664
	s_add_u32 m0, s14, 0xe180
	s_nop 0
	global_load_lds_dwordx4 v[78:79], off offset:1664
	s_add_u32 m0, s14, 0xf180
	s_nop 0
	global_load_lds_dwordx4 v[82:83], off offset:1664
	v_mfma_f32_32x32x16_bf16 v[34:49], v[94:97], v[102:105], v[34:49]
	v_mfma_f32_32x32x16_bf16 v[50:65], v[94:97], v[106:109], v[50:65]
	v_mfma_f32_32x32x16_bf16 v[2:17], v[98:101], v[102:105], v[2:17]
	v_mfma_f32_32x32x16_bf16 v[18:33], v[98:101], v[106:109], v[18:33]
	s_waitcnt vmcnt(8)
	s_barrier
	ds_read_b128 v[94:97], v86 offset:2048
	ds_read_b128 v[98:101], v86 offset:6144
	ds_read_b128 v[102:105], v90 offset:2048
	ds_read_b128 v[106:109], v90 offset:6144
	v_mfma_f32_32x32x16_bf16 v[34:49], v[110:113], v[118:121], v[34:49]
	v_mfma_f32_32x32x16_bf16 v[50:65], v[110:113], v[122:125], v[50:65]
	v_mfma_f32_32x32x16_bf16 v[2:17], v[114:117], v[118:121], v[2:17]
	v_mfma_f32_32x32x16_bf16 v[18:33], v[114:117], v[122:125], v[18:33]
	ds_read_b128 v[110:113], v87 offset:2048
	ds_read_b128 v[114:117], v87 offset:6144
	ds_read_b128 v[118:121], v91 offset:2048
	ds_read_b128 v[122:125], v91 offset:6144
	v_mfma_f32_32x32x16_bf16 v[34:49], v[126:129], v[134:137], v[34:49]
	v_mfma_f32_32x32x16_bf16 v[50:65], v[126:129], v[138:141], v[50:65]
	v_mfma_f32_32x32x16_bf16 v[2:17], v[130:133], v[134:137], v[2:17]
	v_mfma_f32_32x32x16_bf16 v[18:33], v[130:133], v[138:141], v[18:33]
	ds_read_b128 v[126:129], v88 offset:2048
	ds_read_b128 v[130:133], v88 offset:6144
	ds_read_b128 v[134:137], v92 offset:2048
	ds_read_b128 v[138:141], v92 offset:6144
	v_mfma_f32_32x32x16_bf16 v[34:49], v[142:145], v[150:153], v[34:49]
	v_mfma_f32_32x32x16_bf16 v[50:65], v[142:145], v[154:157], v[50:65]
	v_mfma_f32_32x32x16_bf16 v[2:17], v[146:149], v[150:153], v[2:17]
	v_mfma_f32_32x32x16_bf16 v[18:33], v[146:149], v[154:157], v[18:33]
	ds_read_b128 v[142:145], v89 offset:2048
	ds_read_b128 v[146:149], v89 offset:6144
	ds_read_b128 v[150:153], v93 offset:2048
	ds_read_b128 v[154:157], v93 offset:6144
	s_waitcnt lgkmcnt(0)
	s_barrier
	s_add_u32 m0, s14, 0x100
	s_nop 0
	global_load_lds_dwordx4 v[68:69], off offset:1792
	s_add_u32 m0, s14, 0x1100
	s_nop 0
	global_load_lds_dwordx4 v[72:73], off offset:1792
	s_add_u32 m0, s14, 0x2100
	s_nop 0
	global_load_lds_dwordx4 v[76:77], off offset:1792
	s_add_u32 m0, s14, 0x3100
	s_nop 0
	global_load_lds_dwordx4 v[80:81], off offset:1792
	s_add_u32 m0, s14, 0x4100
	s_nop 0
	global_load_lds_dwordx4 v[70:71], off offset:1792
	s_add_u32 m0, s14, 0x5100
	s_nop 0
	global_load_lds_dwordx4 v[74:75], off offset:1792
	s_add_u32 m0, s14, 0x6100
	s_nop 0
	global_load_lds_dwordx4 v[78:79], off offset:1792
	s_add_u32 m0, s14, 0x7100
	s_nop 0
	global_load_lds_dwordx4 v[82:83], off offset:1792
	v_mfma_f32_32x32x16_bf16 v[34:49], v[94:97], v[102:105], v[34:49]
	v_mfma_f32_32x32x16_bf16 v[50:65], v[94:97], v[106:109], v[50:65]
	v_mfma_f32_32x32x16_bf16 v[2:17], v[98:101], v[102:105], v[2:17]
	v_mfma_f32_32x32x16_bf16 v[18:33], v[98:101], v[106:109], v[18:33]
	s_waitcnt vmcnt(8)
	s_barrier
	ds_read_b128 v[94:97], v86 offset:34816
	ds_read_b128 v[98:101], v86 offset:38912
	ds_read_b128 v[102:105], v90 offset:34816
	ds_read_b128 v[106:109], v90 offset:38912
	v_mfma_f32_32x32x16_bf16 v[34:49], v[110:113], v[118:121], v[34:49]
	v_mfma_f32_32x32x16_bf16 v[50:65], v[110:113], v[122:125], v[50:65]
	v_mfma_f32_32x32x16_bf16 v[2:17], v[114:117], v[118:121], v[2:17]
	v_mfma_f32_32x32x16_bf16 v[18:33], v[114:117], v[122:125], v[18:33]
	ds_read_b128 v[110:113], v87 offset:34816
	ds_read_b128 v[114:117], v87 offset:38912
	ds_read_b128 v[118:121], v91 offset:34816
	ds_read_b128 v[122:125], v91 offset:38912
	v_mfma_f32_32x32x16_bf16 v[34:49], v[126:129], v[134:137], v[34:49]
	v_mfma_f32_32x32x16_bf16 v[50:65], v[126:129], v[138:141], v[50:65]
	v_mfma_f32_32x32x16_bf16 v[2:17], v[130:133], v[134:137], v[2:17]
	v_mfma_f32_32x32x16_bf16 v[18:33], v[130:133], v[138:141], v[18:33]
	ds_read_b128 v[126:129], v88 offset:34816
	ds_read_b128 v[130:133], v88 offset:38912
	ds_read_b128 v[134:137], v92 offset:34816
	ds_read_b128 v[138:141], v92 offset:38912
	v_mfma_f32_32x32x16_bf16 v[34:49], v[142:145], v[150:153], v[34:49]
	v_mfma_f32_32x32x16_bf16 v[50:65], v[142:145], v[154:157], v[50:65]
	v_mfma_f32_32x32x16_bf16 v[2:17], v[146:149], v[150:153], v[2:17]
	v_mfma_f32_32x32x16_bf16 v[18:33], v[146:149], v[154:157], v[18:33]
	ds_read_b128 v[142:145], v89 offset:34816
	ds_read_b128 v[146:149], v89 offset:38912
	ds_read_b128 v[150:153], v93 offset:34816
	ds_read_b128 v[154:157], v93 offset:38912
	s_waitcnt lgkmcnt(0)
	s_barrier
	s_add_u32 m0, s14, 0x8080
	s_nop 0
	global_load_lds_dwordx4 v[68:69], off offset:1920
	s_add_u32 m0, s14, 0x9080
	s_nop 0
	global_load_lds_dwordx4 v[72:73], off offset:1920
	s_add_u32 m0, s14, 0xa080
	s_nop 0
	global_load_lds_dwordx4 v[76:77], off offset:1920
	s_add_u32 m0, s14, 0xb080
	s_nop 0
	global_load_lds_dwordx4 v[80:81], off offset:1920
	s_add_u32 m0, s14, 0xc080
	s_nop 0
	global_load_lds_dwordx4 v[70:71], off offset:1920
	s_add_u32 m0, s14, 0xd080
	s_nop 0
	global_load_lds_dwordx4 v[74:75], off offset:1920
	s_add_u32 m0, s14, 0xe080
	s_nop 0
	global_load_lds_dwordx4 v[78:79], off offset:1920
	s_add_u32 m0, s14, 0xf080
	s_nop 0
	global_load_lds_dwordx4 v[82:83], off offset:1920
	v_mfma_f32_32x32x16_bf16 v[34:49], v[94:97], v[102:105], v[34:49]
	v_mfma_f32_32x32x16_bf16 v[50:65], v[94:97], v[106:109], v[50:65]
	v_mfma_f32_32x32x16_bf16 v[2:17], v[98:101], v[102:105], v[2:17]
	v_mfma_f32_32x32x16_bf16 v[18:33], v[98:101], v[106:109], v[18:33]
	s_waitcnt vmcnt(8)
	s_barrier
	ds_read_b128 v[94:97], v86 offset:2048
	ds_read_b128 v[98:101], v86 offset:6144
	ds_read_b128 v[102:105], v90 offset:2048
	ds_read_b128 v[106:109], v90 offset:6144
	v_mfma_f32_32x32x16_bf16 v[34:49], v[110:113], v[118:121], v[34:49]
	v_mfma_f32_32x32x16_bf16 v[50:65], v[110:113], v[122:125], v[50:65]
	v_mfma_f32_32x32x16_bf16 v[2:17], v[114:117], v[118:121], v[2:17]
	v_mfma_f32_32x32x16_bf16 v[18:33], v[114:117], v[122:125], v[18:33]
	ds_read_b128 v[110:113], v87 offset:2048
	ds_read_b128 v[114:117], v87 offset:6144
	ds_read_b128 v[118:121], v91 offset:2048
	ds_read_b128 v[122:125], v91 offset:6144
	v_mfma_f32_32x32x16_bf16 v[34:49], v[126:129], v[134:137], v[34:49]
	v_mfma_f32_32x32x16_bf16 v[50:65], v[126:129], v[138:141], v[50:65]
	v_mfma_f32_32x32x16_bf16 v[2:17], v[130:133], v[134:137], v[2:17]
	v_mfma_f32_32x32x16_bf16 v[18:33], v[130:133], v[138:141], v[18:33]
	ds_read_b128 v[126:129], v88 offset:2048
	ds_read_b128 v[130:133], v88 offset:6144
	ds_read_b128 v[134:137], v92 offset:2048
	ds_read_b128 v[138:141], v92 offset:6144
	v_mfma_f32_32x32x16_bf16 v[34:49], v[142:145], v[150:153], v[34:49]
	v_mfma_f32_32x32x16_bf16 v[50:65], v[142:145], v[154:157], v[50:65]
	v_mfma_f32_32x32x16_bf16 v[2:17], v[146:149], v[150:153], v[2:17]
	v_mfma_f32_32x32x16_bf16 v[18:33], v[146:149], v[154:157], v[18:33]
	ds_read_b128 v[142:145], v89 offset:2048
	ds_read_b128 v[146:149], v89 offset:6144
	ds_read_b128 v[150:153], v93 offset:2048
	ds_read_b128 v[154:157], v93 offset:6144
	s_waitcnt lgkmcnt(0)
	v_mfma_f32_32x32x16_bf16 v[34:49], v[94:97], v[102:105], v[34:49]
	v_mfma_f32_32x32x16_bf16 v[50:65], v[94:97], v[106:109], v[50:65]
	v_mfma_f32_32x32x16_bf16 v[2:17], v[98:101], v[102:105], v[2:17]
	v_mfma_f32_32x32x16_bf16 v[18:33], v[98:101], v[106:109], v[18:33]
	s_waitcnt vmcnt(0)
	s_barrier
	ds_read_b128 v[94:97], v86 offset:34816
	ds_read_b128 v[98:101], v86 offset:38912
	ds_read_b128 v[102:105], v90 offset:34816
	ds_read_b128 v[106:109], v90 offset:38912
	v_mfma_f32_32x32x16_bf16 v[34:49], v[110:113], v[118:121], v[34:49]
	v_mfma_f32_32x32x16_bf16 v[50:65], v[110:113], v[122:125], v[50:65]
	v_mfma_f32_32x32x16_bf16 v[2:17], v[114:117], v[118:121], v[2:17]
	v_mfma_f32_32x32x16_bf16 v[18:33], v[114:117], v[122:125], v[18:33]
	ds_read_b128 v[110:113], v87 offset:34816
	ds_read_b128 v[114:117], v87 offset:38912
	ds_read_b128 v[118:121], v91 offset:34816
	ds_read_b128 v[122:125], v91 offset:38912
	v_mfma_f32_32x32x16_bf16 v[34:49], v[126:129], v[134:137], v[34:49]
	v_mfma_f32_32x32x16_bf16 v[50:65], v[126:129], v[138:141], v[50:65]
	v_mfma_f32_32x32x16_bf16 v[2:17], v[130:133], v[134:137], v[2:17]
	v_mfma_f32_32x32x16_bf16 v[18:33], v[130:133], v[138:141], v[18:33]
	ds_read_b128 v[126:129], v88 offset:34816
	ds_read_b128 v[130:133], v88 offset:38912
	ds_read_b128 v[134:137], v92 offset:34816
	ds_read_b128 v[138:141], v92 offset:38912
	v_mfma_f32_32x32x16_bf16 v[34:49], v[142:145], v[150:153], v[34:49]
	v_mfma_f32_32x32x16_bf16 v[50:65], v[142:145], v[154:157], v[50:65]
	v_mfma_f32_32x32x16_bf16 v[2:17], v[146:149], v[150:153], v[2:17]
	v_mfma_f32_32x32x16_bf16 v[18:33], v[146:149], v[154:157], v[18:33]
	ds_read_b128 v[142:145], v89 offset:34816
	ds_read_b128 v[146:149], v89 offset:38912
	ds_read_b128 v[150:153], v93 offset:34816
	ds_read_b128 v[154:157], v93 offset:38912
	s_waitcnt lgkmcnt(0)
	v_mfma_f32_32x32x16_bf16 v[34:49], v[94:97], v[102:105], v[34:49]
	v_mfma_f32_32x32x16_bf16 v[50:65], v[94:97], v[106:109], v[50:65]
	v_mfma_f32_32x32x16_bf16 v[2:17], v[98:101], v[102:105], v[2:17]
	v_mfma_f32_32x32x16_bf16 v[18:33], v[98:101], v[106:109], v[18:33]
	v_mfma_f32_32x32x16_bf16 v[34:49], v[110:113], v[118:121], v[34:49]
	v_mfma_f32_32x32x16_bf16 v[50:65], v[110:113], v[122:125], v[50:65]
	v_mfma_f32_32x32x16_bf16 v[2:17], v[114:117], v[118:121], v[2:17]
	v_mfma_f32_32x32x16_bf16 v[18:33], v[114:117], v[122:125], v[18:33]
	v_mfma_f32_32x32x16_bf16 v[34:49], v[126:129], v[134:137], v[34:49]
	v_mfma_f32_32x32x16_bf16 v[50:65], v[126:129], v[138:141], v[50:65]
	v_mfma_f32_32x32x16_bf16 v[2:17], v[130:133], v[134:137], v[2:17]
	v_mfma_f32_32x32x16_bf16 v[18:33], v[130:133], v[138:141], v[18:33]
	v_mfma_f32_32x32x16_bf16 v[34:49], v[142:145], v[150:153], v[34:49]
	v_mfma_f32_32x32x16_bf16 v[50:65], v[142:145], v[154:157], v[50:65]
	v_mfma_f32_32x32x16_bf16 v[2:17], v[146:149], v[150:153], v[2:17]
	v_mfma_f32_32x32x16_bf16 v[18:33], v[146:149], v[154:157], v[18:33]
	v_mov_b32_e32 v66, v178
	s_waitcnt lgkmcnt(0)
	s_barrier
	v_lshrrev_b32_e32 v0, 1, v66
	v_and_b32_e32 v0, 0xfffffc0, v0
	v_lshrrev_b32_e32 v67, 3, v66
	v_and_or_b32 v0, v67, 4, v0
	v_and_b32_e32 v67, 0x5f, v66
	v_mul_lo_u32 v0, v0, s83
	v_lshl_add_u32 v0, v67, 2, v0
	s_nop 11
	ds_write2_b32 v0, v34, v50 offset1:32
	ds_write2_b32 v0, v35, v51 offset0:132 offset1:164
	v_add_u32_e32 v34, 0x400, v0
	ds_write2_b32 v34, v36, v52 offset0:8 offset1:40
	ds_write2_b32 v34, v37, v53 offset0:140 offset1:172
	v_add_u32_e32 v34, 0x1000, v0
	ds_write2_b32 v34, v38, v54 offset0:32 offset1:64
	ds_write2_b32 v34, v39, v55 offset0:164 offset1:196
	v_add_u32_e32 v34, 0x1400, v0
	ds_write2_b32 v34, v40, v56 offset0:40 offset1:72
	ds_write2_b32 v34, v41, v57 offset0:172 offset1:204
	v_add_u32_e32 v34, 0x2000, v0
	ds_write2_b32 v34, v42, v58 offset0:64 offset1:96
	ds_write2_b32 v34, v43, v59 offset0:196 offset1:228
	v_add_u32_e32 v34, 0x2400, v0
	ds_write2_b32 v34, v44, v60 offset0:72 offset1:104
	ds_write2_b32 v34, v45, v61 offset0:204 offset1:236
	v_add_u32_e32 v34, 0x3000, v0
	ds_write2_b32 v34, v46, v62 offset0:96 offset1:128
	v_add_u32_e32 v34, 0x3200, v0
	ds_write2_b32 v34, v47, v63 offset0:100 offset1:132
	v_add_u32_e32 v34, 0x3400, v0
	ds_write2_b32 v34, v48, v64 offset0:104 offset1:136
	v_add_u32_e32 v34, 0x3600, v0
	ds_write2_b32 v34, v49, v65 offset0:108 offset1:140
	v_add_u32_e32 v34, 0x4000, v0
	s_nop 11
	ds_write2_b32 v34, v2, v18 offset0:128 offset1:160
	v_add_u32_e32 v2, 0x4400, v0
	ds_write2_b32 v2, v3, v19 offset0:4 offset1:36
	ds_write2_b32 v2, v4, v20 offset0:136 offset1:168
	v_add_u32_e32 v2, 0x4800, v0
	ds_write2_b32 v2, v5, v21 offset0:12 offset1:44
	v_add_u32_e32 v2, 0x5000, v0
	ds_write2_b32 v2, v6, v22 offset0:160 offset1:192
	v_add_u32_e32 v2, 0x5400, v0
	ds_write2_b32 v2, v7, v23 offset0:36 offset1:68
	ds_write2_b32 v2, v8, v24 offset0:168 offset1:200
	v_add_u32_e32 v2, 0x5800, v0
	ds_write2_b32 v2, v9, v25 offset0:44 offset1:76
	v_add_u32_e32 v2, 0x6000, v0
	ds_write2_b32 v2, v10, v26 offset0:192 offset1:224
	v_add_u32_e32 v2, 0x6400, v0
	ds_write2_b32 v2, v11, v27 offset0:68 offset1:100
	ds_write2_b32 v2, v12, v28 offset0:200 offset1:232
	v_add_u32_e32 v2, 0x6800, v0
	ds_write2_b32 v2, v13, v29 offset0:76 offset1:108
	v_add_u32_e32 v2, 0x7200, v0
	ds_write2_b32 v2, v14, v30 offset0:96 offset1:128
	v_add_u32_e32 v2, 0x7400, v0
	ds_write2_b32 v2, v15, v31 offset0:100 offset1:132
	v_add_u32_e32 v2, 0x7600, v0
	v_add_u32_e32 v0, 0x7800, v0
	ds_write2_b32 v0, v17, v33 offset0:108 offset1:140
	v_lshlrev_b32_e32 v0, 3, v66
	v_and_b32_e32 v0, 0x78, v0
	ds_write2_b32 v2, v16, v32 offset0:104 offset1:136
	v_lshlrev_b32_e32 v2, 2, v0
	v_or_b32_e32 v0, s0, v0
	v_lshlrev_b32_e32 v0, 1, v0
	s_waitcnt lgkmcnt(0)
	s_barrier
	v_lshl_add_u64 v[4:5], s[78:79], 0, v[0:1]

.LBB0_909:
	s_lshl_b32 s0, s13, 3
	s_and_b32 s0, s0, 56
	s_bfe_u32 s1, s13, 0x30003
	s_or_b32 s20, s0, s1
	s_lshl_b32 s0, s13, 1
	s_and_b32 s0, s0, 0xffffff80
	s_lshl_b32 s1, s20, 18
	v_readlane_b32 s22, v251, 37
	s_waitcnt vmcnt(12)
	v_mov_b32_e32 v36, v178
	v_readlane_b32 s23, v251, 38
	s_add_u32 s22, s22, s1
	s_addc_u32 s23, s23, 0
	v_ashrrev_i32_e32 v34, 3, v36
	s_ashr_i32 s1, s0, 31
	v_lshlrev_b32_e32 v0, 3, v36
	v_ashrrev_i32_e32 v35, 31, v34
	s_lshl_b64 s[24:25], s[0:1], 11
	v_and_b32_e32 v37, 56, v0
	s_waitcnt vmcnt(5)
	v_lshlrev_b64 v[2:3], 11, v[34:35]
	s_add_u32 s24, s68, s24
	v_lshl_add_u64 v[4:5], s[22:23], 0, v[2:3]
	v_lshlrev_b32_e32 v0, 1, v37
	s_addc_u32 s25, s69, s25
	v_lshl_add_u64 v[68:69], v[4:5], 0, v[0:1]
	v_lshl_add_u64 v[2:3], s[24:25], 0, v[2:3]
	v_lshl_add_u64 v[70:71], v[2:3], 0, v[0:1]
	v_and_b32_e32 v0, 7, v36
	v_bfe_u32 v66, v36, 4, 3
	v_xor_b32_e32 v66, v66, v0
	v_sub_u32_e32 v66, v66, v0
	v_lshlrev_b32_e32 v66, 4, v66
	v_ashrrev_i32_e32 v67, 31, v66
	v_lshl_add_u64 v[68:69], v[68:69], 0, v[66:67]
	v_lshl_add_u64 v[70:71], v[70:71], 0, v[66:67]
	v_add_co_u32_e32 v72, vcc, s73, v68
	s_nop 1
	v_addc_co_u32_e32 v73, vcc, 0, v69, vcc
	v_add_co_u32_e32 v74, vcc, s73, v70
	s_nop 1
	v_addc_co_u32_e32 v75, vcc, 0, v71, vcc
	v_add_co_u32_e32 v76, vcc, s52, v68
	s_nop 1
	v_addc_co_u32_e32 v77, vcc, 0, v69, vcc
	v_add_co_u32_e32 v78, vcc, s52, v70
	s_nop 1
	v_addc_co_u32_e32 v79, vcc, 0, v71, vcc
	v_add_co_u32_e32 v80, vcc, s53, v68
	s_nop 1
	v_addc_co_u32_e32 v81, vcc, 0, v69, vcc
	v_add_co_u32_e32 v82, vcc, s53, v70
	s_nop 1
	v_addc_co_u32_e32 v83, vcc, 0, v71, vcc
	v_and_b32_e32 v0, 31, v36
	v_bfe_u32 v66, v36, 5, 1
	v_bfe_u32 v67, v36, 1, 3
	v_xor_b32_e32 v66, v66, v67
	v_lshlrev_b32_e32 v66, 4, v66
	v_lshl_add_u32 v66, v0, 7, v66
	v_bfe_u32 v67, v36, 7, 1
	v_lshl_add_u32 v86, v67, 13, v66
	v_bfe_u32 v67, v36, 6, 1
	v_lshl_add_u32 v90, v67, 13, v66
	v_add_u32_e32 v90, 0x4000, v90
	v_xor_b32_e32 v87, 32, v86
	v_xor_b32_e32 v91, 32, v90
	v_xor_b32_e32 v88, 64, v86
	v_xor_b32_e32 v92, 64, v90
	v_xor_b32_e32 v89, 96, v86
	v_xor_b32_e32 v93, 96, v90
	v_lshrrev_b32_e32 v66, 6, v36
	v_lshlrev_b32_e32 v66, 10, v66
	s_nop 1
	v_readfirstlane_b32 s14, v66
	s_mov_b32 s21, 0
	s_lshl_b32 s20, s20, 7
	s_add_u32 m0, s14, 0x800
	s_nop 0
	global_load_lds_dwordx4 v[68:69], off
	s_add_u32 m0, s14, 0x1800
	s_nop 0
	global_load_lds_dwordx4 v[72:73], off
	s_add_u32 m0, s14, 0x2800
	s_nop 0
	global_load_lds_dwordx4 v[76:77], off
	s_add_u32 m0, s14, 0x3800
	s_nop 0
	global_load_lds_dwordx4 v[80:81], off
	s_add_u32 m0, s14, 0x4800
	s_nop 0
	global_load_lds_dwordx4 v[70:71], off
	s_add_u32 m0, s14, 0x5800
	s_nop 0
	global_load_lds_dwordx4 v[74:75], off
	s_add_u32 m0, s14, 0x6800
	s_nop 0
	global_load_lds_dwordx4 v[78:79], off
	s_add_u32 m0, s14, 0x7800
	s_nop 0
	global_load_lds_dwordx4 v[82:83], off
	s_add_u32 m0, s14, 0x8780
	s_nop 0
	global_load_lds_dwordx4 v[68:69], off offset:128
	s_add_u32 m0, s14, 0x9780
	s_nop 0
	global_load_lds_dwordx4 v[72:73], off offset:128
	s_add_u32 m0, s14, 0xa780
	s_nop 0
	global_load_lds_dwordx4 v[76:77], off offset:128
	s_add_u32 m0, s14, 0xb780
	s_nop 0
	global_load_lds_dwordx4 v[80:81], off offset:128
	s_add_u32 m0, s14, 0xc780
	s_nop 0
	global_load_lds_dwordx4 v[70:71], off offset:128
	s_add_u32 m0, s14, 0xd780
	s_nop 0
	global_load_lds_dwordx4 v[74:75], off offset:128
	s_add_u32 m0, s14, 0xe780
	s_nop 0
	global_load_lds_dwordx4 v[78:79], off offset:128
	s_add_u32 m0, s14, 0xf780
	s_nop 0
	global_load_lds_dwordx4 v[82:83], off offset:128
	s_waitcnt vmcnt(8)
	s_barrier
	ds_read_b128 v[94:97], v86 offset:2048
	ds_read_b128 v[98:101], v86 offset:6144
	ds_read_b128 v[102:105], v90 offset:2048
	ds_read_b128 v[106:109], v90 offset:6144
	ds_read_b128 v[110:113], v87 offset:2048
	ds_read_b128 v[114:117], v87 offset:6144
	ds_read_b128 v[118:121], v91 offset:2048
	ds_read_b128 v[122:125], v91 offset:6144
	ds_read_b128 v[126:129], v88 offset:2048
	ds_read_b128 v[130:133], v88 offset:6144
	ds_read_b128 v[134:137], v92 offset:2048
	ds_read_b128 v[138:141], v92 offset:6144
	ds_read_b128 v[142:145], v89 offset:2048
	ds_read_b128 v[146:149], v89 offset:6144
	ds_read_b128 v[150:153], v93 offset:2048
	ds_read_b128 v[154:157], v93 offset:6144
	s_waitcnt lgkmcnt(0)
	s_barrier
	s_add_u32 m0, s14, 0x700
	s_nop 0
	global_load_lds_dwordx4 v[68:69], off offset:256
	s_add_u32 m0, s14, 0x1700
	s_nop 0
	global_load_lds_dwordx4 v[72:73], off offset:256
	s_add_u32 m0, s14, 0x2700
	s_nop 0
	global_load_lds_dwordx4 v[76:77], off offset:256
	s_add_u32 m0, s14, 0x3700
	s_nop 0
	global_load_lds_dwordx4 v[80:81], off offset:256
	s_add_u32 m0, s14, 0x4700
	s_nop 0
	global_load_lds_dwordx4 v[70:71], off offset:256
	s_add_u32 m0, s14, 0x5700
	s_nop 0
	global_load_lds_dwordx4 v[74:75], off offset:256
	s_add_u32 m0, s14, 0x6700
	s_nop 0
	global_load_lds_dwordx4 v[78:79], off offset:256
	s_add_u32 m0, s14, 0x7700
	s_nop 0
	global_load_lds_dwordx4 v[82:83], off offset:256
	v_mfma_f32_32x32x16_bf16 v[34:49], v[94:97], v[102:105], 0
	v_mfma_f32_32x32x16_bf16 v[50:65], v[94:97], v[106:109], 0
	v_mfma_f32_32x32x16_bf16 v[2:17], v[98:101], v[102:105], 0
	v_mfma_f32_32x32x16_bf16 v[18:33], v[98:101], v[106:109], 0
	s_waitcnt vmcnt(8)
	s_barrier
	ds_read_b128 v[94:97], v86 offset:34816
	ds_read_b128 v[98:101], v86 offset:38912
	ds_read_b128 v[102:105], v90 offset:34816
	ds_read_b128 v[106:109], v90 offset:38912
	v_mfma_f32_32x32x16_bf16 v[34:49], v[110:113], v[118:121], v[34:49]
	v_mfma_f32_32x32x16_bf16 v[50:65], v[110:113], v[122:125], v[50:65]
	v_mfma_f32_32x32x16_bf16 v[2:17], v[114:117], v[118:121], v[2:17]
	v_mfma_f32_32x32x16_bf16 v[18:33], v[114:117], v[122:125], v[18:33]
	ds_read_b128 v[110:113], v87 offset:34816
	ds_read_b128 v[114:117], v87 offset:38912
	ds_read_b128 v[118:121], v91 offset:34816
	ds_read_b128 v[122:125], v91 offset:38912
	v_mfma_f32_32x32x16_bf16 v[34:49], v[126:129], v[134:137], v[34:49]
	v_mfma_f32_32x32x16_bf16 v[50:65], v[126:129], v[138:141], v[50:65]
	v_mfma_f32_32x32x16_bf16 v[2:17], v[130:133], v[134:137], v[2:17]
	v_mfma_f32_32x32x16_bf16 v[18:33], v[130:133], v[138:141], v[18:33]
	ds_read_b128 v[126:129], v88 offset:34816
	ds_read_b128 v[130:133], v88 offset:38912
	ds_read_b128 v[134:137], v92 offset:34816
	ds_read_b128 v[138:141], v92 offset:38912
	v_mfma_f32_32x32x16_bf16 v[34:49], v[142:145], v[150:153], v[34:49]
	v_mfma_f32_32x32x16_bf16 v[50:65], v[142:145], v[154:157], v[50:65]
	v_mfma_f32_32x32x16_bf16 v[2:17], v[146:149], v[150:153], v[2:17]
	v_mfma_f32_32x32x16_bf16 v[18:33], v[146:149], v[154:157], v[18:33]
	ds_read_b128 v[142:145], v89 offset:34816
	ds_read_b128 v[146:149], v89 offset:38912
	ds_read_b128 v[150:153], v93 offset:34816
	ds_read_b128 v[154:157], v93 offset:38912
	s_waitcnt lgkmcnt(0)
	s_barrier
	s_add_u32 m0, s14, 0x8680
	s_nop 0
	global_load_lds_dwordx4 v[68:69], off offset:384
	s_add_u32 m0, s14, 0x9680
	s_nop 0
	global_load_lds_dwordx4 v[72:73], off offset:384
	s_add_u32 m0, s14, 0xa680
	s_nop 0
	global_load_lds_dwordx4 v[76:77], off offset:384
	s_add_u32 m0, s14, 0xb680
	s_nop 0
	global_load_lds_dwordx4 v[80:81], off offset:384
	s_add_u32 m0, s14, 0xc680
	s_nop 0
	global_load_lds_dwordx4 v[70:71], off offset:384
	s_add_u32 m0, s14, 0xd680
	s_nop 0
	global_load_lds_dwordx4 v[74:75], off offset:384
	s_add_u32 m0, s14, 0xe680
	s_nop 0
	global_load_lds_dwordx4 v[78:79], off offset:384
	s_add_u32 m0, s14, 0xf680
	s_nop 0
	global_load_lds_dwordx4 v[82:83], off offset:384
	v_mfma_f32_32x32x16_bf16 v[34:49], v[94:97], v[102:105], v[34:49]
	v_mfma_f32_32x32x16_bf16 v[50:65], v[94:97], v[106:109], v[50:65]
	v_mfma_f32_32x32x16_bf16 v[2:17], v[98:101], v[102:105], v[2:17]
	v_mfma_f32_32x32x16_bf16 v[18:33], v[98:101], v[106:109], v[18:33]
	s_waitcnt vmcnt(8)
	s_barrier
	ds_read_b128 v[94:97], v86 offset:2048
	ds_read_b128 v[98:101], v86 offset:6144
	ds_read_b128 v[102:105], v90 offset:2048
	ds_read_b128 v[106:109], v90 offset:6144
	v_mfma_f32_32x32x16_bf16 v[34:49], v[110:113], v[118:121], v[34:49]
	v_mfma_f32_32x32x16_bf16 v[50:65], v[110:113], v[122:125], v[50:65]
	v_mfma_f32_32x32x16_bf16 v[2:17], v[114:117], v[118:121], v[2:17]
	v_mfma_f32_32x32x16_bf16 v[18:33], v[114:117], v[122:125], v[18:33]
	ds_read_b128 v[110:113], v87 offset:2048
	ds_read_b128 v[114:117], v87 offset:6144
	ds_read_b128 v[118:121], v91 offset:2048
	ds_read_b128 v[122:125], v91 offset:6144
	v_mfma_f32_32x32x16_bf16 v[34:49], v[126:129], v[134:137], v[34:49]
	v_mfma_f32_32x32x16_bf16 v[50:65], v[126:129], v[138:141], v[50:65]
	v_mfma_f32_32x32x16_bf16 v[2:17], v[130:133], v[134:137], v[2:17]
	v_mfma_f32_32x32x16_bf16 v[18:33], v[130:133], v[138:141], v[18:33]
	ds_read_b128 v[126:129], v88 offset:2048
	ds_read_b128 v[130:133], v88 offset:6144
	ds_read_b128 v[134:137], v92 offset:2048
	ds_read_b128 v[138:141], v92 offset:6144
	v_mfma_f32_32x32x16_bf16 v[34:49], v[142:145], v[150:153], v[34:49]
	v_mfma_f32_32x32x16_bf16 v[50:65], v[142:145], v[154:157], v[50:65]
	v_mfma_f32_32x32x16_bf16 v[2:17], v[146:149], v[150:153], v[2:17]
	v_mfma_f32_32x32x16_bf16 v[18:33], v[146:149], v[154:157], v[18:33]
	ds_read_b128 v[142:145], v89 offset:2048
	ds_read_b128 v[146:149], v89 offset:6144
	ds_read_b128 v[150:153], v93 offset:2048
	ds_read_b128 v[154:157], v93 offset:6144
	s_waitcnt lgkmcnt(0)
	s_barrier
	s_add_u32 m0, s14, 0x600
	s_nop 0
	global_load_lds_dwordx4 v[68:69], off offset:512
	s_add_u32 m0, s14, 0x1600
	s_nop 0
	global_load_lds_dwordx4 v[72:73], off offset:512
	s_add_u32 m0, s14, 0x2600
	s_nop 0
	global_load_lds_dwordx4 v[76:77], off offset:512
	s_add_u32 m0, s14, 0x3600
	s_nop 0
	global_load_lds_dwordx4 v[80:81], off offset:512
	s_add_u32 m0, s14, 0x4600
	s_nop 0
	global_load_lds_dwordx4 v[70:71], off offset:512
	s_add_u32 m0, s14, 0x5600
	s_nop 0
	global_load_lds_dwordx4 v[74:75], off offset:512
	s_add_u32 m0, s14, 0x6600
	s_nop 0
	global_load_lds_dwordx4 v[78:79], off offset:512
	s_add_u32 m0, s14, 0x7600
	s_nop 0
	global_load_lds_dwordx4 v[82:83], off offset:512
	v_mfma_f32_32x32x16_bf16 v[34:49], v[94:97], v[102:105], v[34:49]
	v_mfma_f32_32x32x16_bf16 v[50:65], v[94:97], v[106:109], v[50:65]
	v_mfma_f32_32x32x16_bf16 v[2:17], v[98:101], v[102:105], v[2:17]
	v_mfma_f32_32x32x16_bf16 v[18:33], v[98:101], v[106:109], v[18:33]
	s_waitcnt vmcnt(8)
	s_barrier
	ds_read_b128 v[94:97], v86 offset:34816
	ds_read_b128 v[98:101], v86 offset:38912
	ds_read_b128 v[102:105], v90 offset:34816
	ds_read_b128 v[106:109], v90 offset:38912
	v_mfma_f32_32x32x16_bf16 v[34:49], v[110:113], v[118:121], v[34:49]
	v_mfma_f32_32x32x16_bf16 v[50:65], v[110:113], v[122:125], v[50:65]
	v_mfma_f32_32x32x16_bf16 v[2:17], v[114:117], v[118:121], v[2:17]
	v_mfma_f32_32x32x16_bf16 v[18:33], v[114:117], v[122:125], v[18:33]
	ds_read_b128 v[110:113], v87 offset:34816
	ds_read_b128 v[114:117], v87 offset:38912
	ds_read_b128 v[118:121], v91 offset:34816
	ds_read_b128 v[122:125], v91 offset:38912
	v_mfma_f32_32x32x16_bf16 v[34:49], v[126:129], v[134:137], v[34:49]
	v_mfma_f32_32x32x16_bf16 v[50:65], v[126:129], v[138:141], v[50:65]
	v_mfma_f32_32x32x16_bf16 v[2:17], v[130:133], v[134:137], v[2:17]
	v_mfma_f32_32x32x16_bf16 v[18:33], v[130:133], v[138:141], v[18:33]
	ds_read_b128 v[126:129], v88 offset:34816
	ds_read_b128 v[130:133], v88 offset:38912
	ds_read_b128 v[134:137], v92 offset:34816
	ds_read_b128 v[138:141], v92 offset:38912
	v_mfma_f32_32x32x16_bf16 v[34:49], v[142:145], v[150:153], v[34:49]
	v_mfma_f32_32x32x16_bf16 v[50:65], v[142:145], v[154:157], v[50:65]
	v_mfma_f32_32x32x16_bf16 v[2:17], v[146:149], v[150:153], v[2:17]
	v_mfma_f32_32x32x16_bf16 v[18:33], v[146:149], v[154:157], v[18:33]
	ds_read_b128 v[142:145], v89 offset:34816
	ds_read_b128 v[146:149], v89 offset:38912
	ds_read_b128 v[150:153], v93 offset:34816
	ds_read_b128 v[154:157], v93 offset:38912
	s_waitcnt lgkmcnt(0)
	s_barrier
	s_add_u32 m0, s14, 0x8580
	s_nop 0
	global_load_lds_dwordx4 v[68:69], off offset:640
	s_add_u32 m0, s14, 0x9580
	s_nop 0
	global_load_lds_dwordx4 v[72:73], off offset:640
	s_add_u32 m0, s14, 0xa580
	s_nop 0
	global_load_lds_dwordx4 v[76:77], off offset:640
	s_add_u32 m0, s14, 0xb580
	s_nop 0
	global_load_lds_dwordx4 v[80:81], off offset:640
	s_add_u32 m0, s14, 0xc580
	s_nop 0
	global_load_lds_dwordx4 v[70:71], off offset:640
	s_add_u32 m0, s14, 0xd580
	s_nop 0
	global_load_lds_dwordx4 v[74:75], off offset:640
	s_add_u32 m0, s14, 0xe580
	s_nop 0
	global_load_lds_dwordx4 v[78:79], off offset:640
	s_add_u32 m0, s14, 0xf580
	s_nop 0
	global_load_lds_dwordx4 v[82:83], off offset:640
	v_mfma_f32_32x32x16_bf16 v[34:49], v[94:97], v[102:105], v[34:49]
	v_mfma_f32_32x32x16_bf16 v[50:65], v[94:97], v[106:109], v[50:65]
	v_mfma_f32_32x32x16_bf16 v[2:17], v[98:101], v[102:105], v[2:17]
	v_mfma_f32_32x32x16_bf16 v[18:33], v[98:101], v[106:109], v[18:33]
	s_waitcnt vmcnt(8)
	s_barrier
	ds_read_b128 v[94:97], v86 offset:2048
	ds_read_b128 v[98:101], v86 offset:6144
	ds_read_b128 v[102:105], v90 offset:2048
	ds_read_b128 v[106:109], v90 offset:6144
	v_mfma_f32_32x32x16_bf16 v[34:49], v[110:113], v[118:121], v[34:49]
	v_mfma_f32_32x32x16_bf16 v[50:65], v[110:113], v[122:125], v[50:65]
	v_mfma_f32_32x32x16_bf16 v[2:17], v[114:117], v[118:121], v[2:17]
	v_mfma_f32_32x32x16_bf16 v[18:33], v[114:117], v[122:125], v[18:33]
	ds_read_b128 v[110:113], v87 offset:2048
	ds_read_b128 v[114:117], v87 offset:6144
	ds_read_b128 v[118:121], v91 offset:2048
	ds_read_b128 v[122:125], v91 offset:6144
	v_mfma_f32_32x32x16_bf16 v[34:49], v[126:129], v[134:137], v[34:49]
	v_mfma_f32_32x32x16_bf16 v[50:65], v[126:129], v[138:141], v[50:65]
	v_mfma_f32_32x32x16_bf16 v[2:17], v[130:133], v[134:137], v[2:17]
	v_mfma_f32_32x32x16_bf16 v[18:33], v[130:133], v[138:141], v[18:33]
	ds_read_b128 v[126:129], v88 offset:2048
	ds_read_b128 v[130:133], v88 offset:6144
	ds_read_b128 v[134:137], v92 offset:2048
	ds_read_b128 v[138:141], v92 offset:6144
	v_mfma_f32_32x32x16_bf16 v[34:49], v[142:145], v[150:153], v[34:49]
	v_mfma_f32_32x32x16_bf16 v[50:65], v[142:145], v[154:157], v[50:65]
	v_mfma_f32_32x32x16_bf16 v[2:17], v[146:149], v[150:153], v[2:17]
	v_mfma_f32_32x32x16_bf16 v[18:33], v[146:149], v[154:157], v[18:33]
	ds_read_b128 v[142:145], v89 offset:2048
	ds_read_b128 v[146:149], v89 offset:6144
	ds_read_b128 v[150:153], v93 offset:2048
	ds_read_b128 v[154:157], v93 offset:6144
	s_waitcnt lgkmcnt(0)
	s_barrier
	s_add_u32 m0, s14, 0x500
	s_nop 0
	global_load_lds_dwordx4 v[68:69], off offset:768
	s_add_u32 m0, s14, 0x1500
	s_nop 0
	global_load_lds_dwordx4 v[72:73], off offset:768
	s_add_u32 m0, s14, 0x2500
	s_nop 0
	global_load_lds_dwordx4 v[76:77], off offset:768
	s_add_u32 m0, s14, 0x3500
	s_nop 0
	global_load_lds_dwordx4 v[80:81], off offset:768
	s_add_u32 m0, s14, 0x4500
	s_nop 0
	global_load_lds_dwordx4 v[70:71], off offset:768
	s_add_u32 m0, s14, 0x5500
	s_nop 0
	global_load_lds_dwordx4 v[74:75], off offset:768
	s_add_u32 m0, s14, 0x6500
	s_nop 0
	global_load_lds_dwordx4 v[78:79], off offset:768
	s_add_u32 m0, s14, 0x7500
	s_nop 0
	global_load_lds_dwordx4 v[82:83], off offset:768
	v_mfma_f32_32x32x16_bf16 v[34:49], v[94:97], v[102:105], v[34:49]
	v_mfma_f32_32x32x16_bf16 v[50:65], v[94:97], v[106:109], v[50:65]
	v_mfma_f32_32x32x16_bf16 v[2:17], v[98:101], v[102:105], v[2:17]
	v_mfma_f32_32x32x16_bf16 v[18:33], v[98:101], v[106:109], v[18:33]
	s_waitcnt vmcnt(8)
	s_barrier
	ds_read_b128 v[94:97], v86 offset:34816
	ds_read_b128 v[98:101], v86 offset:38912
	ds_read_b128 v[102:105], v90 offset:34816
	ds_read_b128 v[106:109], v90 offset:38912
	v_mfma_f32_32x32x16_bf16 v[34:49], v[110:113], v[118:121], v[34:49]
	v_mfma_f32_32x32x16_bf16 v[50:65], v[110:113], v[122:125], v[50:65]
	v_mfma_f32_32x32x16_bf16 v[2:17], v[114:117], v[118:121], v[2:17]
	v_mfma_f32_32x32x16_bf16 v[18:33], v[114:117], v[122:125], v[18:33]
	ds_read_b128 v[110:113], v87 offset:34816
	ds_read_b128 v[114:117], v87 offset:38912
	ds_read_b128 v[118:121], v91 offset:34816
	ds_read_b128 v[122:125], v91 offset:38912
	v_mfma_f32_32x32x16_bf16 v[34:49], v[126:129], v[134:137], v[34:49]
	v_mfma_f32_32x32x16_bf16 v[50:65], v[126:129], v[138:141], v[50:65]
	v_mfma_f32_32x32x16_bf16 v[2:17], v[130:133], v[134:137], v[2:17]
	v_mfma_f32_32x32x16_bf16 v[18:33], v[130:133], v[138:141], v[18:33]
	ds_read_b128 v[126:129], v88 offset:34816
	ds_read_b128 v[130:133], v88 offset:38912
	ds_read_b128 v[134:137], v92 offset:34816
	ds_read_b128 v[138:141], v92 offset:38912
	v_mfma_f32_32x32x16_bf16 v[34:49], v[142:145], v[150:153], v[34:49]
	v_mfma_f32_32x32x16_bf16 v[50:65], v[142:145], v[154:157], v[50:65]
	v_mfma_f32_32x32x16_bf16 v[2:17], v[146:149], v[150:153], v[2:17]
	v_mfma_f32_32x32x16_bf16 v[18:33], v[146:149], v[154:157], v[18:33]
	ds_read_b128 v[142:145], v89 offset:34816
	ds_read_b128 v[146:149], v89 offset:38912
	ds_read_b128 v[150:153], v93 offset:34816
	ds_read_b128 v[154:157], v93 offset:38912
	s_waitcnt lgkmcnt(0)
	s_barrier
	s_add_u32 m0, s14, 0x8480
	s_nop 0
	global_load_lds_dwordx4 v[68:69], off offset:896
	s_add_u32 m0, s14, 0x9480
	s_nop 0
	global_load_lds_dwordx4 v[72:73], off offset:896
	s_add_u32 m0, s14, 0xa480
	s_nop 0
	global_load_lds_dwordx4 v[76:77], off offset:896
	s_add_u32 m0, s14, 0xb480
	s_nop 0
	global_load_lds_dwordx4 v[80:81], off offset:896
	s_add_u32 m0, s14, 0xc480
	s_nop 0
	global_load_lds_dwordx4 v[70:71], off offset:896
	s_add_u32 m0, s14, 0xd480
	s_nop 0
	global_load_lds_dwordx4 v[74:75], off offset:896
	s_add_u32 m0, s14, 0xe480
	s_nop 0
	global_load_lds_dwordx4 v[78:79], off offset:896
	s_add_u32 m0, s14, 0xf480
	s_nop 0
	global_load_lds_dwordx4 v[82:83], off offset:896
	v_mfma_f32_32x32x16_bf16 v[34:49], v[94:97], v[102:105], v[34:49]
	v_mfma_f32_32x32x16_bf16 v[50:65], v[94:97], v[106:109], v[50:65]
	v_mfma_f32_32x32x16_bf16 v[2:17], v[98:101], v[102:105], v[2:17]
	v_mfma_f32_32x32x16_bf16 v[18:33], v[98:101], v[106:109], v[18:33]
	s_waitcnt vmcnt(8)
	s_barrier
	ds_read_b128 v[94:97], v86 offset:2048
	ds_read_b128 v[98:101], v86 offset:6144
	ds_read_b128 v[102:105], v90 offset:2048
	ds_read_b128 v[106:109], v90 offset:6144
	v_mfma_f32_32x32x16_bf16 v[34:49], v[110:113], v[118:121], v[34:49]
	v_mfma_f32_32x32x16_bf16 v[50:65], v[110:113], v[122:125], v[50:65]
	v_mfma_f32_32x32x16_bf16 v[2:17], v[114:117], v[118:121], v[2:17]
	v_mfma_f32_32x32x16_bf16 v[18:33], v[114:117], v[122:125], v[18:33]
	ds_read_b128 v[110:113], v87 offset:2048
	ds_read_b128 v[114:117], v87 offset:6144
	ds_read_b128 v[118:121], v91 offset:2048
	ds_read_b128 v[122:125], v91 offset:6144
	v_mfma_f32_32x32x16_bf16 v[34:49], v[126:129], v[134:137], v[34:49]
	v_mfma_f32_32x32x16_bf16 v[50:65], v[126:129], v[138:141], v[50:65]
	v_mfma_f32_32x32x16_bf16 v[2:17], v[130:133], v[134:137], v[2:17]
	v_mfma_f32_32x32x16_bf16 v[18:33], v[130:133], v[138:141], v[18:33]
	ds_read_b128 v[126:129], v88 offset:2048
	ds_read_b128 v[130:133], v88 offset:6144
	ds_read_b128 v[134:137], v92 offset:2048
	ds_read_b128 v[138:141], v92 offset:6144
	v_mfma_f32_32x32x16_bf16 v[34:49], v[142:145], v[150:153], v[34:49]
	v_mfma_f32_32x32x16_bf16 v[50:65], v[142:145], v[154:157], v[50:65]
	v_mfma_f32_32x32x16_bf16 v[2:17], v[146:149], v[150:153], v[2:17]
	v_mfma_f32_32x32x16_bf16 v[18:33], v[146:149], v[154:157], v[18:33]
	ds_read_b128 v[142:145], v89 offset:2048
	ds_read_b128 v[146:149], v89 offset:6144
	ds_read_b128 v[150:153], v93 offset:2048
	ds_read_b128 v[154:157], v93 offset:6144
	s_waitcnt lgkmcnt(0)
	s_barrier
	s_add_u32 m0, s14, 0x400
	s_nop 0
	global_load_lds_dwordx4 v[68:69], off offset:1024
	s_add_u32 m0, s14, 0x1400
	s_nop 0
	global_load_lds_dwordx4 v[72:73], off offset:1024
	s_add_u32 m0, s14, 0x2400
	s_nop 0
	global_load_lds_dwordx4 v[76:77], off offset:1024
	s_add_u32 m0, s14, 0x3400
	s_nop 0
	global_load_lds_dwordx4 v[80:81], off offset:1024
	s_add_u32 m0, s14, 0x4400
	s_nop 0
	global_load_lds_dwordx4 v[70:71], off offset:1024
	s_add_u32 m0, s14, 0x5400
	s_nop 0
	global_load_lds_dwordx4 v[74:75], off offset:1024
	s_add_u32 m0, s14, 0x6400
	s_nop 0
	global_load_lds_dwordx4 v[78:79], off offset:1024
	s_add_u32 m0, s14, 0x7400
	s_nop 0
	global_load_lds_dwordx4 v[82:83], off offset:1024
	v_mfma_f32_32x32x16_bf16 v[34:49], v[94:97], v[102:105], v[34:49]
	v_mfma_f32_32x32x16_bf16 v[50:65], v[94:97], v[106:109], v[50:65]
	v_mfma_f32_32x32x16_bf16 v[2:17], v[98:101], v[102:105], v[2:17]
	v_mfma_f32_32x32x16_bf16 v[18:33], v[98:101], v[106:109], v[18:33]
	s_waitcnt vmcnt(8)
	s_barrier
	ds_read_b128 v[94:97], v86 offset:34816
	ds_read_b128 v[98:101], v86 offset:38912
	ds_read_b128 v[102:105], v90 offset:34816
	ds_read_b128 v[106:109], v90 offset:38912
	v_mfma_f32_32x32x16_bf16 v[34:49], v[110:113], v[118:121], v[34:49]
	v_mfma_f32_32x32x16_bf16 v[50:65], v[110:113], v[122:125], v[50:65]
	v_mfma_f32_32x32x16_bf16 v[2:17], v[114:117], v[118:121], v[2:17]
	v_mfma_f32_32x32x16_bf16 v[18:33], v[114:117], v[122:125], v[18:33]
	ds_read_b128 v[110:113], v87 offset:34816
	ds_read_b128 v[114:117], v87 offset:38912
	ds_read_b128 v[118:121], v91 offset:34816
	ds_read_b128 v[122:125], v91 offset:38912
	v_mfma_f32_32x32x16_bf16 v[34:49], v[126:129], v[134:137], v[34:49]
	v_mfma_f32_32x32x16_bf16 v[50:65], v[126:129], v[138:141], v[50:65]
	v_mfma_f32_32x32x16_bf16 v[2:17], v[130:133], v[134:137], v[2:17]
	v_mfma_f32_32x32x16_bf16 v[18:33], v[130:133], v[138:141], v[18:33]
	ds_read_b128 v[126:129], v88 offset:34816
	ds_read_b128 v[130:133], v88 offset:38912
	ds_read_b128 v[134:137], v92 offset:34816
	ds_read_b128 v[138:141], v92 offset:38912
	v_mfma_f32_32x32x16_bf16 v[34:49], v[142:145], v[150:153], v[34:49]
	v_mfma_f32_32x32x16_bf16 v[50:65], v[142:145], v[154:157], v[50:65]
	v_mfma_f32_32x32x16_bf16 v[2:17], v[146:149], v[150:153], v[2:17]
	v_mfma_f32_32x32x16_bf16 v[18:33], v[146:149], v[154:157], v[18:33]
	ds_read_b128 v[142:145], v89 offset:34816
	ds_read_b128 v[146:149], v89 offset:38912
	ds_read_b128 v[150:153], v93 offset:34816
	ds_read_b128 v[154:157], v93 offset:38912
	s_waitcnt lgkmcnt(0)
	s_barrier
	s_add_u32 m0, s14, 0x8380
	s_nop 0
	global_load_lds_dwordx4 v[68:69], off offset:1152
	s_add_u32 m0, s14, 0x9380
	s_nop 0
	global_load_lds_dwordx4 v[72:73], off offset:1152
	s_add_u32 m0, s14, 0xa380
	s_nop 0
	global_load_lds_dwordx4 v[76:77], off offset:1152
	s_add_u32 m0, s14, 0xb380
	s_nop 0
	global_load_lds_dwordx4 v[80:81], off offset:1152
	s_add_u32 m0, s14, 0xc380
	s_nop 0
	global_load_lds_dwordx4 v[70:71], off offset:1152
	s_add_u32 m0, s14, 0xd380
	s_nop 0
	global_load_lds_dwordx4 v[74:75], off offset:1152
	s_add_u32 m0, s14, 0xe380
	s_nop 0
	global_load_lds_dwordx4 v[78:79], off offset:1152
	s_add_u32 m0, s14, 0xf380
	s_nop 0
	global_load_lds_dwordx4 v[82:83], off offset:1152
	v_mfma_f32_32x32x16_bf16 v[34:49], v[94:97], v[102:105], v[34:49]
	v_mfma_f32_32x32x16_bf16 v[50:65], v[94:97], v[106:109], v[50:65]
	v_mfma_f32_32x32x16_bf16 v[2:17], v[98:101], v[102:105], v[2:17]
	v_mfma_f32_32x32x16_bf16 v[18:33], v[98:101], v[106:109], v[18:33]
	s_waitcnt vmcnt(8)
	s_barrier
	ds_read_b128 v[94:97], v86 offset:2048
	ds_read_b128 v[98:101], v86 offset:6144
	ds_read_b128 v[102:105], v90 offset:2048
	ds_read_b128 v[106:109], v90 offset:6144
	v_mfma_f32_32x32x16_bf16 v[34:49], v[110:113], v[118:121], v[34:49]
	v_mfma_f32_32x32x16_bf16 v[50:65], v[110:113], v[122:125], v[50:65]
	v_mfma_f32_32x32x16_bf16 v[2:17], v[114:117], v[118:121], v[2:17]
	v_mfma_f32_32x32x16_bf16 v[18:33], v[114:117], v[122:125], v[18:33]
	ds_read_b128 v[110:113], v87 offset:2048
	ds_read_b128 v[114:117], v87 offset:6144
	ds_read_b128 v[118:121], v91 offset:2048
	ds_read_b128 v[122:125], v91 offset:6144
	v_mfma_f32_32x32x16_bf16 v[34:49], v[126:129], v[134:137], v[34:49]
	v_mfma_f32_32x32x16_bf16 v[50:65], v[126:129], v[138:141], v[50:65]
	v_mfma_f32_32x32x16_bf16 v[2:17], v[130:133], v[134:137], v[2:17]
	v_mfma_f32_32x32x16_bf16 v[18:33], v[130:133], v[138:141], v[18:33]
	ds_read_b128 v[126:129], v88 offset:2048
	ds_read_b128 v[130:133], v88 offset:6144
	ds_read_b128 v[134:137], v92 offset:2048
	ds_read_b128 v[138:141], v92 offset:6144
	v_mfma_f32_32x32x16_bf16 v[34:49], v[142:145], v[150:153], v[34:49]
	v_mfma_f32_32x32x16_bf16 v[50:65], v[142:145], v[154:157], v[50:65]
	v_mfma_f32_32x32x16_bf16 v[2:17], v[146:149], v[150:153], v[2:17]
	v_mfma_f32_32x32x16_bf16 v[18:33], v[146:149], v[154:157], v[18:33]
	ds_read_b128 v[142:145], v89 offset:2048
	ds_read_b128 v[146:149], v89 offset:6144
	ds_read_b128 v[150:153], v93 offset:2048
	ds_read_b128 v[154:157], v93 offset:6144
	s_waitcnt lgkmcnt(0)
	s_barrier
	s_add_u32 m0, s14, 0x300
	s_nop 0
	global_load_lds_dwordx4 v[68:69], off offset:1280
	s_add_u32 m0, s14, 0x1300
	s_nop 0
	global_load_lds_dwordx4 v[72:73], off offset:1280
	s_add_u32 m0, s14, 0x2300
	s_nop 0
	global_load_lds_dwordx4 v[76:77], off offset:1280
	s_add_u32 m0, s14, 0x3300
	s_nop 0
	global_load_lds_dwordx4 v[80:81], off offset:1280
	s_add_u32 m0, s14, 0x4300
	s_nop 0
	global_load_lds_dwordx4 v[70:71], off offset:1280
	s_add_u32 m0, s14, 0x5300
	s_nop 0
	global_load_lds_dwordx4 v[74:75], off offset:1280
	s_add_u32 m0, s14, 0x6300
	s_nop 0
	global_load_lds_dwordx4 v[78:79], off offset:1280
	s_add_u32 m0, s14, 0x7300
	s_nop 0
	global_load_lds_dwordx4 v[82:83], off offset:1280
	v_mfma_f32_32x32x16_bf16 v[34:49], v[94:97], v[102:105], v[34:49]
	v_mfma_f32_32x32x16_bf16 v[50:65], v[94:97], v[106:109], v[50:65]
	v_mfma_f32_32x32x16_bf16 v[2:17], v[98:101], v[102:105], v[2:17]
	v_mfma_f32_32x32x16_bf16 v[18:33], v[98:101], v[106:109], v[18:33]
	s_waitcnt vmcnt(8)
	s_barrier
	ds_read_b128 v[94:97], v86 offset:34816
	ds_read_b128 v[98:101], v86 offset:38912
	ds_read_b128 v[102:105], v90 offset:34816
	ds_read_b128 v[106:109], v90 offset:38912
	v_mfma_f32_32x32x16_bf16 v[34:49], v[110:113], v[118:121], v[34:49]
	v_mfma_f32_32x32x16_bf16 v[50:65], v[110:113], v[122:125], v[50:65]
	v_mfma_f32_32x32x16_bf16 v[2:17], v[114:117], v[118:121], v[2:17]
	v_mfma_f32_32x32x16_bf16 v[18:33], v[114:117], v[122:125], v[18:33]
	ds_read_b128 v[110:113], v87 offset:34816
	ds_read_b128 v[114:117], v87 offset:38912
	ds_read_b128 v[118:121], v91 offset:34816
	ds_read_b128 v[122:125], v91 offset:38912
	v_mfma_f32_32x32x16_bf16 v[34:49], v[126:129], v[134:137], v[34:49]
	v_mfma_f32_32x32x16_bf16 v[50:65], v[126:129], v[138:141], v[50:65]
	v_mfma_f32_32x32x16_bf16 v[2:17], v[130:133], v[134:137], v[2:17]
	v_mfma_f32_32x32x16_bf16 v[18:33], v[130:133], v[138:141], v[18:33]
	ds_read_b128 v[126:129], v88 offset:34816
	ds_read_b128 v[130:133], v88 offset:38912
	ds_read_b128 v[134:137], v92 offset:34816
	ds_read_b128 v[138:141], v92 offset:38912
	v_mfma_f32_32x32x16_bf16 v[34:49], v[142:145], v[150:153], v[34:49]
	v_mfma_f32_32x32x16_bf16 v[50:65], v[142:145], v[154:157], v[50:65]
	v_mfma_f32_32x32x16_bf16 v[2:17], v[146:149], v[150:153], v[2:17]
	v_mfma_f32_32x32x16_bf16 v[18:33], v[146:149], v[154:157], v[18:33]
	ds_read_b128 v[142:145], v89 offset:34816
	ds_read_b128 v[146:149], v89 offset:38912
	ds_read_b128 v[150:153], v93 offset:34816
	ds_read_b128 v[154:157], v93 offset:38912
	s_waitcnt lgkmcnt(0)
	s_barrier
	s_add_u32 m0, s14, 0x8280
	s_nop 0
	global_load_lds_dwordx4 v[68:69], off offset:1408
	s_add_u32 m0, s14, 0x9280
	s_nop 0
	global_load_lds_dwordx4 v[72:73], off offset:1408
	s_add_u32 m0, s14, 0xa280
	s_nop 0
	global_load_lds_dwordx4 v[76:77], off offset:1408
	s_add_u32 m0, s14, 0xb280
	s_nop 0
	global_load_lds_dwordx4 v[80:81], off offset:1408
	s_add_u32 m0, s14, 0xc280
	s_nop 0
	global_load_lds_dwordx4 v[70:71], off offset:1408
	s_add_u32 m0, s14, 0xd280
	s_nop 0
	global_load_lds_dwordx4 v[74:75], off offset:1408
	s_add_u32 m0, s14, 0xe280
	s_nop 0
	global_load_lds_dwordx4 v[78:79], off offset:1408
	s_add_u32 m0, s14, 0xf280
	s_nop 0
	global_load_lds_dwordx4 v[82:83], off offset:1408
	v_mfma_f32_32x32x16_bf16 v[34:49], v[94:97], v[102:105], v[34:49]
	v_mfma_f32_32x32x16_bf16 v[50:65], v[94:97], v[106:109], v[50:65]
	v_mfma_f32_32x32x16_bf16 v[2:17], v[98:101], v[102:105], v[2:17]
	v_mfma_f32_32x32x16_bf16 v[18:33], v[98:101], v[106:109], v[18:33]
	s_waitcnt vmcnt(8)
	s_barrier
	ds_read_b128 v[94:97], v86 offset:2048
	ds_read_b128 v[98:101], v86 offset:6144
	ds_read_b128 v[102:105], v90 offset:2048
	ds_read_b128 v[106:109], v90 offset:6144
	v_mfma_f32_32x32x16_bf16 v[34:49], v[110:113], v[118:121], v[34:49]
	v_mfma_f32_32x32x16_bf16 v[50:65], v[110:113], v[122:125], v[50:65]
	v_mfma_f32_32x32x16_bf16 v[2:17], v[114:117], v[118:121], v[2:17]
	v_mfma_f32_32x32x16_bf16 v[18:33], v[114:117], v[122:125], v[18:33]
	ds_read_b128 v[110:113], v87 offset:2048
	ds_read_b128 v[114:117], v87 offset:6144
	ds_read_b128 v[118:121], v91 offset:2048
	ds_read_b128 v[122:125], v91 offset:6144
	v_mfma_f32_32x32x16_bf16 v[34:49], v[126:129], v[134:137], v[34:49]
	v_mfma_f32_32x32x16_bf16 v[50:65], v[126:129], v[138:141], v[50:65]
	v_mfma_f32_32x32x16_bf16 v[2:17], v[130:133], v[134:137], v[2:17]
	v_mfma_f32_32x32x16_bf16 v[18:33], v[130:133], v[138:141], v[18:33]
	ds_read_b128 v[126:129], v88 offset:2048
	ds_read_b128 v[130:133], v88 offset:6144
	ds_read_b128 v[134:137], v92 offset:2048
	ds_read_b128 v[138:141], v92 offset:6144
	v_mfma_f32_32x32x16_bf16 v[34:49], v[142:145], v[150:153], v[34:49]
	v_mfma_f32_32x32x16_bf16 v[50:65], v[142:145], v[154:157], v[50:65]
	v_mfma_f32_32x32x16_bf16 v[2:17], v[146:149], v[150:153], v[2:17]
	v_mfma_f32_32x32x16_bf16 v[18:33], v[146:149], v[154:157], v[18:33]
	ds_read_b128 v[142:145], v89 offset:2048
	ds_read_b128 v[146:149], v89 offset:6144
	ds_read_b128 v[150:153], v93 offset:2048
	ds_read_b128 v[154:157], v93 offset:6144
	s_waitcnt lgkmcnt(0)
	s_barrier
	s_add_u32 m0, s14, 0x200
	s_nop 0
	global_load_lds_dwordx4 v[68:69], off offset:1536
	s_add_u32 m0, s14, 0x1200
	s_nop 0
	global_load_lds_dwordx4 v[72:73], off offset:1536
	s_add_u32 m0, s14, 0x2200
	s_nop 0
	global_load_lds_dwordx4 v[76:77], off offset:1536
	s_add_u32 m0, s14, 0x3200
	s_nop 0
	global_load_lds_dwordx4 v[80:81], off offset:1536
	s_add_u32 m0, s14, 0x4200
	s_nop 0
	global_load_lds_dwordx4 v[70:71], off offset:1536
	s_add_u32 m0, s14, 0x5200
	s_nop 0
	global_load_lds_dwordx4 v[74:75], off offset:1536
	s_add_u32 m0, s14, 0x6200
	s_nop 0
	global_load_lds_dwordx4 v[78:79], off offset:1536
	s_add_u32 m0, s14, 0x7200
	s_nop 0
	global_load_lds_dwordx4 v[82:83], off offset:1536
	v_mfma_f32_32x32x16_bf16 v[34:49], v[94:97], v[102:105], v[34:49]
	v_mfma_f32_32x32x16_bf16 v[50:65], v[94:97], v[106:109], v[50:65]
	v_mfma_f32_32x32x16_bf16 v[2:17], v[98:101], v[102:105], v[2:17]
	v_mfma_f32_32x32x16_bf16 v[18:33], v[98:101], v[106:109], v[18:33]
	s_waitcnt vmcnt(8)
	s_barrier
	ds_read_b128 v[94:97], v86 offset:34816
	ds_read_b128 v[98:101], v86 offset:38912
	ds_read_b128 v[102:105], v90 offset:34816
	ds_read_b128 v[106:109], v90 offset:38912
	v_mfma_f32_32x32x16_bf16 v[34:49], v[110:113], v[118:121], v[34:49]
	v_mfma_f32_32x32x16_bf16 v[50:65], v[110:113], v[122:125], v[50:65]
	v_mfma_f32_32x32x16_bf16 v[2:17], v[114:117], v[118:121], v[2:17]
	v_mfma_f32_32x32x16_bf16 v[18:33], v[114:117], v[122:125], v[18:33]
	ds_read_b128 v[110:113], v87 offset:34816
	ds_read_b128 v[114:117], v87 offset:38912
	ds_read_b128 v[118:121], v91 offset:34816
	ds_read_b128 v[122:125], v91 offset:38912
	v_mfma_f32_32x32x16_bf16 v[34:49], v[126:129], v[134:137], v[34:49]
	v_mfma_f32_32x32x16_bf16 v[50:65], v[126:129], v[138:141], v[50:65]
	v_mfma_f32_32x32x16_bf16 v[2:17], v[130:133], v[134:137], v[2:17]
	v_mfma_f32_32x32x16_bf16 v[18:33], v[130:133], v[138:141], v[18:33]
	ds_read_b128 v[126:129], v88 offset:34816
	ds_read_b128 v[130:133], v88 offset:38912
	ds_read_b128 v[134:137], v92 offset:34816
	ds_read_b128 v[138:141], v92 offset:38912
	v_mfma_f32_32x32x16_bf16 v[34:49], v[142:145], v[150:153], v[34:49]
	v_mfma_f32_32x32x16_bf16 v[50:65], v[142:145], v[154:157], v[50:65]
	v_mfma_f32_32x32x16_bf16 v[2:17], v[146:149], v[150:153], v[2:17]
	v_mfma_f32_32x32x16_bf16 v[18:33], v[146:149], v[154:157], v[18:33]
	ds_read_b128 v[142:145], v89 offset:34816
	ds_read_b128 v[146:149], v89 offset:38912
	ds_read_b128 v[150:153], v93 offset:34816
	ds_read_b128 v[154:157], v93 offset:38912
	s_waitcnt lgkmcnt(0)
	s_barrier
	s_add_u32 m0, s14, 0x8180
	s_nop 0
	global_load_lds_dwordx4 v[68:69], off offset:1664
	s_add_u32 m0, s14, 0x9180
	s_nop 0
	global_load_lds_dwordx4 v[72:73], off offset:1664
	s_add_u32 m0, s14, 0xa180
	s_nop 0
	global_load_lds_dwordx4 v[76:77], off offset:1664
	s_add_u32 m0, s14, 0xb180
	s_nop 0
	global_load_lds_dwordx4 v[80:81], off offset:1664
	s_add_u32 m0, s14, 0xc180
	s_nop 0
	global_load_lds_dwordx4 v[70:71], off offset:1664
	s_add_u32 m0, s14, 0xd180
	s_nop 0
	global_load_lds_dwordx4 v[74:75], off offset:1664
	s_add_u32 m0, s14, 0xe180
	s_nop 0
	global_load_lds_dwordx4 v[78:79], off offset:1664
	s_add_u32 m0, s14, 0xf180
	s_nop 0
	global_load_lds_dwordx4 v[82:83], off offset:1664
	v_mfma_f32_32x32x16_bf16 v[34:49], v[94:97], v[102:105], v[34:49]
	v_mfma_f32_32x32x16_bf16 v[50:65], v[94:97], v[106:109], v[50:65]
	v_mfma_f32_32x32x16_bf16 v[2:17], v[98:101], v[102:105], v[2:17]
	v_mfma_f32_32x32x16_bf16 v[18:33], v[98:101], v[106:109], v[18:33]
	s_waitcnt vmcnt(8)
	s_barrier
	ds_read_b128 v[94:97], v86 offset:2048
	ds_read_b128 v[98:101], v86 offset:6144
	ds_read_b128 v[102:105], v90 offset:2048
	ds_read_b128 v[106:109], v90 offset:6144
	v_mfma_f32_32x32x16_bf16 v[34:49], v[110:113], v[118:121], v[34:49]
	v_mfma_f32_32x32x16_bf16 v[50:65], v[110:113], v[122:125], v[50:65]
	v_mfma_f32_32x32x16_bf16 v[2:17], v[114:117], v[118:121], v[2:17]
	v_mfma_f32_32x32x16_bf16 v[18:33], v[114:117], v[122:125], v[18:33]
	ds_read_b128 v[110:113], v87 offset:2048
	ds_read_b128 v[114:117], v87 offset:6144
	ds_read_b128 v[118:121], v91 offset:2048
	ds_read_b128 v[122:125], v91 offset:6144
	v_mfma_f32_32x32x16_bf16 v[34:49], v[126:129], v[134:137], v[34:49]
	v_mfma_f32_32x32x16_bf16 v[50:65], v[126:129], v[138:141], v[50:65]
	v_mfma_f32_32x32x16_bf16 v[2:17], v[130:133], v[134:137], v[2:17]
	v_mfma_f32_32x32x16_bf16 v[18:33], v[130:133], v[138:141], v[18:33]
	ds_read_b128 v[126:129], v88 offset:2048
	ds_read_b128 v[130:133], v88 offset:6144
	ds_read_b128 v[134:137], v92 offset:2048
	ds_read_b128 v[138:141], v92 offset:6144
	v_mfma_f32_32x32x16_bf16 v[34:49], v[142:145], v[150:153], v[34:49]
	v_mfma_f32_32x32x16_bf16 v[50:65], v[142:145], v[154:157], v[50:65]
	v_mfma_f32_32x32x16_bf16 v[2:17], v[146:149], v[150:153], v[2:17]
	v_mfma_f32_32x32x16_bf16 v[18:33], v[146:149], v[154:157], v[18:33]
	ds_read_b128 v[142:145], v89 offset:2048
	ds_read_b128 v[146:149], v89 offset:6144
	ds_read_b128 v[150:153], v93 offset:2048
	ds_read_b128 v[154:157], v93 offset:6144
	s_waitcnt lgkmcnt(0)
	s_barrier
	s_add_u32 m0, s14, 0x100
	s_nop 0
	global_load_lds_dwordx4 v[68:69], off offset:1792
	s_add_u32 m0, s14, 0x1100
	s_nop 0
	global_load_lds_dwordx4 v[72:73], off offset:1792
	s_add_u32 m0, s14, 0x2100
	s_nop 0
	global_load_lds_dwordx4 v[76:77], off offset:1792
	s_add_u32 m0, s14, 0x3100
	s_nop 0
	global_load_lds_dwordx4 v[80:81], off offset:1792
	s_add_u32 m0, s14, 0x4100
	s_nop 0
	global_load_lds_dwordx4 v[70:71], off offset:1792
	s_add_u32 m0, s14, 0x5100
	s_nop 0
	global_load_lds_dwordx4 v[74:75], off offset:1792
	s_add_u32 m0, s14, 0x6100
	s_nop 0
	global_load_lds_dwordx4 v[78:79], off offset:1792
	s_add_u32 m0, s14, 0x7100
	s_nop 0
	global_load_lds_dwordx4 v[82:83], off offset:1792
	v_mfma_f32_32x32x16_bf16 v[34:49], v[94:97], v[102:105], v[34:49]
	v_mfma_f32_32x32x16_bf16 v[50:65], v[94:97], v[106:109], v[50:65]
	v_mfma_f32_32x32x16_bf16 v[2:17], v[98:101], v[102:105], v[2:17]
	v_mfma_f32_32x32x16_bf16 v[18:33], v[98:101], v[106:109], v[18:33]
	s_waitcnt vmcnt(8)
	s_barrier
	ds_read_b128 v[94:97], v86 offset:34816
	ds_read_b128 v[98:101], v86 offset:38912
	ds_read_b128 v[102:105], v90 offset:34816
	ds_read_b128 v[106:109], v90 offset:38912
	v_mfma_f32_32x32x16_bf16 v[34:49], v[110:113], v[118:121], v[34:49]
	v_mfma_f32_32x32x16_bf16 v[50:65], v[110:113], v[122:125], v[50:65]
	v_mfma_f32_32x32x16_bf16 v[2:17], v[114:117], v[118:121], v[2:17]
	v_mfma_f32_32x32x16_bf16 v[18:33], v[114:117], v[122:125], v[18:33]
	ds_read_b128 v[110:113], v87 offset:34816
	ds_read_b128 v[114:117], v87 offset:38912
	ds_read_b128 v[118:121], v91 offset:34816
	ds_read_b128 v[122:125], v91 offset:38912
	v_mfma_f32_32x32x16_bf16 v[34:49], v[126:129], v[134:137], v[34:49]
	v_mfma_f32_32x32x16_bf16 v[50:65], v[126:129], v[138:141], v[50:65]
	v_mfma_f32_32x32x16_bf16 v[2:17], v[130:133], v[134:137], v[2:17]
	v_mfma_f32_32x32x16_bf16 v[18:33], v[130:133], v[138:141], v[18:33]
	ds_read_b128 v[126:129], v88 offset:34816
	ds_read_b128 v[130:133], v88 offset:38912
	ds_read_b128 v[134:137], v92 offset:34816
	ds_read_b128 v[138:141], v92 offset:38912
	v_mfma_f32_32x32x16_bf16 v[34:49], v[142:145], v[150:153], v[34:49]
	v_mfma_f32_32x32x16_bf16 v[50:65], v[142:145], v[154:157], v[50:65]
	v_mfma_f32_32x32x16_bf16 v[2:17], v[146:149], v[150:153], v[2:17]
	v_mfma_f32_32x32x16_bf16 v[18:33], v[146:149], v[154:157], v[18:33]
	ds_read_b128 v[142:145], v89 offset:34816
	ds_read_b128 v[146:149], v89 offset:38912
	ds_read_b128 v[150:153], v93 offset:34816
	ds_read_b128 v[154:157], v93 offset:38912
	s_waitcnt lgkmcnt(0)
	s_barrier
	s_add_u32 m0, s14, 0x8080
	s_nop 0
	global_load_lds_dwordx4 v[68:69], off offset:1920
	s_add_u32 m0, s14, 0x9080
	s_nop 0
	global_load_lds_dwordx4 v[72:73], off offset:1920
	s_add_u32 m0, s14, 0xa080
	s_nop 0
	global_load_lds_dwordx4 v[76:77], off offset:1920
	s_add_u32 m0, s14, 0xb080
	s_nop 0
	global_load_lds_dwordx4 v[80:81], off offset:1920
	s_add_u32 m0, s14, 0xc080
	s_nop 0
	global_load_lds_dwordx4 v[70:71], off offset:1920
	s_add_u32 m0, s14, 0xd080
	s_nop 0
	global_load_lds_dwordx4 v[74:75], off offset:1920
	s_add_u32 m0, s14, 0xe080
	s_nop 0
	global_load_lds_dwordx4 v[78:79], off offset:1920
	s_add_u32 m0, s14, 0xf080
	s_nop 0
	global_load_lds_dwordx4 v[82:83], off offset:1920
	v_mfma_f32_32x32x16_bf16 v[34:49], v[94:97], v[102:105], v[34:49]
	v_mfma_f32_32x32x16_bf16 v[50:65], v[94:97], v[106:109], v[50:65]
	v_mfma_f32_32x32x16_bf16 v[2:17], v[98:101], v[102:105], v[2:17]
	v_mfma_f32_32x32x16_bf16 v[18:33], v[98:101], v[106:109], v[18:33]
	s_waitcnt vmcnt(8)
	s_barrier
	ds_read_b128 v[94:97], v86 offset:2048
	ds_read_b128 v[98:101], v86 offset:6144
	ds_read_b128 v[102:105], v90 offset:2048
	ds_read_b128 v[106:109], v90 offset:6144
	v_mfma_f32_32x32x16_bf16 v[34:49], v[110:113], v[118:121], v[34:49]
	v_mfma_f32_32x32x16_bf16 v[50:65], v[110:113], v[122:125], v[50:65]
	v_mfma_f32_32x32x16_bf16 v[2:17], v[114:117], v[118:121], v[2:17]
	v_mfma_f32_32x32x16_bf16 v[18:33], v[114:117], v[122:125], v[18:33]
	ds_read_b128 v[110:113], v87 offset:2048
	ds_read_b128 v[114:117], v87 offset:6144
	ds_read_b128 v[118:121], v91 offset:2048
	ds_read_b128 v[122:125], v91 offset:6144
	v_mfma_f32_32x32x16_bf16 v[34:49], v[126:129], v[134:137], v[34:49]
	v_mfma_f32_32x32x16_bf16 v[50:65], v[126:129], v[138:141], v[50:65]
	v_mfma_f32_32x32x16_bf16 v[2:17], v[130:133], v[134:137], v[2:17]
	v_mfma_f32_32x32x16_bf16 v[18:33], v[130:133], v[138:141], v[18:33]
	ds_read_b128 v[126:129], v88 offset:2048
	ds_read_b128 v[130:133], v88 offset:6144
	ds_read_b128 v[134:137], v92 offset:2048
	ds_read_b128 v[138:141], v92 offset:6144
	v_mfma_f32_32x32x16_bf16 v[34:49], v[142:145], v[150:153], v[34:49]
	v_mfma_f32_32x32x16_bf16 v[50:65], v[142:145], v[154:157], v[50:65]
	v_mfma_f32_32x32x16_bf16 v[2:17], v[146:149], v[150:153], v[2:17]
	v_mfma_f32_32x32x16_bf16 v[18:33], v[146:149], v[154:157], v[18:33]
	ds_read_b128 v[142:145], v89 offset:2048
	ds_read_b128 v[146:149], v89 offset:6144
	ds_read_b128 v[150:153], v93 offset:2048
	ds_read_b128 v[154:157], v93 offset:6144
	s_waitcnt lgkmcnt(0)
	v_mfma_f32_32x32x16_bf16 v[34:49], v[94:97], v[102:105], v[34:49]
	v_mfma_f32_32x32x16_bf16 v[50:65], v[94:97], v[106:109], v[50:65]
	v_mfma_f32_32x32x16_bf16 v[2:17], v[98:101], v[102:105], v[2:17]
	v_mfma_f32_32x32x16_bf16 v[18:33], v[98:101], v[106:109], v[18:33]
	s_waitcnt vmcnt(0)
	s_barrier
	ds_read_b128 v[94:97], v86 offset:34816
	ds_read_b128 v[98:101], v86 offset:38912
	ds_read_b128 v[102:105], v90 offset:34816
	ds_read_b128 v[106:109], v90 offset:38912
	v_mfma_f32_32x32x16_bf16 v[34:49], v[110:113], v[118:121], v[34:49]
	v_mfma_f32_32x32x16_bf16 v[50:65], v[110:113], v[122:125], v[50:65]
	v_mfma_f32_32x32x16_bf16 v[2:17], v[114:117], v[118:121], v[2:17]
	v_mfma_f32_32x32x16_bf16 v[18:33], v[114:117], v[122:125], v[18:33]
	ds_read_b128 v[110:113], v87 offset:34816
	ds_read_b128 v[114:117], v87 offset:38912
	ds_read_b128 v[118:121], v91 offset:34816
	ds_read_b128 v[122:125], v91 offset:38912
	v_mfma_f32_32x32x16_bf16 v[34:49], v[126:129], v[134:137], v[34:49]
	v_mfma_f32_32x32x16_bf16 v[50:65], v[126:129], v[138:141], v[50:65]
	v_mfma_f32_32x32x16_bf16 v[2:17], v[130:133], v[134:137], v[2:17]
	v_mfma_f32_32x32x16_bf16 v[18:33], v[130:133], v[138:141], v[18:33]
	ds_read_b128 v[126:129], v88 offset:34816
	ds_read_b128 v[130:133], v88 offset:38912
	ds_read_b128 v[134:137], v92 offset:34816
	ds_read_b128 v[138:141], v92 offset:38912
	v_mfma_f32_32x32x16_bf16 v[34:49], v[142:145], v[150:153], v[34:49]
	v_mfma_f32_32x32x16_bf16 v[50:65], v[142:145], v[154:157], v[50:65]
	v_mfma_f32_32x32x16_bf16 v[2:17], v[146:149], v[150:153], v[2:17]
	v_mfma_f32_32x32x16_bf16 v[18:33], v[146:149], v[154:157], v[18:33]
	ds_read_b128 v[142:145], v89 offset:34816
	ds_read_b128 v[146:149], v89 offset:38912
	ds_read_b128 v[150:153], v93 offset:34816
	ds_read_b128 v[154:157], v93 offset:38912
	s_waitcnt lgkmcnt(0)
	v_mfma_f32_32x32x16_bf16 v[34:49], v[94:97], v[102:105], v[34:49]
	v_mfma_f32_32x32x16_bf16 v[50:65], v[94:97], v[106:109], v[50:65]
	v_mfma_f32_32x32x16_bf16 v[2:17], v[98:101], v[102:105], v[2:17]
	v_mfma_f32_32x32x16_bf16 v[18:33], v[98:101], v[106:109], v[18:33]
	v_mfma_f32_32x32x16_bf16 v[34:49], v[110:113], v[118:121], v[34:49]
	v_mfma_f32_32x32x16_bf16 v[50:65], v[110:113], v[122:125], v[50:65]
	v_mfma_f32_32x32x16_bf16 v[2:17], v[114:117], v[118:121], v[2:17]
	v_mfma_f32_32x32x16_bf16 v[18:33], v[114:117], v[122:125], v[18:33]
	v_mfma_f32_32x32x16_bf16 v[34:49], v[126:129], v[134:137], v[34:49]
	v_mfma_f32_32x32x16_bf16 v[50:65], v[126:129], v[138:141], v[50:65]
	v_mfma_f32_32x32x16_bf16 v[2:17], v[130:133], v[134:137], v[2:17]
	v_mfma_f32_32x32x16_bf16 v[18:33], v[130:133], v[138:141], v[18:33]
	v_mfma_f32_32x32x16_bf16 v[34:49], v[142:145], v[150:153], v[34:49]
	v_mfma_f32_32x32x16_bf16 v[50:65], v[142:145], v[154:157], v[50:65]
	v_mfma_f32_32x32x16_bf16 v[2:17], v[146:149], v[150:153], v[2:17]
	v_mfma_f32_32x32x16_bf16 v[18:33], v[146:149], v[154:157], v[18:33]
	v_mov_b32_e32 v66, v178
	s_waitcnt lgkmcnt(0)
	s_barrier
	v_lshrrev_b32_e32 v0, 1, v66
	v_and_b32_e32 v0, 0xfffffc0, v0
	v_lshrrev_b32_e32 v67, 3, v66
	v_and_or_b32 v0, v67, 4, v0
	v_and_b32_e32 v67, 0x5f, v66
	v_mul_lo_u32 v0, v0, s83
	v_lshl_add_u32 v0, v67, 2, v0
	s_nop 11
	ds_write2_b32 v0, v34, v50 offset1:32
	ds_write2_b32 v0, v35, v51 offset0:132 offset1:164
	v_add_u32_e32 v34, 0x400, v0
	ds_write2_b32 v34, v36, v52 offset0:8 offset1:40
	ds_write2_b32 v34, v37, v53 offset0:140 offset1:172
	v_add_u32_e32 v34, 0x1000, v0
	ds_write2_b32 v34, v38, v54 offset0:32 offset1:64
	ds_write2_b32 v34, v39, v55 offset0:164 offset1:196
	v_add_u32_e32 v34, 0x1400, v0
	ds_write2_b32 v34, v40, v56 offset0:40 offset1:72
	ds_write2_b32 v34, v41, v57 offset0:172 offset1:204
	v_add_u32_e32 v34, 0x2000, v0
	ds_write2_b32 v34, v42, v58 offset0:64 offset1:96
	ds_write2_b32 v34, v43, v59 offset0:196 offset1:228
	v_add_u32_e32 v34, 0x2400, v0
	ds_write2_b32 v34, v44, v60 offset0:72 offset1:104
	ds_write2_b32 v34, v45, v61 offset0:204 offset1:236
	v_add_u32_e32 v34, 0x3000, v0
	ds_write2_b32 v34, v46, v62 offset0:96 offset1:128
	v_add_u32_e32 v34, 0x3200, v0
	ds_write2_b32 v34, v47, v63 offset0:100 offset1:132
	v_add_u32_e32 v34, 0x3400, v0
	ds_write2_b32 v34, v48, v64 offset0:104 offset1:136
	v_add_u32_e32 v34, 0x3600, v0
	ds_write2_b32 v34, v49, v65 offset0:108 offset1:140
	v_add_u32_e32 v34, 0x4000, v0
	s_nop 11
	ds_write2_b32 v34, v2, v18 offset0:128 offset1:160
	v_add_u32_e32 v2, 0x4400, v0
	ds_write2_b32 v2, v3, v19 offset0:4 offset1:36
	ds_write2_b32 v2, v4, v20 offset0:136 offset1:168
	v_add_u32_e32 v2, 0x4800, v0
	ds_write2_b32 v2, v5, v21 offset0:12 offset1:44
	v_add_u32_e32 v2, 0x5000, v0
	ds_write2_b32 v2, v6, v22 offset0:160 offset1:192
	v_add_u32_e32 v2, 0x5400, v0
	ds_write2_b32 v2, v7, v23 offset0:36 offset1:68
	ds_write2_b32 v2, v8, v24 offset0:168 offset1:200
	v_add_u32_e32 v2, 0x5800, v0
	ds_write2_b32 v2, v9, v25 offset0:44 offset1:76
	v_add_u32_e32 v2, 0x6000, v0
	ds_write2_b32 v2, v10, v26 offset0:192 offset1:224
	v_add_u32_e32 v2, 0x6400, v0
	ds_write2_b32 v2, v11, v27 offset0:68 offset1:100
	ds_write2_b32 v2, v12, v28 offset0:200 offset1:232
	v_add_u32_e32 v2, 0x6800, v0
	ds_write2_b32 v2, v13, v29 offset0:76 offset1:108
	v_add_u32_e32 v2, 0x7200, v0
	ds_write2_b32 v2, v14, v30 offset0:96 offset1:128
	v_add_u32_e32 v2, 0x7400, v0
	ds_write2_b32 v2, v15, v31 offset0:100 offset1:132
	v_add_u32_e32 v2, 0x7600, v0
	v_add_u32_e32 v0, 0x7800, v0
	ds_write2_b32 v0, v17, v33 offset0:108 offset1:140
	v_lshlrev_b32_e32 v0, 3, v66
	v_and_b32_e32 v0, 0x78, v0
	v_or_b32_e32 v12, s0, v0
	v_ashrrev_i32_e32 v13, 31, v12
	v_readlane_b32 s0, v249, 13
	ds_write2_b32 v2, v16, v32 offset0:104 offset1:136
	v_lshlrev_b64 v[2:3], 2, v[12:13]
	v_readlane_b32 s1, v249, 14
	v_lshlrev_b32_e32 v10, 2, v0
	v_lshl_add_u64 v[16:17], s[90:91], 0, v[2:3]
	v_lshl_add_u64 v[14:15], s[0:1], 0, v[2:3]
	s_waitcnt lgkmcnt(0)
	s_barrier
	s_branch .LBB0_912
